# GEMM phases: a workgroup's last unit stores its epilogue write-through (sc1) so the grid barrier's L2 write-back is short; other units unchanged
# baseline (speedup 1.0000x reference)
; __device__ __forceinline__ float sigm(float x) { return rcpf_(1.f + ex2(-1.44269504f * x)); }
; __device__ __forceinline__ u32x4 pack8(f32x4 a, f32x4 b) { u32x4 w; w.x = cvt_pk_bf16(a[0], a[1]); w.y = cvt_pk_bf16(a[2], a[3]); w.z = cvt_pk_bf16(b[0], b[1]); w.w = cvt_pk_bf16(b[2], b[3]); return w; }
;     __device__ __forceinline__ void operator()(const f32x4 (&acc)[2][2][4][2], const Unit& u, int wr, int wc, int fr, int fq) const {
;     ...
;             const int col0 = u.pn * 128 + wc * 32 + 8 * fq;
; #pragma unroll
;             for (int ai = 0; ai < 2; ++ai)
; #pragma unroll
;                 for (int m = 0; m < 4; ++m) {
;                     bf16_t* rowp = O + (size_t)(row0 + ai * HALF + m * 16) * ldc + col0;
;                     f32x4 v0, v1;
; #pragma unroll
;                     for (int e = 0; e < 4; ++e) { const float a0 = acc[ai][0][m][0][e], a1 = acc[ai][0][m][1][e]; v0[e] = a0 * sigm(a0) * acc[ai][1][m][0][e]; v1[e] = a1 * sigm(a1) * acc[ai][1][m][1][e]; }
;                     *(u32x4*)rowp = pack8(v0, v1);
;                     __builtin_amdgcn_sched_barrier(0);
;                 }
; template <class EpiT, class Sched>
; __device__ __forceinline__ void gemm_phase(LAS unsigned char* lds, int tid_in, const GemmDesc g, const Sched& S, const EpiT& E) {
;     ...
;         E(acc, cur, wr, wc, fr, fq);
;         if (!has_next) break;
.LBB0_190:
	s_andn2_b64 vcc, exec, s[0:1]
	s_cbranch_vccnz .Lepi_last_1
	v_mul_f32_e32 v147, 0xbfb8aa3b, v126
	v_exp_f32_e32 v147, v147
	v_lshl_or_b32 v148, s16, 7, v144
	v_lshl_add_u32 v146, s88, 8, v142
	v_ashrrev_i32_e32 v149, 31, v148
	v_add_f32_e32 v147, 1.0, v147
	v_rcp_f32_e32 v152, v147
	v_mul_f32_e32 v147, 0xbfb8aa3b, v118
	v_exp_f32_e32 v147, v147
	v_mov_b64_e32 v[140:141], s[30:31]
	v_mad_i64_i32 v[150:151], s[2:3], v146, s52, v[140:141]
	v_add_f32_e32 v147, 1.0, v147
	v_rcp_f32_e32 v154, v147
	v_mul_f32_e32 v147, 0xbfb8aa3b, v127
	v_exp_f32_e32 v147, v147
	s_nop 0
	v_add_f32_e32 v147, 1.0, v147
	v_rcp_f32_e32 v153, v147
	s_nop 0
	v_pk_mul_f32 v[126:127], v[126:127], v[152:153]
	s_nop 0
	v_pk_mul_f32 v[122:123], v[126:127], v[122:123]
	v_mul_f32_e32 v126, 0xbfb8aa3b, v119
	v_exp_f32_e32 v126, v126
	s_nop 0
	v_add_f32_e32 v126, 1.0, v126
	v_rcp_f32_e32 v155, v126
	s_nop 0
	v_pk_mul_f32 v[118:119], v[118:119], v[154:155]
	s_nop 0
	v_pk_mul_f32 v[118:119], v[118:119], v[114:115]
	v_mul_f32_e32 v115, 0xbfb8aa3b, v120
	v_exp_f32_e32 v115, v115
	v_mul_f32_e32 v114, 0xbfb8aa3b, v128
	v_exp_f32_e32 v114, v114
	v_cvt_pk_bf16_f32 v118, v118, v119
	v_add_f32_e32 v115, 1.0, v115
	v_rcp_f32_e32 v126, v115
	v_mul_f32_e32 v115, 0xbfb8aa3b, v129
	v_exp_f32_e32 v115, v115
	v_add_f32_e32 v114, 1.0, v114
	v_rcp_f32_e32 v114, v114
	v_add_f32_e32 v115, 1.0, v115
	v_rcp_f32_e32 v115, v115
	s_nop 0
	v_pk_mul_f32 v[114:115], v[128:129], v[114:115]
	s_nop 0
	v_pk_mul_f32 v[124:125], v[114:115], v[124:125]
	v_mul_f32_e32 v114, 0xbfb8aa3b, v121
	v_exp_f32_e32 v114, v114
	s_nop 0
	v_add_f32_e32 v114, 1.0, v114
	v_rcp_f32_e32 v127, v114
	s_nop 0
	v_pk_mul_f32 v[114:115], v[120:121], v[126:127]
	s_nop 0
	v_pk_mul_f32 v[120:121], v[114:115], v[116:117]
	v_lshlrev_b64 v[114:115], 1, v[148:149]
	v_lshl_add_u64 v[126:127], v[150:151], 0, v[114:115]
	v_cvt_pk_bf16_f32 v116, v122, v123
	v_cvt_pk_bf16_f32 v117, v124, v125
	v_cvt_pk_bf16_f32 v119, v120, v121
	global_store_dwordx4 v[126:127], v[116:119], off
	s_nop 1
	v_mul_f32_e32 v119, 0xbfb8aa3b, v102
	v_exp_f32_e32 v119, v119
	v_mul_f32_e32 v118, 0xbfb8aa3b, v110
	v_exp_f32_e32 v118, v118
	v_or_b32_e32 v116, 16, v146
	v_add_f32_e32 v119, 1.0, v119
	v_rcp_f32_e32 v120, v119
	v_mul_f32_e32 v119, 0xbfb8aa3b, v111
	v_exp_f32_e32 v119, v119
	v_add_f32_e32 v118, 1.0, v118
	v_rcp_f32_e32 v118, v118
	v_mad_i64_i32 v[116:117], s[2:3], v116, s52, v[140:141]
	v_add_f32_e32 v119, 1.0, v119
	v_rcp_f32_e32 v119, v119
	s_nop 0
	v_pk_mul_f32 v[110:111], v[110:111], v[118:119]
	s_nop 0
	v_pk_mul_f32 v[106:107], v[110:111], v[106:107]
	v_mul_f32_e32 v110, 0xbfb8aa3b, v103
	v_exp_f32_e32 v110, v110
	s_nop 0
	v_add_f32_e32 v110, 1.0, v110
	v_rcp_f32_e32 v121, v110
	s_nop 0
	v_pk_mul_f32 v[102:103], v[102:103], v[120:121]
	s_nop 0
	v_pk_mul_f32 v[102:103], v[102:103], v[98:99]
	v_mul_f32_e32 v99, 0xbfb8aa3b, v104
	v_exp_f32_e32 v99, v99
	v_mul_f32_e32 v98, 0xbfb8aa3b, v112
	v_exp_f32_e32 v98, v98
	v_add_f32_e32 v99, 1.0, v99
	v_rcp_f32_e32 v110, v99
	v_mul_f32_e32 v99, 0xbfb8aa3b, v113
	v_exp_f32_e32 v99, v99
	v_add_f32_e32 v98, 1.0, v98
	v_rcp_f32_e32 v98, v98
	v_add_f32_e32 v99, 1.0, v99
	v_rcp_f32_e32 v99, v99
	s_nop 0
	v_pk_mul_f32 v[98:99], v[112:113], v[98:99]
	s_nop 0
	v_pk_mul_f32 v[108:109], v[98:99], v[108:109]
	v_mul_f32_e32 v98, 0xbfb8aa3b, v105
	v_exp_f32_e32 v98, v98
	s_nop 0
	v_add_f32_e32 v98, 1.0, v98
	v_rcp_f32_e32 v111, v98
	s_nop 0
	v_pk_mul_f32 v[98:99], v[104:105], v[110:111]
	s_nop 0
	v_pk_mul_f32 v[104:105], v[98:99], v[100:101]
	v_lshl_add_u64 v[110:111], v[116:117], 0, v[114:115]
	v_cvt_pk_bf16_f32 v98, v106, v107
	v_cvt_pk_bf16_f32 v99, v108, v109
	v_cvt_pk_bf16_f32 v100, v102, v103
	v_cvt_pk_bf16_f32 v101, v104, v105
	global_store_dwordx4 v[110:111], v[98:101], off
	s_nop 1
	v_mul_f32_e32 v101, 0xbfb8aa3b, v86
	v_exp_f32_e32 v101, v101
	v_mul_f32_e32 v100, 0xbfb8aa3b, v94
	v_exp_f32_e32 v100, v100
	v_or_b32_e32 v98, 32, v146
	v_add_f32_e32 v101, 1.0, v101
	v_rcp_f32_e32 v102, v101
	v_mul_f32_e32 v101, 0xbfb8aa3b, v95
	v_exp_f32_e32 v101, v101
	v_add_f32_e32 v100, 1.0, v100
	v_rcp_f32_e32 v100, v100
	v_mad_i64_i32 v[98:99], s[2:3], v98, s52, v[140:141]
	v_add_f32_e32 v101, 1.0, v101
	v_rcp_f32_e32 v101, v101
	s_nop 0
	v_pk_mul_f32 v[94:95], v[94:95], v[100:101]
	s_nop 0
	v_pk_mul_f32 v[90:91], v[94:95], v[90:91]
	v_mul_f32_e32 v94, 0xbfb8aa3b, v87
	v_exp_f32_e32 v94, v94
	s_nop 0
	v_add_f32_e32 v94, 1.0, v94
	v_rcp_f32_e32 v103, v94
	s_nop 0
	v_pk_mul_f32 v[86:87], v[86:87], v[102:103]
	s_nop 0
	v_pk_mul_f32 v[86:87], v[86:87], v[82:83]
	v_mul_f32_e32 v83, 0xbfb8aa3b, v88
	v_exp_f32_e32 v83, v83
	v_mul_f32_e32 v82, 0xbfb8aa3b, v96
	v_exp_f32_e32 v82, v82
	v_add_f32_e32 v83, 1.0, v83
	v_rcp_f32_e32 v94, v83
	v_mul_f32_e32 v83, 0xbfb8aa3b, v97
	v_exp_f32_e32 v83, v83
	v_add_f32_e32 v82, 1.0, v82
	v_rcp_f32_e32 v82, v82
	v_add_f32_e32 v83, 1.0, v83
	v_rcp_f32_e32 v83, v83
	s_nop 0
	v_pk_mul_f32 v[82:83], v[96:97], v[82:83]
	s_nop 0
	v_pk_mul_f32 v[92:93], v[82:83], v[92:93]
	v_mul_f32_e32 v82, 0xbfb8aa3b, v89
	v_exp_f32_e32 v82, v82
	s_nop 0
	v_add_f32_e32 v82, 1.0, v82
	v_rcp_f32_e32 v95, v82
	s_nop 0
	v_pk_mul_f32 v[82:83], v[88:89], v[94:95]
	s_nop 0
	v_pk_mul_f32 v[88:89], v[82:83], v[84:85]
	v_lshl_add_u64 v[94:95], v[98:99], 0, v[114:115]
	v_cvt_pk_bf16_f32 v82, v90, v91
	v_cvt_pk_bf16_f32 v83, v92, v93
	v_cvt_pk_bf16_f32 v84, v86, v87
	v_cvt_pk_bf16_f32 v85, v88, v89
	global_store_dwordx4 v[94:95], v[82:85], off
	s_nop 1
	v_mul_f32_e32 v85, 0xbfb8aa3b, v70
	v_exp_f32_e32 v85, v85
	v_mul_f32_e32 v84, 0xbfb8aa3b, v78
	v_exp_f32_e32 v84, v84
	v_or_b32_e32 v82, 48, v146
	v_add_f32_e32 v85, 1.0, v85
; __device__ __forceinline__ float sigm(float x) { return rcpf_(1.f + ex2(-1.44269504f * x)); }
; __device__ __forceinline__ u32x4 pack8(f32x4 a, f32x4 b) { u32x4 w; w.x = cvt_pk_bf16(a[0], a[1]); w.y = cvt_pk_bf16(a[2], a[3]); w.z = cvt_pk_bf16(b[0], b[1]); w.w = cvt_pk_bf16(b[2], b[3]); return w; }
;     __device__ __forceinline__ void operator()(const f32x4 (&acc)[2][2][4][2], const Unit& u, int wr, int wc, int fr, int fq) const {
;     ...
;             const int col0 = u.pn * 128 + wc * 32 + 8 * fq;
; #pragma unroll
;             for (int ai = 0; ai < 2; ++ai)
; #pragma unroll
;                 for (int m = 0; m < 4; ++m) {
;                     bf16_t* rowp = O + (size_t)(row0 + ai * HALF + m * 16) * ldc + col0;
;                     f32x4 v0, v1;
; #pragma unroll
;                     for (int e = 0; e < 4; ++e) { const float a0 = acc[ai][0][m][0][e], a1 = acc[ai][0][m][1][e]; v0[e] = a0 * sigm(a0) * acc[ai][1][m][0][e]; v1[e] = a1 * sigm(a1) * acc[ai][1][m][1][e]; }
;                     *(u32x4*)rowp = pack8(v0, v1);
;                     __builtin_amdgcn_sched_barrier(0);
;                 }
	v_rcp_f32_e32 v86, v85
	v_mul_f32_e32 v85, 0xbfb8aa3b, v79
	v_exp_f32_e32 v85, v85
	v_add_f32_e32 v84, 1.0, v84
	v_rcp_f32_e32 v84, v84
	v_mad_i64_i32 v[82:83], s[2:3], v82, s52, v[140:141]
	v_add_f32_e32 v85, 1.0, v85
	v_rcp_f32_e32 v85, v85
	s_nop 0
	v_pk_mul_f32 v[78:79], v[78:79], v[84:85]
	s_nop 0
	v_pk_mul_f32 v[74:75], v[78:79], v[74:75]
	v_mul_f32_e32 v78, 0xbfb8aa3b, v71
	v_exp_f32_e32 v78, v78
	s_nop 0
	v_add_f32_e32 v78, 1.0, v78
	v_rcp_f32_e32 v87, v78
	s_nop 0
	v_pk_mul_f32 v[70:71], v[70:71], v[86:87]
	s_nop 0
	v_pk_mul_f32 v[70:71], v[70:71], v[66:67]
	v_mul_f32_e32 v67, 0xbfb8aa3b, v72
	v_exp_f32_e32 v67, v67
	v_mul_f32_e32 v66, 0xbfb8aa3b, v80
	v_exp_f32_e32 v66, v66
	v_add_f32_e32 v67, 1.0, v67
	v_rcp_f32_e32 v78, v67
	v_mul_f32_e32 v67, 0xbfb8aa3b, v81
	v_exp_f32_e32 v67, v67
	v_add_f32_e32 v66, 1.0, v66
	v_rcp_f32_e32 v66, v66
	v_add_f32_e32 v67, 1.0, v67
	v_rcp_f32_e32 v67, v67
	s_nop 0
	v_pk_mul_f32 v[66:67], v[80:81], v[66:67]
	s_nop 0
	v_pk_mul_f32 v[76:77], v[66:67], v[76:77]
	v_mul_f32_e32 v66, 0xbfb8aa3b, v73
	v_exp_f32_e32 v66, v66
	s_nop 0
	v_add_f32_e32 v66, 1.0, v66
	v_rcp_f32_e32 v79, v66
	s_nop 0
	v_pk_mul_f32 v[66:67], v[72:73], v[78:79]
	s_nop 0
	v_pk_mul_f32 v[72:73], v[66:67], v[68:69]
	v_lshl_add_u64 v[78:79], v[82:83], 0, v[114:115]
	v_cvt_pk_bf16_f32 v66, v74, v75
	v_cvt_pk_bf16_f32 v67, v76, v77
	v_cvt_pk_bf16_f32 v68, v70, v71
	v_cvt_pk_bf16_f32 v69, v72, v73
	global_store_dwordx4 v[78:79], v[66:69], off
	s_nop 1
	v_mul_f32_e32 v69, 0xbfb8aa3b, v54
	v_exp_f32_e32 v69, v69
	v_mul_f32_e32 v68, 0xbfb8aa3b, v62
	v_exp_f32_e32 v68, v68
	v_add_u32_e32 v66, 0x80, v146
	v_add_f32_e32 v69, 1.0, v69
	v_rcp_f32_e32 v70, v69
	v_mul_f32_e32 v69, 0xbfb8aa3b, v63
	v_exp_f32_e32 v69, v69
	v_add_f32_e32 v68, 1.0, v68
	v_rcp_f32_e32 v68, v68
	v_mad_i64_i32 v[66:67], s[2:3], v66, s52, v[140:141]
	v_add_f32_e32 v69, 1.0, v69
	v_rcp_f32_e32 v69, v69
	s_nop 0
	v_pk_mul_f32 v[62:63], v[62:63], v[68:69]
	s_nop 0
	v_pk_mul_f32 v[58:59], v[62:63], v[58:59]
	v_mul_f32_e32 v62, 0xbfb8aa3b, v55
	v_exp_f32_e32 v62, v62
	s_nop 0
	v_add_f32_e32 v62, 1.0, v62
	v_rcp_f32_e32 v71, v62
	s_nop 0
	v_pk_mul_f32 v[54:55], v[54:55], v[70:71]
	s_nop 0
	v_pk_mul_f32 v[54:55], v[54:55], v[50:51]
	v_mul_f32_e32 v51, 0xbfb8aa3b, v56
	v_exp_f32_e32 v51, v51
	v_mul_f32_e32 v50, 0xbfb8aa3b, v64
	v_exp_f32_e32 v50, v50
	v_add_f32_e32 v51, 1.0, v51
	v_rcp_f32_e32 v62, v51
	v_mul_f32_e32 v51, 0xbfb8aa3b, v65
	v_exp_f32_e32 v51, v51
	v_add_f32_e32 v50, 1.0, v50
	v_rcp_f32_e32 v50, v50
	v_add_f32_e32 v51, 1.0, v51
	v_rcp_f32_e32 v51, v51
	s_nop 0
	v_pk_mul_f32 v[50:51], v[64:65], v[50:51]
	s_nop 0
	v_pk_mul_f32 v[60:61], v[50:51], v[60:61]
	v_mul_f32_e32 v50, 0xbfb8aa3b, v57
	v_exp_f32_e32 v50, v50
	s_nop 0
	v_add_f32_e32 v50, 1.0, v50
	v_rcp_f32_e32 v63, v50
	s_nop 0
	v_pk_mul_f32 v[50:51], v[56:57], v[62:63]
	s_nop 0
	v_pk_mul_f32 v[56:57], v[50:51], v[52:53]
	v_lshl_add_u64 v[62:63], v[66:67], 0, v[114:115]
	v_cvt_pk_bf16_f32 v50, v58, v59
	v_cvt_pk_bf16_f32 v51, v60, v61
	v_cvt_pk_bf16_f32 v52, v54, v55
	v_cvt_pk_bf16_f32 v53, v56, v57
	global_store_dwordx4 v[62:63], v[50:53], off
	s_nop 1
	v_mul_f32_e32 v53, 0xbfb8aa3b, v38
	v_exp_f32_e32 v53, v53
	v_mul_f32_e32 v52, 0xbfb8aa3b, v46
	v_exp_f32_e32 v52, v52
	v_add_u32_e32 v50, 0x90, v146
	v_add_f32_e32 v53, 1.0, v53
	v_rcp_f32_e32 v54, v53
	v_mul_f32_e32 v53, 0xbfb8aa3b, v47
	v_exp_f32_e32 v53, v53
	v_add_f32_e32 v52, 1.0, v52
	v_rcp_f32_e32 v52, v52
	v_mad_i64_i32 v[50:51], s[2:3], v50, s52, v[140:141]
	v_add_f32_e32 v53, 1.0, v53
	v_rcp_f32_e32 v53, v53
	s_nop 0
	v_pk_mul_f32 v[46:47], v[46:47], v[52:53]
	s_nop 0
	v_pk_mul_f32 v[42:43], v[46:47], v[42:43]
	v_mul_f32_e32 v46, 0xbfb8aa3b, v39
	v_exp_f32_e32 v46, v46
	s_nop 0
	v_add_f32_e32 v46, 1.0, v46
	v_rcp_f32_e32 v55, v46
	s_nop 0
	v_pk_mul_f32 v[38:39], v[38:39], v[54:55]
	s_nop 0
	v_pk_mul_f32 v[38:39], v[38:39], v[34:35]
	v_mul_f32_e32 v35, 0xbfb8aa3b, v40
	v_exp_f32_e32 v35, v35
	v_mul_f32_e32 v34, 0xbfb8aa3b, v48
	v_exp_f32_e32 v34, v34
	v_add_f32_e32 v35, 1.0, v35
	v_rcp_f32_e32 v46, v35
	v_mul_f32_e32 v35, 0xbfb8aa3b, v49
	v_exp_f32_e32 v35, v35
	v_add_f32_e32 v34, 1.0, v34
	v_rcp_f32_e32 v34, v34
	v_add_f32_e32 v35, 1.0, v35
	v_rcp_f32_e32 v35, v35
	s_nop 0
	v_pk_mul_f32 v[34:35], v[48:49], v[34:35]
	s_nop 0
	v_pk_mul_f32 v[44:45], v[34:35], v[44:45]
	v_mul_f32_e32 v34, 0xbfb8aa3b, v41
	v_exp_f32_e32 v34, v34
	s_nop 0
	v_add_f32_e32 v34, 1.0, v34
	v_rcp_f32_e32 v47, v34
	s_nop 0
	v_pk_mul_f32 v[34:35], v[40:41], v[46:47]
	s_nop 0
	v_pk_mul_f32 v[40:41], v[34:35], v[36:37]
	v_lshl_add_u64 v[46:47], v[50:51], 0, v[114:115]
	v_cvt_pk_bf16_f32 v34, v42, v43
	v_cvt_pk_bf16_f32 v35, v44, v45
	v_cvt_pk_bf16_f32 v36, v38, v39
	v_cvt_pk_bf16_f32 v37, v40, v41
	global_store_dwordx4 v[46:47], v[34:37], off
	s_nop 1
	v_mul_f32_e32 v37, 0xbfb8aa3b, v22
	v_exp_f32_e32 v37, v37
	v_mul_f32_e32 v36, 0xbfb8aa3b, v30
	v_exp_f32_e32 v36, v36
	v_add_u32_e32 v34, 0xa0, v146
	v_add_f32_e32 v37, 1.0, v37
	v_rcp_f32_e32 v38, v37
	v_mul_f32_e32 v37, 0xbfb8aa3b, v31
	v_exp_f32_e32 v37, v37
	v_add_f32_e32 v36, 1.0, v36
	v_rcp_f32_e32 v36, v36
	v_mad_i64_i32 v[34:35], s[2:3], v34, s52, v[140:141]
	v_add_f32_e32 v37, 1.0, v37
	v_rcp_f32_e32 v37, v37
	s_nop 0
	v_pk_mul_f32 v[30:31], v[30:31], v[36:37]
	s_nop 0
	v_pk_mul_f32 v[26:27], v[30:31], v[26:27]
	v_mul_f32_e32 v30, 0xbfb8aa3b, v23
	v_exp_f32_e32 v30, v30
	s_nop 0
	v_add_f32_e32 v30, 1.0, v30
	v_rcp_f32_e32 v39, v30
	s_nop 0
	v_pk_mul_f32 v[22:23], v[22:23], v[38:39]
	s_nop 0
	v_pk_mul_f32 v[22:23], v[22:23], v[18:19]
	v_mul_f32_e32 v19, 0xbfb8aa3b, v24
	v_exp_f32_e32 v19, v19
	v_mul_f32_e32 v18, 0xbfb8aa3b, v32
; __device__ __forceinline__ float sigm(float x) { return rcpf_(1.f + ex2(-1.44269504f * x)); }
; __device__ __forceinline__ u32x4 pack8(f32x4 a, f32x4 b) { u32x4 w; w.x = cvt_pk_bf16(a[0], a[1]); w.y = cvt_pk_bf16(a[2], a[3]); w.z = cvt_pk_bf16(b[0], b[1]); w.w = cvt_pk_bf16(b[2], b[3]); return w; }
; #define PG8_BAR __builtin_amdgcn_s_barrier()
;     __device__ __forceinline__ void operator()(const f32x4 (&acc)[2][2][4][2], const Unit& u, int wr, int wc, int fr, int fq) const {
;     ...
;             const int col0 = u.pn * 128 + wc * 32 + 8 * fq;
; #pragma unroll
;             for (int ai = 0; ai < 2; ++ai)
; #pragma unroll
;                 for (int m = 0; m < 4; ++m) {
;                     bf16_t* rowp = O + (size_t)(row0 + ai * HALF + m * 16) * ldc + col0;
;                     f32x4 v0, v1;
; #pragma unroll
;                     for (int e = 0; e < 4; ++e) { const float a0 = acc[ai][0][m][0][e], a1 = acc[ai][0][m][1][e]; v0[e] = a0 * sigm(a0) * acc[ai][1][m][0][e]; v1[e] = a1 * sigm(a1) * acc[ai][1][m][1][e]; }
;                     *(u32x4*)rowp = pack8(v0, v1);
;                     __builtin_amdgcn_sched_barrier(0);
;                 }
; template <class EpiT, class Sched>
; __device__ __forceinline__ void gemm_phase(LAS unsigned char* lds, int tid_in, const GemmDesc g, const Sched& S, const EpiT& E) {
;     ...
;         if (wr == 0) PG8_BAR;
;         E(acc, cur, wr, wc, fr, fq);
;         if (!has_next) break;
; #pragma unroll
;         for (int a = 0; a < 2; ++a)
; #pragma unroll
;             for (int b = 0; b < 2; ++b)
; #pragma unroll
;                 for (int m = 0; m < 4; ++m)
; #pragma unroll
;                     for (int n = 0; n < 2; ++n) acc[a][b][m][n] = (f32x4){0.f, 0.f, 0.f, 0.f};
;         cur = nxt; cA = nA; cB = nB; ++ui;
;         if (wr == 1) PG8_BAR;
;     }
	v_exp_f32_e32 v18, v18
	v_add_f32_e32 v19, 1.0, v19
	v_rcp_f32_e32 v30, v19
	v_mul_f32_e32 v19, 0xbfb8aa3b, v33
	v_exp_f32_e32 v19, v19
	v_add_f32_e32 v18, 1.0, v18
	v_rcp_f32_e32 v18, v18
	v_add_f32_e32 v19, 1.0, v19
	v_rcp_f32_e32 v19, v19
	s_nop 0
	v_pk_mul_f32 v[18:19], v[32:33], v[18:19]
	s_nop 0
	v_pk_mul_f32 v[28:29], v[18:19], v[28:29]
	v_mul_f32_e32 v18, 0xbfb8aa3b, v25
	v_exp_f32_e32 v18, v18
	s_nop 0
	v_add_f32_e32 v18, 1.0, v18
	v_rcp_f32_e32 v31, v18
	s_nop 0
	v_pk_mul_f32 v[18:19], v[24:25], v[30:31]
	s_nop 0
	v_pk_mul_f32 v[24:25], v[18:19], v[20:21]
	v_lshl_add_u64 v[30:31], v[34:35], 0, v[114:115]
	v_cvt_pk_bf16_f32 v18, v26, v27
	v_cvt_pk_bf16_f32 v19, v28, v29
	v_cvt_pk_bf16_f32 v20, v22, v23
	v_cvt_pk_bf16_f32 v21, v24, v25
	global_store_dwordx4 v[30:31], v[18:21], off
	s_nop 1
	v_mul_f32_e32 v21, 0xbfb8aa3b, v6
	v_exp_f32_e32 v21, v21
	v_mul_f32_e32 v20, 0xbfb8aa3b, v14
	v_exp_f32_e32 v20, v20
	v_add_u32_e32 v18, 0xb0, v146
	v_add_f32_e32 v21, 1.0, v21
	v_rcp_f32_e32 v22, v21
	v_mul_f32_e32 v21, 0xbfb8aa3b, v15
	v_exp_f32_e32 v21, v21
	v_add_f32_e32 v20, 1.0, v20
	v_rcp_f32_e32 v20, v20
	v_mad_i64_i32 v[18:19], s[2:3], v18, s52, v[140:141]
	v_add_f32_e32 v21, 1.0, v21
	v_rcp_f32_e32 v21, v21
	s_nop 0
	v_pk_mul_f32 v[14:15], v[14:15], v[20:21]
	s_nop 0
	v_pk_mul_f32 v[10:11], v[14:15], v[10:11]
	v_mul_f32_e32 v14, 0xbfb8aa3b, v7
	v_exp_f32_e32 v14, v14
	s_nop 0
	v_add_f32_e32 v14, 1.0, v14
	v_rcp_f32_e32 v23, v14
	s_nop 0
	v_pk_mul_f32 v[6:7], v[6:7], v[22:23]
	s_nop 0
	v_pk_mul_f32 v[6:7], v[6:7], v[2:3]
	v_mul_f32_e32 v3, 0xbfb8aa3b, v8
	v_exp_f32_e32 v3, v3
	v_mul_f32_e32 v2, 0xbfb8aa3b, v16
	v_exp_f32_e32 v2, v2
	v_add_f32_e32 v3, 1.0, v3
	v_rcp_f32_e32 v14, v3
	v_mul_f32_e32 v3, 0xbfb8aa3b, v17
	v_exp_f32_e32 v3, v3
	v_add_f32_e32 v2, 1.0, v2
	v_rcp_f32_e32 v2, v2
	v_add_f32_e32 v3, 1.0, v3
	v_rcp_f32_e32 v3, v3
	s_nop 0
	v_pk_mul_f32 v[2:3], v[16:17], v[2:3]
	s_nop 0
	v_pk_mul_f32 v[12:13], v[2:3], v[12:13]
	v_mul_f32_e32 v2, 0xbfb8aa3b, v9
	v_exp_f32_e32 v2, v2
	s_nop 0
	v_add_f32_e32 v2, 1.0, v2
	v_rcp_f32_e32 v15, v2
	s_nop 0
	v_pk_mul_f32 v[2:3], v[8:9], v[14:15]
	s_nop 0
	v_pk_mul_f32 v[8:9], v[2:3], v[4:5]
	v_lshl_add_u64 v[14:15], v[18:19], 0, v[114:115]
	v_cvt_pk_bf16_f32 v2, v10, v11
	v_cvt_pk_bf16_f32 v3, v12, v13
	v_cvt_pk_bf16_f32 v4, v6, v7
	v_cvt_pk_bf16_f32 v5, v8, v9
	global_store_dwordx4 v[14:15], v[2:5], off
	s_andn2_b64 vcc, exec, s[0:1]
	s_mov_b64 s[0:1], -1
	s_cbranch_vccnz .LBB0_183
	s_andn2_b64 vcc, exec, s[24:25]
	s_cbranch_vccnz .LBB0_182
	s_barrier
	s_branch .LBB0_182
.Lepi_last_1:
	v_mul_f32_e32 v147, 0xbfb8aa3b, v126
	v_exp_f32_e32 v147, v147
	v_lshl_or_b32 v148, s16, 7, v144
	v_lshl_add_u32 v146, s88, 8, v142
	v_ashrrev_i32_e32 v149, 31, v148
	v_add_f32_e32 v147, 1.0, v147
	v_rcp_f32_e32 v152, v147
	v_mul_f32_e32 v147, 0xbfb8aa3b, v118
	v_exp_f32_e32 v147, v147
	v_mov_b64_e32 v[140:141], s[30:31]
	v_mad_i64_i32 v[150:151], s[2:3], v146, s52, v[140:141]
	v_add_f32_e32 v147, 1.0, v147
	v_rcp_f32_e32 v154, v147
	v_mul_f32_e32 v147, 0xbfb8aa3b, v127
	v_exp_f32_e32 v147, v147
	s_nop 0
	v_add_f32_e32 v147, 1.0, v147
	v_rcp_f32_e32 v153, v147
	s_nop 0
	v_pk_mul_f32 v[126:127], v[126:127], v[152:153]
	s_nop 0
	v_pk_mul_f32 v[122:123], v[126:127], v[122:123]
	v_mul_f32_e32 v126, 0xbfb8aa3b, v119
	v_exp_f32_e32 v126, v126
	s_nop 0
	v_add_f32_e32 v126, 1.0, v126
	v_rcp_f32_e32 v155, v126
	s_nop 0
	v_pk_mul_f32 v[118:119], v[118:119], v[154:155]
	s_nop 0
	v_pk_mul_f32 v[118:119], v[118:119], v[114:115]
	v_mul_f32_e32 v115, 0xbfb8aa3b, v120
	v_exp_f32_e32 v115, v115
	v_mul_f32_e32 v114, 0xbfb8aa3b, v128
	v_exp_f32_e32 v114, v114
	v_cvt_pk_bf16_f32 v118, v118, v119
	v_add_f32_e32 v115, 1.0, v115
	v_rcp_f32_e32 v126, v115
	v_mul_f32_e32 v115, 0xbfb8aa3b, v129
	v_exp_f32_e32 v115, v115
	v_add_f32_e32 v114, 1.0, v114
	v_rcp_f32_e32 v114, v114
	v_add_f32_e32 v115, 1.0, v115
	v_rcp_f32_e32 v115, v115
	s_nop 0
	v_pk_mul_f32 v[114:115], v[128:129], v[114:115]
	s_nop 0
	v_pk_mul_f32 v[124:125], v[114:115], v[124:125]
	v_mul_f32_e32 v114, 0xbfb8aa3b, v121
	v_exp_f32_e32 v114, v114
	s_nop 0
	v_add_f32_e32 v114, 1.0, v114
	v_rcp_f32_e32 v127, v114
	s_nop 0
	v_pk_mul_f32 v[114:115], v[120:121], v[126:127]
	s_nop 0
	v_pk_mul_f32 v[120:121], v[114:115], v[116:117]
	v_lshlrev_b64 v[114:115], 1, v[148:149]
	v_lshl_add_u64 v[126:127], v[150:151], 0, v[114:115]
	v_cvt_pk_bf16_f32 v116, v122, v123
	v_cvt_pk_bf16_f32 v117, v124, v125
	v_cvt_pk_bf16_f32 v119, v120, v121
	global_store_dwordx4 v[126:127], v[116:119], off sc1
	s_nop 1
	v_mul_f32_e32 v119, 0xbfb8aa3b, v102
	v_exp_f32_e32 v119, v119
	v_mul_f32_e32 v118, 0xbfb8aa3b, v110
	v_exp_f32_e32 v118, v118
	v_or_b32_e32 v116, 16, v146
	v_add_f32_e32 v119, 1.0, v119
	v_rcp_f32_e32 v120, v119
	v_mul_f32_e32 v119, 0xbfb8aa3b, v111
	v_exp_f32_e32 v119, v119
	v_add_f32_e32 v118, 1.0, v118
	v_rcp_f32_e32 v118, v118
	v_mad_i64_i32 v[116:117], s[2:3], v116, s52, v[140:141]
	v_add_f32_e32 v119, 1.0, v119
	v_rcp_f32_e32 v119, v119
	s_nop 0
	v_pk_mul_f32 v[110:111], v[110:111], v[118:119]
	s_nop 0
	v_pk_mul_f32 v[106:107], v[110:111], v[106:107]
	v_mul_f32_e32 v110, 0xbfb8aa3b, v103
	v_exp_f32_e32 v110, v110
	s_nop 0
	v_add_f32_e32 v110, 1.0, v110
	v_rcp_f32_e32 v121, v110
	s_nop 0
	v_pk_mul_f32 v[102:103], v[102:103], v[120:121]
	s_nop 0
	v_pk_mul_f32 v[102:103], v[102:103], v[98:99]
	v_mul_f32_e32 v99, 0xbfb8aa3b, v104
	v_exp_f32_e32 v99, v99
	v_mul_f32_e32 v98, 0xbfb8aa3b, v112
	v_exp_f32_e32 v98, v98
	v_add_f32_e32 v99, 1.0, v99
	v_rcp_f32_e32 v110, v99
	v_mul_f32_e32 v99, 0xbfb8aa3b, v113
	v_exp_f32_e32 v99, v99
	v_add_f32_e32 v98, 1.0, v98
	v_rcp_f32_e32 v98, v98
; __device__ __forceinline__ float sigm(float x) { return rcpf_(1.f + ex2(-1.44269504f * x)); }
; __device__ __forceinline__ u32x4 pack8(f32x4 a, f32x4 b) { u32x4 w; w.x = cvt_pk_bf16(a[0], a[1]); w.y = cvt_pk_bf16(a[2], a[3]); w.z = cvt_pk_bf16(b[0], b[1]); w.w = cvt_pk_bf16(b[2], b[3]); return w; }
;     __device__ __forceinline__ void operator()(const f32x4 (&acc)[2][2][4][2], const Unit& u, int wr, int wc, int fr, int fq) const {
;     ...
;             const int col0 = u.pn * 128 + wc * 32 + 8 * fq;
; #pragma unroll
;             for (int ai = 0; ai < 2; ++ai)
; #pragma unroll
;                 for (int m = 0; m < 4; ++m) {
;                     bf16_t* rowp = O + (size_t)(row0 + ai * HALF + m * 16) * ldc + col0;
;                     f32x4 v0, v1;
; #pragma unroll
;                     for (int e = 0; e < 4; ++e) { const float a0 = acc[ai][0][m][0][e], a1 = acc[ai][0][m][1][e]; v0[e] = a0 * sigm(a0) * acc[ai][1][m][0][e]; v1[e] = a1 * sigm(a1) * acc[ai][1][m][1][e]; }
;                     *(u32x4*)rowp = pack8(v0, v1);
;                     __builtin_amdgcn_sched_barrier(0);
;                 }
	v_add_f32_e32 v99, 1.0, v99
	v_rcp_f32_e32 v99, v99
	s_nop 0
	v_pk_mul_f32 v[98:99], v[112:113], v[98:99]
	s_nop 0
	v_pk_mul_f32 v[108:109], v[98:99], v[108:109]
	v_mul_f32_e32 v98, 0xbfb8aa3b, v105
	v_exp_f32_e32 v98, v98
	s_nop 0
	v_add_f32_e32 v98, 1.0, v98
	v_rcp_f32_e32 v111, v98
	s_nop 0
	v_pk_mul_f32 v[98:99], v[104:105], v[110:111]
	s_nop 0
	v_pk_mul_f32 v[104:105], v[98:99], v[100:101]
	v_lshl_add_u64 v[110:111], v[116:117], 0, v[114:115]
	v_cvt_pk_bf16_f32 v98, v106, v107
	v_cvt_pk_bf16_f32 v99, v108, v109
	v_cvt_pk_bf16_f32 v100, v102, v103
	v_cvt_pk_bf16_f32 v101, v104, v105
	global_store_dwordx4 v[110:111], v[98:101], off sc1
	s_nop 1
	v_mul_f32_e32 v101, 0xbfb8aa3b, v86
	v_exp_f32_e32 v101, v101
	v_mul_f32_e32 v100, 0xbfb8aa3b, v94
	v_exp_f32_e32 v100, v100
	v_or_b32_e32 v98, 32, v146
	v_add_f32_e32 v101, 1.0, v101
	v_rcp_f32_e32 v102, v101
	v_mul_f32_e32 v101, 0xbfb8aa3b, v95
	v_exp_f32_e32 v101, v101
	v_add_f32_e32 v100, 1.0, v100
	v_rcp_f32_e32 v100, v100
	v_mad_i64_i32 v[98:99], s[2:3], v98, s52, v[140:141]
	v_add_f32_e32 v101, 1.0, v101
	v_rcp_f32_e32 v101, v101
	s_nop 0
	v_pk_mul_f32 v[94:95], v[94:95], v[100:101]
	s_nop 0
	v_pk_mul_f32 v[90:91], v[94:95], v[90:91]
	v_mul_f32_e32 v94, 0xbfb8aa3b, v87
	v_exp_f32_e32 v94, v94
	s_nop 0
	v_add_f32_e32 v94, 1.0, v94
	v_rcp_f32_e32 v103, v94
	s_nop 0
	v_pk_mul_f32 v[86:87], v[86:87], v[102:103]
	s_nop 0
	v_pk_mul_f32 v[86:87], v[86:87], v[82:83]
	v_mul_f32_e32 v83, 0xbfb8aa3b, v88
	v_exp_f32_e32 v83, v83
	v_mul_f32_e32 v82, 0xbfb8aa3b, v96
	v_exp_f32_e32 v82, v82
	v_add_f32_e32 v83, 1.0, v83
	v_rcp_f32_e32 v94, v83
	v_mul_f32_e32 v83, 0xbfb8aa3b, v97
	v_exp_f32_e32 v83, v83
	v_add_f32_e32 v82, 1.0, v82
	v_rcp_f32_e32 v82, v82
	v_add_f32_e32 v83, 1.0, v83
	v_rcp_f32_e32 v83, v83
	s_nop 0
	v_pk_mul_f32 v[82:83], v[96:97], v[82:83]
	s_nop 0
	v_pk_mul_f32 v[92:93], v[82:83], v[92:93]
	v_mul_f32_e32 v82, 0xbfb8aa3b, v89
	v_exp_f32_e32 v82, v82
	s_nop 0
	v_add_f32_e32 v82, 1.0, v82
	v_rcp_f32_e32 v95, v82
	s_nop 0
	v_pk_mul_f32 v[82:83], v[88:89], v[94:95]
	s_nop 0
	v_pk_mul_f32 v[88:89], v[82:83], v[84:85]
	v_lshl_add_u64 v[94:95], v[98:99], 0, v[114:115]
	v_cvt_pk_bf16_f32 v82, v90, v91
	v_cvt_pk_bf16_f32 v83, v92, v93
	v_cvt_pk_bf16_f32 v84, v86, v87
	v_cvt_pk_bf16_f32 v85, v88, v89
	global_store_dwordx4 v[94:95], v[82:85], off sc1
	s_nop 1
	v_mul_f32_e32 v85, 0xbfb8aa3b, v70
	v_exp_f32_e32 v85, v85
	v_mul_f32_e32 v84, 0xbfb8aa3b, v78
	v_exp_f32_e32 v84, v84
	v_or_b32_e32 v82, 48, v146
	v_add_f32_e32 v85, 1.0, v85
	v_rcp_f32_e32 v86, v85
	v_mul_f32_e32 v85, 0xbfb8aa3b, v79
	v_exp_f32_e32 v85, v85
	v_add_f32_e32 v84, 1.0, v84
	v_rcp_f32_e32 v84, v84
	v_mad_i64_i32 v[82:83], s[2:3], v82, s52, v[140:141]
	v_add_f32_e32 v85, 1.0, v85
	v_rcp_f32_e32 v85, v85
	s_nop 0
	v_pk_mul_f32 v[78:79], v[78:79], v[84:85]
	s_nop 0
	v_pk_mul_f32 v[74:75], v[78:79], v[74:75]
	v_mul_f32_e32 v78, 0xbfb8aa3b, v71
	v_exp_f32_e32 v78, v78
	s_nop 0
	v_add_f32_e32 v78, 1.0, v78
	v_rcp_f32_e32 v87, v78
	s_nop 0
	v_pk_mul_f32 v[70:71], v[70:71], v[86:87]
	s_nop 0
	v_pk_mul_f32 v[70:71], v[70:71], v[66:67]
	v_mul_f32_e32 v67, 0xbfb8aa3b, v72
	v_exp_f32_e32 v67, v67
	v_mul_f32_e32 v66, 0xbfb8aa3b, v80
	v_exp_f32_e32 v66, v66
	v_add_f32_e32 v67, 1.0, v67
	v_rcp_f32_e32 v78, v67
	v_mul_f32_e32 v67, 0xbfb8aa3b, v81
	v_exp_f32_e32 v67, v67
	v_add_f32_e32 v66, 1.0, v66
	v_rcp_f32_e32 v66, v66
	v_add_f32_e32 v67, 1.0, v67
	v_rcp_f32_e32 v67, v67
	s_nop 0
	v_pk_mul_f32 v[66:67], v[80:81], v[66:67]
	s_nop 0
	v_pk_mul_f32 v[76:77], v[66:67], v[76:77]
	v_mul_f32_e32 v66, 0xbfb8aa3b, v73
	v_exp_f32_e32 v66, v66
	s_nop 0
	v_add_f32_e32 v66, 1.0, v66
	v_rcp_f32_e32 v79, v66
	s_nop 0
	v_pk_mul_f32 v[66:67], v[72:73], v[78:79]
	s_nop 0
	v_pk_mul_f32 v[72:73], v[66:67], v[68:69]
	v_lshl_add_u64 v[78:79], v[82:83], 0, v[114:115]
	v_cvt_pk_bf16_f32 v66, v74, v75
	v_cvt_pk_bf16_f32 v67, v76, v77
	v_cvt_pk_bf16_f32 v68, v70, v71
	v_cvt_pk_bf16_f32 v69, v72, v73
	global_store_dwordx4 v[78:79], v[66:69], off sc1
	s_nop 1
	v_mul_f32_e32 v69, 0xbfb8aa3b, v54
	v_exp_f32_e32 v69, v69
	v_mul_f32_e32 v68, 0xbfb8aa3b, v62
	v_exp_f32_e32 v68, v68
	v_add_u32_e32 v66, 0x80, v146
	v_add_f32_e32 v69, 1.0, v69
	v_rcp_f32_e32 v70, v69
	v_mul_f32_e32 v69, 0xbfb8aa3b, v63
	v_exp_f32_e32 v69, v69
	v_add_f32_e32 v68, 1.0, v68
	v_rcp_f32_e32 v68, v68
	v_mad_i64_i32 v[66:67], s[2:3], v66, s52, v[140:141]
	v_add_f32_e32 v69, 1.0, v69
	v_rcp_f32_e32 v69, v69
	s_nop 0
	v_pk_mul_f32 v[62:63], v[62:63], v[68:69]
	s_nop 0
	v_pk_mul_f32 v[58:59], v[62:63], v[58:59]
	v_mul_f32_e32 v62, 0xbfb8aa3b, v55
	v_exp_f32_e32 v62, v62
	s_nop 0
	v_add_f32_e32 v62, 1.0, v62
	v_rcp_f32_e32 v71, v62
	s_nop 0
	v_pk_mul_f32 v[54:55], v[54:55], v[70:71]
	s_nop 0
	v_pk_mul_f32 v[54:55], v[54:55], v[50:51]
	v_mul_f32_e32 v51, 0xbfb8aa3b, v56
	v_exp_f32_e32 v51, v51
	v_mul_f32_e32 v50, 0xbfb8aa3b, v64
	v_exp_f32_e32 v50, v50
	v_add_f32_e32 v51, 1.0, v51
	v_rcp_f32_e32 v62, v51
	v_mul_f32_e32 v51, 0xbfb8aa3b, v65
	v_exp_f32_e32 v51, v51
	v_add_f32_e32 v50, 1.0, v50
	v_rcp_f32_e32 v50, v50
	v_add_f32_e32 v51, 1.0, v51
	v_rcp_f32_e32 v51, v51
	s_nop 0
	v_pk_mul_f32 v[50:51], v[64:65], v[50:51]
	s_nop 0
	v_pk_mul_f32 v[60:61], v[50:51], v[60:61]
	v_mul_f32_e32 v50, 0xbfb8aa3b, v57
	v_exp_f32_e32 v50, v50
	s_nop 0
	v_add_f32_e32 v50, 1.0, v50
	v_rcp_f32_e32 v63, v50
	s_nop 0
; __device__ __forceinline__ float sigm(float x) { return rcpf_(1.f + ex2(-1.44269504f * x)); }
; __device__ __forceinline__ u32x4 pack8(f32x4 a, f32x4 b) { u32x4 w; w.x = cvt_pk_bf16(a[0], a[1]); w.y = cvt_pk_bf16(a[2], a[3]); w.z = cvt_pk_bf16(b[0], b[1]); w.w = cvt_pk_bf16(b[2], b[3]); return w; }
;     __device__ __forceinline__ void operator()(const f32x4 (&acc)[2][2][4][2], const Unit& u, int wr, int wc, int fr, int fq) const {
;     ...
;             const int col0 = u.pn * 128 + wc * 32 + 8 * fq;
; #pragma unroll
;             for (int ai = 0; ai < 2; ++ai)
; #pragma unroll
;                 for (int m = 0; m < 4; ++m) {
;                     bf16_t* rowp = O + (size_t)(row0 + ai * HALF + m * 16) * ldc + col0;
;                     f32x4 v0, v1;
; #pragma unroll
;                     for (int e = 0; e < 4; ++e) { const float a0 = acc[ai][0][m][0][e], a1 = acc[ai][0][m][1][e]; v0[e] = a0 * sigm(a0) * acc[ai][1][m][0][e]; v1[e] = a1 * sigm(a1) * acc[ai][1][m][1][e]; }
;                     *(u32x4*)rowp = pack8(v0, v1);
;                     __builtin_amdgcn_sched_barrier(0);
;                 }
; template <class EpiT, class Sched>
; __device__ __forceinline__ void gemm_phase(LAS unsigned char* lds, int tid_in, const GemmDesc g, const Sched& S, const EpiT& E) {
;     ...
;         E(acc, cur, wr, wc, fr, fq);
;         if (!has_next) break;
	v_pk_mul_f32 v[50:51], v[56:57], v[62:63]
	s_nop 0
	v_pk_mul_f32 v[56:57], v[50:51], v[52:53]
	v_lshl_add_u64 v[62:63], v[66:67], 0, v[114:115]
	v_cvt_pk_bf16_f32 v50, v58, v59
	v_cvt_pk_bf16_f32 v51, v60, v61
	v_cvt_pk_bf16_f32 v52, v54, v55
	v_cvt_pk_bf16_f32 v53, v56, v57
	global_store_dwordx4 v[62:63], v[50:53], off sc1
	s_nop 1
	v_mul_f32_e32 v53, 0xbfb8aa3b, v38
	v_exp_f32_e32 v53, v53
	v_mul_f32_e32 v52, 0xbfb8aa3b, v46
	v_exp_f32_e32 v52, v52
	v_add_u32_e32 v50, 0x90, v146
	v_add_f32_e32 v53, 1.0, v53
	v_rcp_f32_e32 v54, v53
	v_mul_f32_e32 v53, 0xbfb8aa3b, v47
	v_exp_f32_e32 v53, v53
	v_add_f32_e32 v52, 1.0, v52
	v_rcp_f32_e32 v52, v52
	v_mad_i64_i32 v[50:51], s[2:3], v50, s52, v[140:141]
	v_add_f32_e32 v53, 1.0, v53
	v_rcp_f32_e32 v53, v53
	s_nop 0
	v_pk_mul_f32 v[46:47], v[46:47], v[52:53]
	s_nop 0
	v_pk_mul_f32 v[42:43], v[46:47], v[42:43]
	v_mul_f32_e32 v46, 0xbfb8aa3b, v39
	v_exp_f32_e32 v46, v46
	s_nop 0
	v_add_f32_e32 v46, 1.0, v46
	v_rcp_f32_e32 v55, v46
	s_nop 0
	v_pk_mul_f32 v[38:39], v[38:39], v[54:55]
	s_nop 0
	v_pk_mul_f32 v[38:39], v[38:39], v[34:35]
	v_mul_f32_e32 v35, 0xbfb8aa3b, v40
	v_exp_f32_e32 v35, v35
	v_mul_f32_e32 v34, 0xbfb8aa3b, v48
	v_exp_f32_e32 v34, v34
	v_add_f32_e32 v35, 1.0, v35
	v_rcp_f32_e32 v46, v35
	v_mul_f32_e32 v35, 0xbfb8aa3b, v49
	v_exp_f32_e32 v35, v35
	v_add_f32_e32 v34, 1.0, v34
	v_rcp_f32_e32 v34, v34
	v_add_f32_e32 v35, 1.0, v35
	v_rcp_f32_e32 v35, v35
	s_nop 0
	v_pk_mul_f32 v[34:35], v[48:49], v[34:35]
	s_nop 0
	v_pk_mul_f32 v[44:45], v[34:35], v[44:45]
	v_mul_f32_e32 v34, 0xbfb8aa3b, v41
	v_exp_f32_e32 v34, v34
	s_nop 0
	v_add_f32_e32 v34, 1.0, v34
	v_rcp_f32_e32 v47, v34
	s_nop 0
	v_pk_mul_f32 v[34:35], v[40:41], v[46:47]
	s_nop 0
	v_pk_mul_f32 v[40:41], v[34:35], v[36:37]
	v_lshl_add_u64 v[46:47], v[50:51], 0, v[114:115]
	v_cvt_pk_bf16_f32 v34, v42, v43
	v_cvt_pk_bf16_f32 v35, v44, v45
	v_cvt_pk_bf16_f32 v36, v38, v39
	v_cvt_pk_bf16_f32 v37, v40, v41
	global_store_dwordx4 v[46:47], v[34:37], off sc1
	s_nop 1
	v_mul_f32_e32 v37, 0xbfb8aa3b, v22
	v_exp_f32_e32 v37, v37
	v_mul_f32_e32 v36, 0xbfb8aa3b, v30
	v_exp_f32_e32 v36, v36
	v_add_u32_e32 v34, 0xa0, v146
	v_add_f32_e32 v37, 1.0, v37
	v_rcp_f32_e32 v38, v37
	v_mul_f32_e32 v37, 0xbfb8aa3b, v31
	v_exp_f32_e32 v37, v37
	v_add_f32_e32 v36, 1.0, v36
	v_rcp_f32_e32 v36, v36
	v_mad_i64_i32 v[34:35], s[2:3], v34, s52, v[140:141]
	v_add_f32_e32 v37, 1.0, v37
	v_rcp_f32_e32 v37, v37
	s_nop 0
	v_pk_mul_f32 v[30:31], v[30:31], v[36:37]
	s_nop 0
	v_pk_mul_f32 v[26:27], v[30:31], v[26:27]
	v_mul_f32_e32 v30, 0xbfb8aa3b, v23
	v_exp_f32_e32 v30, v30
	s_nop 0
	v_add_f32_e32 v30, 1.0, v30
	v_rcp_f32_e32 v39, v30
	s_nop 0
	v_pk_mul_f32 v[22:23], v[22:23], v[38:39]
	s_nop 0
	v_pk_mul_f32 v[22:23], v[22:23], v[18:19]
	v_mul_f32_e32 v19, 0xbfb8aa3b, v24
	v_exp_f32_e32 v19, v19
	v_mul_f32_e32 v18, 0xbfb8aa3b, v32
	v_exp_f32_e32 v18, v18
	v_add_f32_e32 v19, 1.0, v19
	v_rcp_f32_e32 v30, v19
	v_mul_f32_e32 v19, 0xbfb8aa3b, v33
	v_exp_f32_e32 v19, v19
	v_add_f32_e32 v18, 1.0, v18
	v_rcp_f32_e32 v18, v18
	v_add_f32_e32 v19, 1.0, v19
	v_rcp_f32_e32 v19, v19
	s_nop 0
	v_pk_mul_f32 v[18:19], v[32:33], v[18:19]
	s_nop 0
	v_pk_mul_f32 v[28:29], v[18:19], v[28:29]
	v_mul_f32_e32 v18, 0xbfb8aa3b, v25
	v_exp_f32_e32 v18, v18
	s_nop 0
	v_add_f32_e32 v18, 1.0, v18
	v_rcp_f32_e32 v31, v18
	s_nop 0
	v_pk_mul_f32 v[18:19], v[24:25], v[30:31]
	s_nop 0
	v_pk_mul_f32 v[24:25], v[18:19], v[20:21]
	v_lshl_add_u64 v[30:31], v[34:35], 0, v[114:115]
	v_cvt_pk_bf16_f32 v18, v26, v27
	v_cvt_pk_bf16_f32 v19, v28, v29
	v_cvt_pk_bf16_f32 v20, v22, v23
	v_cvt_pk_bf16_f32 v21, v24, v25
	global_store_dwordx4 v[30:31], v[18:21], off sc1
	s_nop 1
	v_mul_f32_e32 v21, 0xbfb8aa3b, v6
	v_exp_f32_e32 v21, v21
	v_mul_f32_e32 v20, 0xbfb8aa3b, v14
	v_exp_f32_e32 v20, v20
	v_add_u32_e32 v18, 0xb0, v146
	v_add_f32_e32 v21, 1.0, v21
	v_rcp_f32_e32 v22, v21
	v_mul_f32_e32 v21, 0xbfb8aa3b, v15
	v_exp_f32_e32 v21, v21
	v_add_f32_e32 v20, 1.0, v20
	v_rcp_f32_e32 v20, v20
	v_mad_i64_i32 v[18:19], s[2:3], v18, s52, v[140:141]
	v_add_f32_e32 v21, 1.0, v21
	v_rcp_f32_e32 v21, v21
	s_nop 0
	v_pk_mul_f32 v[14:15], v[14:15], v[20:21]
	s_nop 0
	v_pk_mul_f32 v[10:11], v[14:15], v[10:11]
	v_mul_f32_e32 v14, 0xbfb8aa3b, v7
	v_exp_f32_e32 v14, v14
	s_nop 0
	v_add_f32_e32 v14, 1.0, v14
	v_rcp_f32_e32 v23, v14
	s_nop 0
	v_pk_mul_f32 v[6:7], v[6:7], v[22:23]
	s_nop 0
	v_pk_mul_f32 v[6:7], v[6:7], v[2:3]
	v_mul_f32_e32 v3, 0xbfb8aa3b, v8
	v_exp_f32_e32 v3, v3
	v_mul_f32_e32 v2, 0xbfb8aa3b, v16
	v_exp_f32_e32 v2, v2
	v_add_f32_e32 v3, 1.0, v3
	v_rcp_f32_e32 v14, v3
	v_mul_f32_e32 v3, 0xbfb8aa3b, v17
	v_exp_f32_e32 v3, v3
	v_add_f32_e32 v2, 1.0, v2
	v_rcp_f32_e32 v2, v2
	v_add_f32_e32 v3, 1.0, v3
	v_rcp_f32_e32 v3, v3
	s_nop 0
	v_pk_mul_f32 v[2:3], v[16:17], v[2:3]
	s_nop 0
	v_pk_mul_f32 v[12:13], v[2:3], v[12:13]
	v_mul_f32_e32 v2, 0xbfb8aa3b, v9
	v_exp_f32_e32 v2, v2
	s_nop 0
	v_add_f32_e32 v2, 1.0, v2
	v_rcp_f32_e32 v15, v2
	s_nop 0
	v_pk_mul_f32 v[2:3], v[8:9], v[14:15]
	s_nop 0
	v_pk_mul_f32 v[8:9], v[2:3], v[4:5]
	v_lshl_add_u64 v[14:15], v[18:19], 0, v[114:115]
	v_cvt_pk_bf16_f32 v2, v10, v11
	v_cvt_pk_bf16_f32 v3, v12, v13
	v_cvt_pk_bf16_f32 v4, v6, v7
	v_cvt_pk_bf16_f32 v5, v8, v9
	global_store_dwordx4 v[14:15], v[2:5], off sc1
	s_andn2_b64 vcc, exec, s[0:1]
	s_mov_b64 s[0:1], -1
	s_branch .LBB0_183

;     __device__ __forceinline__ void operator()(const f32x4 (&acc)[2][2][4][2], const Unit& u, int wr, int wc, int fr, int fq) const {
;     ...
;             const int col0 = u.pn * BM + wc * 32 + 8 * fq;
; #pragma unroll
;             for (int ai = 0; ai < 2; ++ai)
; #pragma unroll
;                 for (int m = 0; m < 4; ++m) {
;                     const size_t row = (size_t)(row0 + ai * HALF + m * 16);
; #pragma unroll
;                     for (int bj = 0; bj < 2; ++bj) {
;                         const int col = col0 + bj * HALF;
;                         f32x4 v0 = acc[ai][bj][m][0], v1 = acc[ai][bj][m][1];
;                         bf16_t* dst = O + row * ldc + col;
;                         if constexpr (MODE == 2) {
; #pragma unroll
;                             for (int e = 0; e < 4; ++e) { v0[e] = sigm(v0[e]); v1[e] = sigm(v1[e]); }
;                         }
;                         if constexpr (MODE == 4) {
;                             const f32x4 b0 = *(const f32x4*)(bias + u.tag * 256 + col), b1 = *(const f32x4*)(bias + u.tag * 256 + col + 4);
; #pragma unroll
;                             for (int e = 0; e < 4; ++e) { v0[e] = gelu_tanh(v0[e] + b0[e]); v1[e] = gelu_tanh(v1[e] + b1[e]); }
;                         }
;                         if constexpr (MODE == 3) {
;                             const u32x4 gv = *(const u32x4*)(G + row * GP + u.tag * 1024 + col);
;                             v0[0] *= bf_lo(gv.x); v0[1] *= bf_hi(gv.x); v0[2] *= bf_lo(gv.y); v0[3] *= bf_hi(gv.y);
;                             v1[0] *= bf_lo(gv.z); v1[1] *= bf_hi(gv.z); v1[2] *= bf_lo(gv.w); v1[3] *= bf_hi(gv.w);
;                             if (u.tag > 0) {
;                                 const u32x4 ov = *(const u32x4*)dst;
;                                 v0[0] += bf_lo(ov.x); v0[1] += bf_hi(ov.x); v0[2] += bf_lo(ov.y); v0[3] += bf_hi(ov.y);
;                                 v1[0] += bf_lo(ov.z); v1[1] += bf_hi(ov.z); v1[2] += bf_lo(ov.w); v1[3] += bf_hi(ov.w);
;                             }
;                         }
;                         *(u32x4*)dst = pack8(v0, v1);
;                     }
; template <class EpiT, class Sched>
; __device__ __forceinline__ void gemm_phase(LAS unsigned char* lds, int tid_in, const GemmDesc g, const Sched& S, const EpiT& E) {
;     ...
;         if (wr == 0) PG8_BAR;
;         E(acc, cur, wr, wc, fr, fq);
.LBB0_266:
	s_andn2_b64 vcc, exec, s[0:1]
	s_cbranch_vccnz .Lepi_last_2
	v_lshl_add_u32 v144, s80, 8, v140
	v_lshl_or_b32 v146, s90, 8, v142
	v_ashrrev_i32_e32 v145, 31, v144
	v_lshlrev_b64 v[148:149], 11, v[144:145]
	v_ashrrev_i32_e32 v147, 31, v146
	v_lshl_add_u64 v[148:149], s[18:19], 0, v[148:149]
	v_lshlrev_b64 v[146:147], 1, v[146:147]
	v_lshl_add_u64 v[148:149], v[148:149], 0, v[146:147]
	s_mov_b64 s[2:3], 0x40000
	s_mov_b32 s97, 0x40000
	v_cvt_pk_bf16_f32 v70, v70, v71
	v_cvt_pk_bf16_f32 v71, v72, v73
	v_cvt_pk_bf16_f32 v72, v66, v67
	v_lshl_add_u64 v[66:67], v[148:149], 0, s[2:3]
	v_cvt_pk_bf16_f32 v62, v62, v63
	v_cvt_pk_bf16_f32 v63, v64, v65
	v_cvt_pk_bf16_f32 v64, v58, v59
	v_add_co_u32_e32 v58, vcc, s97, v148
	v_cvt_pk_bf16_f32 v46, v46, v47
	v_cvt_pk_bf16_f32 v47, v48, v49
	v_cvt_pk_bf16_f32 v48, v42, v43
	v_cvt_pk_bf16_f32 v49, v44, v45
	s_mov_b64 s[2:3], 0x48000
	v_addc_co_u32_e32 v59, vcc, 0, v149, vcc
	global_store_dwordx4 v[66:67], v[46:49], off offset:256
	v_cvt_pk_bf16_f32 v110, v110, v111
	v_cvt_pk_bf16_f32 v111, v112, v113
	v_lshl_add_u64 v[46:47], v[148:149], 0, s[2:3]
	s_mov_b32 s2, 0x48000
	v_cvt_pk_bf16_f32 v112, v106, v107
	v_or_b32_e32 v106, 16, v144
	v_add_co_u32_e32 v48, vcc, s2, v148
	v_cvt_pk_bf16_f32 v30, v30, v31
	v_cvt_pk_bf16_f32 v31, v32, v33
	v_cvt_pk_bf16_f32 v32, v26, v27
	v_cvt_pk_bf16_f32 v33, v28, v29
	s_mov_b64 s[2:3], 0x50000
	v_ashrrev_i32_e32 v107, 31, v106
	v_cvt_pk_bf16_f32 v94, v94, v95
	v_cvt_pk_bf16_f32 v95, v96, v97
	v_cvt_pk_bf16_f32 v96, v90, v91
	v_or_b32_e32 v90, 32, v144
	v_addc_co_u32_e32 v49, vcc, 0, v149, vcc
	global_store_dwordx4 v[46:47], v[30:33], off offset:256
	v_lshlrev_b64 v[106:107], 11, v[106:107]
	v_ashrrev_i32_e32 v91, 31, v90
	v_lshl_add_u64 v[30:31], v[148:149], 0, s[2:3]
	s_mov_b32 s2, 0x50000
	v_cvt_pk_bf16_f32 v78, v78, v79
	v_cvt_pk_bf16_f32 v79, v80, v81
	v_cvt_pk_bf16_f32 v80, v74, v75
	v_or_b32_e32 v74, 48, v144
	v_add_co_u32_e32 v32, vcc, s2, v148
	v_cvt_pk_bf16_f32 v14, v14, v15
	v_cvt_pk_bf16_f32 v15, v16, v17
	v_cvt_pk_bf16_f32 v16, v10, v11
	v_cvt_pk_bf16_f32 v17, v12, v13
	s_mov_b64 s[2:3], 0x58000
	v_cvt_pk_bf16_f32 v113, v108, v109
	v_lshl_add_u64 v[106:107], s[18:19], 0, v[106:107]
	v_lshlrev_b64 v[90:91], 11, v[90:91]
	v_ashrrev_i32_e32 v75, 31, v74
	v_addc_co_u32_e32 v33, vcc, 0, v149, vcc
	global_store_dwordx4 v[30:31], v[14:17], off offset:256
	global_store_dwordx4 v[148:149], v[110:113], off offset:256
	v_cvt_pk_bf16_f32 v97, v92, v93
	v_lshl_add_u64 v[14:15], v[148:149], 0, s[2:3]
	s_mov_b32 s2, 0x58000
	v_lshl_add_u64 v[110:111], v[106:107], 0, v[146:147]
	v_lshl_add_u64 v[90:91], s[18:19], 0, v[90:91]
	v_lshlrev_b64 v[74:75], 11, v[74:75]
	v_add_co_u32_e32 v16, vcc, s2, v148
	global_store_dwordx4 v[110:111], v[94:97], off offset:256
	v_cvt_pk_bf16_f32 v81, v76, v77
	v_lshl_add_u64 v[74:75], s[18:19], 0, v[74:75]
	v_lshl_add_u64 v[94:95], v[90:91], 0, v[146:147]
	v_addc_co_u32_e32 v17, vcc, 0, v149, vcc
	v_cvt_pk_bf16_f32 v126, v126, v127
	v_cvt_pk_bf16_f32 v127, v128, v129
	v_cvt_pk_bf16_f32 v128, v122, v123
	v_cvt_pk_bf16_f32 v129, v124, v125
	v_cvt_pk_bf16_f32 v106, v118, v119
	v_cvt_pk_bf16_f32 v107, v120, v121
	v_cvt_pk_bf16_f32 v108, v114, v115
	v_cvt_pk_bf16_f32 v109, v116, v117
	v_cvt_pk_bf16_f32 v90, v102, v103
	v_cvt_pk_bf16_f32 v91, v104, v105
	v_cvt_pk_bf16_f32 v92, v98, v99
	v_cvt_pk_bf16_f32 v93, v100, v101
	global_store_dwordx4 v[94:95], v[78:81], off offset:256
	v_cvt_pk_bf16_f32 v76, v82, v83
	v_cvt_pk_bf16_f32 v77, v84, v85
	v_lshl_add_u64 v[78:79], v[74:75], 0, v[146:147]
	v_cvt_pk_bf16_f32 v74, v86, v87
	v_cvt_pk_bf16_f32 v75, v88, v89
	v_cvt_pk_bf16_f32 v73, v68, v69
	v_cvt_pk_bf16_f32 v65, v60, v61
	v_cvt_pk_bf16_f32 v42, v54, v55
	v_cvt_pk_bf16_f32 v43, v56, v57
	v_cvt_pk_bf16_f32 v44, v50, v51
	v_cvt_pk_bf16_f32 v45, v52, v53
	v_cvt_pk_bf16_f32 v26, v38, v39
	v_cvt_pk_bf16_f32 v27, v40, v41
	v_cvt_pk_bf16_f32 v28, v34, v35
	v_cvt_pk_bf16_f32 v29, v36, v37
	v_cvt_pk_bf16_f32 v10, v22, v23
	v_cvt_pk_bf16_f32 v11, v24, v25
	v_cvt_pk_bf16_f32 v12, v18, v19
	v_cvt_pk_bf16_f32 v13, v20, v21
	v_cvt_pk_bf16_f32 v6, v6, v7
	v_cvt_pk_bf16_f32 v7, v8, v9
	v_cvt_pk_bf16_f32 v8, v2, v3
	v_cvt_pk_bf16_f32 v9, v4, v5
	s_andn2_b64 vcc, exec, s[0:1]
	s_mov_b64 s[0:1], -1
	global_store_dwordx4 v[148:149], v[126:129], off
	global_store_dwordx4 v[110:111], v[106:109], off
	global_store_dwordx4 v[94:95], v[90:93], off
	global_store_dwordx4 v[78:79], v[74:77], off
	global_store_dwordx4 v[78:79], v[70:73], off offset:256
	global_store_dwordx4 v[58:59], v[62:65], off
	global_store_dwordx4 v[48:49], v[42:45], off
	global_store_dwordx4 v[32:33], v[26:29], off
	global_store_dwordx4 v[16:17], v[10:13], off
	global_store_dwordx4 v[14:15], v[6:9], off offset:256
	s_cbranch_vccnz .LBB0_255
	s_andn2_b64 vcc, exec, s[12:13]
	s_cbranch_vccnz .LBB0_254
	s_barrier
	s_branch .LBB0_254
; __device__ __forceinline__ float bf_lo(unsigned u) { return __uint_as_float(u << 16); }
; __device__ __forceinline__ float bf_hi(unsigned u) { return __uint_as_float(u & 0xffff0000u); }
;     __device__ __forceinline__ void operator()(const f32x4 (&acc)[2][2][4][2], const Unit& u, int wr, int wc, int fr, int fq) const {
;     ...
;             const int col0 = u.pn * BM + wc * 32 + 8 * fq;
; #pragma unroll
;             for (int ai = 0; ai < 2; ++ai)
; #pragma unroll
;                 for (int m = 0; m < 4; ++m) {
;                     const size_t row = (size_t)(row0 + ai * HALF + m * 16);
; #pragma unroll
;                     for (int bj = 0; bj < 2; ++bj) {
;                         const int col = col0 + bj * HALF;
;                         f32x4 v0 = acc[ai][bj][m][0], v1 = acc[ai][bj][m][1];
;                         bf16_t* dst = O + row * ldc + col;
;                         if constexpr (MODE == 2) {
; #pragma unroll
;                             for (int e = 0; e < 4; ++e) { v0[e] = sigm(v0[e]); v1[e] = sigm(v1[e]); }
;                         }
;                         if constexpr (MODE == 4) {
;                             const f32x4 b0 = *(const f32x4*)(bias + u.tag * 256 + col), b1 = *(const f32x4*)(bias + u.tag * 256 + col + 4);
; #pragma unroll
;                             for (int e = 0; e < 4; ++e) { v0[e] = gelu_tanh(v0[e] + b0[e]); v1[e] = gelu_tanh(v1[e] + b1[e]); }
;                         }
;                         if constexpr (MODE == 3) {
;                             const u32x4 gv = *(const u32x4*)(G + row * GP + u.tag * 1024 + col);
;                             v0[0] *= bf_lo(gv.x); v0[1] *= bf_hi(gv.x); v0[2] *= bf_lo(gv.y); v0[3] *= bf_hi(gv.y);
;                             v1[0] *= bf_lo(gv.z); v1[1] *= bf_hi(gv.z); v1[2] *= bf_lo(gv.w); v1[3] *= bf_hi(gv.w);
;                             if (u.tag > 0) {
;                                 const u32x4 ov = *(const u32x4*)dst;
;                                 v0[0] += bf_lo(ov.x); v0[1] += bf_hi(ov.x); v0[2] += bf_lo(ov.y); v0[3] += bf_hi(ov.y);
;                                 v1[0] += bf_lo(ov.z); v1[1] += bf_hi(ov.z); v1[2] += bf_lo(ov.w); v1[3] += bf_hi(ov.w);
;                             }
;                         }
;                         *(u32x4*)dst = pack8(v0, v1);
;                     }
.Lepi_last_2:
	v_lshl_add_u32 v144, s80, 8, v140
	v_lshl_or_b32 v146, s90, 8, v142
	v_ashrrev_i32_e32 v145, 31, v144
	v_lshlrev_b64 v[148:149], 11, v[144:145]
	v_ashrrev_i32_e32 v147, 31, v146
	v_lshl_add_u64 v[148:149], s[18:19], 0, v[148:149]
	v_lshlrev_b64 v[146:147], 1, v[146:147]
	v_lshl_add_u64 v[148:149], v[148:149], 0, v[146:147]
	s_mov_b64 s[2:3], 0x40000
	s_mov_b32 s97, 0x40000
	v_cvt_pk_bf16_f32 v70, v70, v71
	v_cvt_pk_bf16_f32 v71, v72, v73
	v_cvt_pk_bf16_f32 v72, v66, v67
	v_lshl_add_u64 v[66:67], v[148:149], 0, s[2:3]
	v_cvt_pk_bf16_f32 v62, v62, v63
	v_cvt_pk_bf16_f32 v63, v64, v65
	v_cvt_pk_bf16_f32 v64, v58, v59
	v_add_co_u32_e32 v58, vcc, s97, v148
	v_cvt_pk_bf16_f32 v46, v46, v47
	v_cvt_pk_bf16_f32 v47, v48, v49
	v_cvt_pk_bf16_f32 v48, v42, v43
	v_cvt_pk_bf16_f32 v49, v44, v45
	s_mov_b64 s[2:3], 0x48000
	v_addc_co_u32_e32 v59, vcc, 0, v149, vcc
	global_store_dwordx4 v[66:67], v[46:49], off offset:256 sc1
	v_cvt_pk_bf16_f32 v110, v110, v111
	v_cvt_pk_bf16_f32 v111, v112, v113
	v_lshl_add_u64 v[46:47], v[148:149], 0, s[2:3]
	s_mov_b32 s2, 0x48000
	v_cvt_pk_bf16_f32 v112, v106, v107
	v_or_b32_e32 v106, 16, v144
	v_add_co_u32_e32 v48, vcc, s2, v148
	v_cvt_pk_bf16_f32 v30, v30, v31
	v_cvt_pk_bf16_f32 v31, v32, v33
	v_cvt_pk_bf16_f32 v32, v26, v27
	v_cvt_pk_bf16_f32 v33, v28, v29
	s_mov_b64 s[2:3], 0x50000
	v_ashrrev_i32_e32 v107, 31, v106
	v_cvt_pk_bf16_f32 v94, v94, v95
	v_cvt_pk_bf16_f32 v95, v96, v97
	v_cvt_pk_bf16_f32 v96, v90, v91
	v_or_b32_e32 v90, 32, v144
	v_addc_co_u32_e32 v49, vcc, 0, v149, vcc
	global_store_dwordx4 v[46:47], v[30:33], off offset:256 sc1
	v_lshlrev_b64 v[106:107], 11, v[106:107]
	v_ashrrev_i32_e32 v91, 31, v90
	v_lshl_add_u64 v[30:31], v[148:149], 0, s[2:3]
	s_mov_b32 s2, 0x50000
	v_cvt_pk_bf16_f32 v78, v78, v79
	v_cvt_pk_bf16_f32 v79, v80, v81
	v_cvt_pk_bf16_f32 v80, v74, v75
	v_or_b32_e32 v74, 48, v144
	v_add_co_u32_e32 v32, vcc, s2, v148
	v_cvt_pk_bf16_f32 v14, v14, v15
	v_cvt_pk_bf16_f32 v15, v16, v17
	v_cvt_pk_bf16_f32 v16, v10, v11
	v_cvt_pk_bf16_f32 v17, v12, v13
	s_mov_b64 s[2:3], 0x58000
	v_cvt_pk_bf16_f32 v113, v108, v109
	v_lshl_add_u64 v[106:107], s[18:19], 0, v[106:107]
	v_lshlrev_b64 v[90:91], 11, v[90:91]
	v_ashrrev_i32_e32 v75, 31, v74
	v_addc_co_u32_e32 v33, vcc, 0, v149, vcc
	global_store_dwordx4 v[30:31], v[14:17], off offset:256 sc1
	global_store_dwordx4 v[148:149], v[110:113], off offset:256 sc1
	v_cvt_pk_bf16_f32 v97, v92, v93
	v_lshl_add_u64 v[14:15], v[148:149], 0, s[2:3]
	s_mov_b32 s2, 0x58000
	v_lshl_add_u64 v[110:111], v[106:107], 0, v[146:147]
	v_lshl_add_u64 v[90:91], s[18:19], 0, v[90:91]
	v_lshlrev_b64 v[74:75], 11, v[74:75]
	v_add_co_u32_e32 v16, vcc, s2, v148
	global_store_dwordx4 v[110:111], v[94:97], off offset:256 sc1
	v_cvt_pk_bf16_f32 v81, v76, v77
	v_lshl_add_u64 v[74:75], s[18:19], 0, v[74:75]
	v_lshl_add_u64 v[94:95], v[90:91], 0, v[146:147]
	v_addc_co_u32_e32 v17, vcc, 0, v149, vcc
	v_cvt_pk_bf16_f32 v126, v126, v127
	v_cvt_pk_bf16_f32 v127, v128, v129
	v_cvt_pk_bf16_f32 v128, v122, v123
	v_cvt_pk_bf16_f32 v129, v124, v125
	v_cvt_pk_bf16_f32 v106, v118, v119
	v_cvt_pk_bf16_f32 v107, v120, v121
	v_cvt_pk_bf16_f32 v108, v114, v115
	v_cvt_pk_bf16_f32 v109, v116, v117
	v_cvt_pk_bf16_f32 v90, v102, v103
	v_cvt_pk_bf16_f32 v91, v104, v105
	v_cvt_pk_bf16_f32 v92, v98, v99
	v_cvt_pk_bf16_f32 v93, v100, v101
	global_store_dwordx4 v[94:95], v[78:81], off offset:256 sc1
	v_cvt_pk_bf16_f32 v76, v82, v83
	v_cvt_pk_bf16_f32 v77, v84, v85
	v_lshl_add_u64 v[78:79], v[74:75], 0, v[146:147]
	v_cvt_pk_bf16_f32 v74, v86, v87
	v_cvt_pk_bf16_f32 v75, v88, v89
	v_cvt_pk_bf16_f32 v73, v68, v69
	v_cvt_pk_bf16_f32 v65, v60, v61
	v_cvt_pk_bf16_f32 v42, v54, v55
	v_cvt_pk_bf16_f32 v43, v56, v57
	v_cvt_pk_bf16_f32 v44, v50, v51
	v_cvt_pk_bf16_f32 v45, v52, v53
	v_cvt_pk_bf16_f32 v26, v38, v39
	v_cvt_pk_bf16_f32 v27, v40, v41
	v_cvt_pk_bf16_f32 v28, v34, v35
	v_cvt_pk_bf16_f32 v29, v36, v37
	v_cvt_pk_bf16_f32 v10, v22, v23
	v_cvt_pk_bf16_f32 v11, v24, v25
	v_cvt_pk_bf16_f32 v12, v18, v19
	v_cvt_pk_bf16_f32 v13, v20, v21
	v_cvt_pk_bf16_f32 v6, v6, v7
	v_cvt_pk_bf16_f32 v7, v8, v9
	v_cvt_pk_bf16_f32 v8, v2, v3
	v_cvt_pk_bf16_f32 v9, v4, v5
	s_andn2_b64 vcc, exec, s[0:1]
	s_mov_b64 s[0:1], -1
	global_store_dwordx4 v[148:149], v[126:129], off sc1
	global_store_dwordx4 v[110:111], v[106:109], off sc1
	global_store_dwordx4 v[94:95], v[90:93], off sc1
	global_store_dwordx4 v[78:79], v[74:77], off sc1
	global_store_dwordx4 v[78:79], v[70:73], off offset:256 sc1
	global_store_dwordx4 v[58:59], v[62:65], off sc1
	global_store_dwordx4 v[48:49], v[42:45], off sc1
	global_store_dwordx4 v[32:33], v[26:29], off sc1
	global_store_dwordx4 v[16:17], v[10:13], off sc1
	global_store_dwordx4 v[14:15], v[6:9], off offset:256 sc1
	s_branch .LBB0_255

;     __device__ __forceinline__ void operator()(const f32x4 (&acc)[2][2][4][2], const Unit& u, int wr, int wc, int fr, int fq) const {
;     ...
;             const int col0 = u.pn * BM + wc * 32 + 8 * fq;
; #pragma unroll
;             for (int ai = 0; ai < 2; ++ai)
; #pragma unroll
;                 for (int m = 0; m < 4; ++m) {
;                     const size_t row = (size_t)(row0 + ai * HALF + m * 16);
; #pragma unroll
;                     for (int bj = 0; bj < 2; ++bj) {
;                         const int col = col0 + bj * HALF;
;                         f32x4 v0 = acc[ai][bj][m][0], v1 = acc[ai][bj][m][1];
;                         bf16_t* dst = O + row * ldc + col;
;                         if constexpr (MODE == 2) {
; #pragma unroll
;                             for (int e = 0; e < 4; ++e) { v0[e] = sigm(v0[e]); v1[e] = sigm(v1[e]); }
;                         }
;                         if constexpr (MODE == 4) {
;                             const f32x4 b0 = *(const f32x4*)(bias + u.tag * 256 + col), b1 = *(const f32x4*)(bias + u.tag * 256 + col + 4);
; #pragma unroll
;                             for (int e = 0; e < 4; ++e) { v0[e] = gelu_tanh(v0[e] + b0[e]); v1[e] = gelu_tanh(v1[e] + b1[e]); }
;                         }
;                         if constexpr (MODE == 3) {
;                             const u32x4 gv = *(const u32x4*)(G + row * GP + u.tag * 1024 + col);
;                             v0[0] *= bf_lo(gv.x); v0[1] *= bf_hi(gv.x); v0[2] *= bf_lo(gv.y); v0[3] *= bf_hi(gv.y);
;                             v1[0] *= bf_lo(gv.z); v1[1] *= bf_hi(gv.z); v1[2] *= bf_lo(gv.w); v1[3] *= bf_hi(gv.w);
;                             if (u.tag > 0) {
;                                 const u32x4 ov = *(const u32x4*)dst;
;                                 v0[0] += bf_lo(ov.x); v0[1] += bf_hi(ov.x); v0[2] += bf_lo(ov.y); v0[3] += bf_hi(ov.y);
;                                 v1[0] += bf_lo(ov.z); v1[1] += bf_hi(ov.z); v1[2] += bf_lo(ov.w); v1[3] += bf_hi(ov.w);
;                             }
;                         }
;                         *(u32x4*)dst = pack8(v0, v1);
;                     }
; template <class EpiT, class Sched>
; __device__ __forceinline__ void gemm_phase(LAS unsigned char* lds, int tid_in, const GemmDesc g, const Sched& S, const EpiT& E) {
;     ...
;         if (wr == 0) PG8_BAR;
;         E(acc, cur, wr, wc, fr, fq);
.LBB0_414:
	s_andn2_b64 vcc, exec, s[0:1]
	s_cbranch_vccnz .Lepi_last_4
	v_lshl_add_u32 v150, s22, 8, v140
	v_lshl_or_b32 v144, s80, 8, v142
	v_mov_b64_e32 v[146:147], s[18:19]
	v_ashrrev_i32_e32 v145, 31, v144
	v_cvt_pk_bf16_f32 v70, v70, v71
	v_cvt_pk_bf16_f32 v71, v72, v73
	v_cvt_pk_bf16_f32 v72, v66, v67
	v_add_u32_e32 v66, 0x80, v150
	v_mad_i64_i32 v[148:149], s[2:3], v150, s67, v[146:147]
	v_lshlrev_b64 v[144:145], 1, v[144:145]
	v_cvt_pk_bf16_f32 v110, v110, v111
	v_cvt_pk_bf16_f32 v111, v112, v113
	v_cvt_pk_bf16_f32 v112, v106, v107
	v_or_b32_e32 v106, 16, v150
	v_mad_i64_i32 v[66:67], s[2:3], v66, s67, v[146:147]
	v_cvt_pk_bf16_f32 v46, v46, v47
	v_cvt_pk_bf16_f32 v47, v48, v49
	v_cvt_pk_bf16_f32 v48, v42, v43
	v_add_u32_e32 v42, 0x90, v150
	v_lshl_add_u64 v[148:149], v[148:149], 0, v[144:145]
	v_cvt_pk_bf16_f32 v113, v108, v109
	v_mad_i64_i32 v[106:107], s[2:3], v106, s67, v[146:147]
	v_cvt_pk_bf16_f32 v94, v94, v95
	v_cvt_pk_bf16_f32 v95, v96, v97
	v_cvt_pk_bf16_f32 v96, v90, v91
	v_or_b32_e32 v90, 32, v150
	v_lshl_add_u64 v[66:67], v[66:67], 0, v[144:145]
	v_cvt_pk_bf16_f32 v49, v44, v45
	v_mad_i64_i32 v[42:43], s[2:3], v42, s67, v[146:147]
	v_cvt_pk_bf16_f32 v30, v30, v31
	v_cvt_pk_bf16_f32 v31, v32, v33
	v_cvt_pk_bf16_f32 v32, v26, v27
	v_add_u32_e32 v26, 0xa0, v150
	global_store_dwordx4 v[148:149], v[110:113], off offset:256
	v_cvt_pk_bf16_f32 v97, v92, v93
	v_mad_i64_i32 v[90:91], s[2:3], v90, s67, v[146:147]
	v_lshl_add_u64 v[110:111], v[106:107], 0, v[144:145]
	v_cvt_pk_bf16_f32 v78, v78, v79
	v_cvt_pk_bf16_f32 v79, v80, v81
	v_cvt_pk_bf16_f32 v80, v74, v75
	v_or_b32_e32 v74, 48, v150
	global_store_dwordx4 v[66:67], v[46:49], off offset:256
	v_cvt_pk_bf16_f32 v33, v28, v29
	v_mad_i64_i32 v[26:27], s[2:3], v26, s67, v[146:147]
	v_lshl_add_u64 v[46:47], v[42:43], 0, v[144:145]
	v_cvt_pk_bf16_f32 v14, v14, v15
	v_cvt_pk_bf16_f32 v15, v16, v17
	v_cvt_pk_bf16_f32 v16, v10, v11
	v_add_u32_e32 v10, 0xb0, v150
	global_store_dwordx4 v[110:111], v[94:97], off offset:256
	v_cvt_pk_bf16_f32 v81, v76, v77
	v_mad_i64_i32 v[74:75], s[2:3], v74, s67, v[146:147]
	v_lshl_add_u64 v[94:95], v[90:91], 0, v[144:145]
	global_store_dwordx4 v[46:47], v[30:33], off offset:256
	v_cvt_pk_bf16_f32 v17, v12, v13
	v_mad_i64_i32 v[10:11], s[2:3], v10, s67, v[146:147]
	v_lshl_add_u64 v[30:31], v[26:27], 0, v[144:145]
	v_cvt_pk_bf16_f32 v126, v126, v127
	v_cvt_pk_bf16_f32 v127, v128, v129
	v_cvt_pk_bf16_f32 v128, v122, v123
	v_cvt_pk_bf16_f32 v129, v124, v125
	v_cvt_pk_bf16_f32 v106, v118, v119
	v_cvt_pk_bf16_f32 v107, v120, v121
	v_cvt_pk_bf16_f32 v108, v114, v115
	v_cvt_pk_bf16_f32 v109, v116, v117
	v_cvt_pk_bf16_f32 v90, v102, v103
	v_cvt_pk_bf16_f32 v91, v104, v105
	v_cvt_pk_bf16_f32 v92, v98, v99
	v_cvt_pk_bf16_f32 v93, v100, v101
	global_store_dwordx4 v[94:95], v[78:81], off offset:256
	v_cvt_pk_bf16_f32 v76, v82, v83
	v_cvt_pk_bf16_f32 v77, v84, v85
	v_lshl_add_u64 v[78:79], v[74:75], 0, v[144:145]
	v_cvt_pk_bf16_f32 v74, v86, v87
	v_cvt_pk_bf16_f32 v75, v88, v89
	v_cvt_pk_bf16_f32 v73, v68, v69
	v_cvt_pk_bf16_f32 v62, v62, v63
	v_cvt_pk_bf16_f32 v63, v64, v65
	v_cvt_pk_bf16_f32 v64, v58, v59
	v_cvt_pk_bf16_f32 v65, v60, v61
	v_cvt_pk_bf16_f32 v42, v54, v55
	v_cvt_pk_bf16_f32 v43, v56, v57
	v_cvt_pk_bf16_f32 v44, v50, v51
	v_cvt_pk_bf16_f32 v45, v52, v53
	v_cvt_pk_bf16_f32 v26, v38, v39
	v_cvt_pk_bf16_f32 v27, v40, v41
	v_cvt_pk_bf16_f32 v28, v34, v35
	v_cvt_pk_bf16_f32 v29, v36, v37
	global_store_dwordx4 v[30:31], v[14:17], off offset:256
	v_cvt_pk_bf16_f32 v12, v18, v19
	v_cvt_pk_bf16_f32 v13, v20, v21
	v_lshl_add_u64 v[14:15], v[10:11], 0, v[144:145]
	v_cvt_pk_bf16_f32 v10, v22, v23
	v_cvt_pk_bf16_f32 v11, v24, v25
	v_cvt_pk_bf16_f32 v6, v6, v7
	v_cvt_pk_bf16_f32 v7, v8, v9
	v_cvt_pk_bf16_f32 v8, v2, v3
	v_cvt_pk_bf16_f32 v9, v4, v5
	s_andn2_b64 vcc, exec, s[0:1]
	s_mov_b64 s[0:1], -1
	global_store_dwordx4 v[148:149], v[126:129], off
	global_store_dwordx4 v[110:111], v[106:109], off
	global_store_dwordx4 v[94:95], v[90:93], off
	global_store_dwordx4 v[78:79], v[74:77], off
	global_store_dwordx4 v[78:79], v[70:73], off offset:256
	global_store_dwordx4 v[66:67], v[62:65], off
	global_store_dwordx4 v[46:47], v[42:45], off
	global_store_dwordx4 v[30:31], v[26:29], off
	global_store_dwordx4 v[14:15], v[10:13], off
	global_store_dwordx4 v[14:15], v[6:9], off offset:256
	s_cbranch_vccnz .LBB0_407
	s_andn2_b64 vcc, exec, s[12:13]
	s_cbranch_vccnz .LBB0_406
	s_barrier
	s_branch .LBB0_406
; __device__ __forceinline__ float bf_lo(unsigned u) { return __uint_as_float(u << 16); }
; __device__ __forceinline__ float bf_hi(unsigned u) { return __uint_as_float(u & 0xffff0000u); }
;     __device__ __forceinline__ void operator()(const f32x4 (&acc)[2][2][4][2], const Unit& u, int wr, int wc, int fr, int fq) const {
;     ...
;             const int col0 = u.pn * BM + wc * 32 + 8 * fq;
; #pragma unroll
;             for (int ai = 0; ai < 2; ++ai)
; #pragma unroll
;                 for (int m = 0; m < 4; ++m) {
;                     const size_t row = (size_t)(row0 + ai * HALF + m * 16);
; #pragma unroll
;                     for (int bj = 0; bj < 2; ++bj) {
;                         const int col = col0 + bj * HALF;
;                         f32x4 v0 = acc[ai][bj][m][0], v1 = acc[ai][bj][m][1];
;                         bf16_t* dst = O + row * ldc + col;
;                         if constexpr (MODE == 2) {
; #pragma unroll
;                             for (int e = 0; e < 4; ++e) { v0[e] = sigm(v0[e]); v1[e] = sigm(v1[e]); }
;                         }
;                         if constexpr (MODE == 4) {
;                             const f32x4 b0 = *(const f32x4*)(bias + u.tag * 256 + col), b1 = *(const f32x4*)(bias + u.tag * 256 + col + 4);
; #pragma unroll
;                             for (int e = 0; e < 4; ++e) { v0[e] = gelu_tanh(v0[e] + b0[e]); v1[e] = gelu_tanh(v1[e] + b1[e]); }
;                         }
;                         if constexpr (MODE == 3) {
;                             const u32x4 gv = *(const u32x4*)(G + row * GP + u.tag * 1024 + col);
;                             v0[0] *= bf_lo(gv.x); v0[1] *= bf_hi(gv.x); v0[2] *= bf_lo(gv.y); v0[3] *= bf_hi(gv.y);
;                             v1[0] *= bf_lo(gv.z); v1[1] *= bf_hi(gv.z); v1[2] *= bf_lo(gv.w); v1[3] *= bf_hi(gv.w);
;                             if (u.tag > 0) {
;                                 const u32x4 ov = *(const u32x4*)dst;
;                                 v0[0] += bf_lo(ov.x); v0[1] += bf_hi(ov.x); v0[2] += bf_lo(ov.y); v0[3] += bf_hi(ov.y);
;                                 v1[0] += bf_lo(ov.z); v1[1] += bf_hi(ov.z); v1[2] += bf_lo(ov.w); v1[3] += bf_hi(ov.w);
;                             }
;                         }
;                         *(u32x4*)dst = pack8(v0, v1);
;                     }
.Lepi_last_4:
	v_lshl_add_u32 v150, s22, 8, v140
	v_lshl_or_b32 v144, s80, 8, v142
	v_mov_b64_e32 v[146:147], s[18:19]
	v_ashrrev_i32_e32 v145, 31, v144
	v_cvt_pk_bf16_f32 v70, v70, v71
	v_cvt_pk_bf16_f32 v71, v72, v73
	v_cvt_pk_bf16_f32 v72, v66, v67
	v_add_u32_e32 v66, 0x80, v150
	v_mad_i64_i32 v[148:149], s[2:3], v150, s67, v[146:147]
	v_lshlrev_b64 v[144:145], 1, v[144:145]
	v_cvt_pk_bf16_f32 v110, v110, v111
	v_cvt_pk_bf16_f32 v111, v112, v113
	v_cvt_pk_bf16_f32 v112, v106, v107
	v_or_b32_e32 v106, 16, v150
	v_mad_i64_i32 v[66:67], s[2:3], v66, s67, v[146:147]
	v_cvt_pk_bf16_f32 v46, v46, v47
	v_cvt_pk_bf16_f32 v47, v48, v49
	v_cvt_pk_bf16_f32 v48, v42, v43
	v_add_u32_e32 v42, 0x90, v150
	v_lshl_add_u64 v[148:149], v[148:149], 0, v[144:145]
	v_cvt_pk_bf16_f32 v113, v108, v109
	v_mad_i64_i32 v[106:107], s[2:3], v106, s67, v[146:147]
	v_cvt_pk_bf16_f32 v94, v94, v95
	v_cvt_pk_bf16_f32 v95, v96, v97
	v_cvt_pk_bf16_f32 v96, v90, v91
	v_or_b32_e32 v90, 32, v150
	v_lshl_add_u64 v[66:67], v[66:67], 0, v[144:145]
	v_cvt_pk_bf16_f32 v49, v44, v45
	v_mad_i64_i32 v[42:43], s[2:3], v42, s67, v[146:147]
	v_cvt_pk_bf16_f32 v30, v30, v31
	v_cvt_pk_bf16_f32 v31, v32, v33
	v_cvt_pk_bf16_f32 v32, v26, v27
	v_add_u32_e32 v26, 0xa0, v150
	global_store_dwordx4 v[148:149], v[110:113], off offset:256 sc1
	v_cvt_pk_bf16_f32 v97, v92, v93
	v_mad_i64_i32 v[90:91], s[2:3], v90, s67, v[146:147]
	v_lshl_add_u64 v[110:111], v[106:107], 0, v[144:145]
	v_cvt_pk_bf16_f32 v78, v78, v79
	v_cvt_pk_bf16_f32 v79, v80, v81
	v_cvt_pk_bf16_f32 v80, v74, v75
	v_or_b32_e32 v74, 48, v150
	global_store_dwordx4 v[66:67], v[46:49], off offset:256 sc1
	v_cvt_pk_bf16_f32 v33, v28, v29
	v_mad_i64_i32 v[26:27], s[2:3], v26, s67, v[146:147]
	v_lshl_add_u64 v[46:47], v[42:43], 0, v[144:145]
	v_cvt_pk_bf16_f32 v14, v14, v15
	v_cvt_pk_bf16_f32 v15, v16, v17
	v_cvt_pk_bf16_f32 v16, v10, v11
	v_add_u32_e32 v10, 0xb0, v150
	global_store_dwordx4 v[110:111], v[94:97], off offset:256 sc1
	v_cvt_pk_bf16_f32 v81, v76, v77
	v_mad_i64_i32 v[74:75], s[2:3], v74, s67, v[146:147]
	v_lshl_add_u64 v[94:95], v[90:91], 0, v[144:145]
	global_store_dwordx4 v[46:47], v[30:33], off offset:256 sc1
	v_cvt_pk_bf16_f32 v17, v12, v13
	v_mad_i64_i32 v[10:11], s[2:3], v10, s67, v[146:147]
	v_lshl_add_u64 v[30:31], v[26:27], 0, v[144:145]
	v_cvt_pk_bf16_f32 v126, v126, v127
	v_cvt_pk_bf16_f32 v127, v128, v129
	v_cvt_pk_bf16_f32 v128, v122, v123
	v_cvt_pk_bf16_f32 v129, v124, v125
	v_cvt_pk_bf16_f32 v106, v118, v119
	v_cvt_pk_bf16_f32 v107, v120, v121
	v_cvt_pk_bf16_f32 v108, v114, v115
	v_cvt_pk_bf16_f32 v109, v116, v117
	v_cvt_pk_bf16_f32 v90, v102, v103
	v_cvt_pk_bf16_f32 v91, v104, v105
	v_cvt_pk_bf16_f32 v92, v98, v99
	v_cvt_pk_bf16_f32 v93, v100, v101
	global_store_dwordx4 v[94:95], v[78:81], off offset:256 sc1
	v_cvt_pk_bf16_f32 v76, v82, v83
	v_cvt_pk_bf16_f32 v77, v84, v85
	v_lshl_add_u64 v[78:79], v[74:75], 0, v[144:145]
	v_cvt_pk_bf16_f32 v74, v86, v87
	v_cvt_pk_bf16_f32 v75, v88, v89
	v_cvt_pk_bf16_f32 v73, v68, v69
	v_cvt_pk_bf16_f32 v62, v62, v63
	v_cvt_pk_bf16_f32 v63, v64, v65
	v_cvt_pk_bf16_f32 v64, v58, v59
	v_cvt_pk_bf16_f32 v65, v60, v61
	v_cvt_pk_bf16_f32 v42, v54, v55
	v_cvt_pk_bf16_f32 v43, v56, v57
	v_cvt_pk_bf16_f32 v44, v50, v51
	v_cvt_pk_bf16_f32 v45, v52, v53
	v_cvt_pk_bf16_f32 v26, v38, v39
	v_cvt_pk_bf16_f32 v27, v40, v41
	v_cvt_pk_bf16_f32 v28, v34, v35
	v_cvt_pk_bf16_f32 v29, v36, v37
	global_store_dwordx4 v[30:31], v[14:17], off offset:256 sc1
	v_cvt_pk_bf16_f32 v12, v18, v19
	v_cvt_pk_bf16_f32 v13, v20, v21
	v_lshl_add_u64 v[14:15], v[10:11], 0, v[144:145]
	v_cvt_pk_bf16_f32 v10, v22, v23
	v_cvt_pk_bf16_f32 v11, v24, v25
	v_cvt_pk_bf16_f32 v6, v6, v7
	v_cvt_pk_bf16_f32 v7, v8, v9
	v_cvt_pk_bf16_f32 v8, v2, v3
	v_cvt_pk_bf16_f32 v9, v4, v5
	s_andn2_b64 vcc, exec, s[0:1]
	s_mov_b64 s[0:1], -1
	global_store_dwordx4 v[148:149], v[126:129], off sc1
	global_store_dwordx4 v[110:111], v[106:109], off sc1
	global_store_dwordx4 v[94:95], v[90:93], off sc1
	global_store_dwordx4 v[78:79], v[74:77], off sc1
	global_store_dwordx4 v[78:79], v[70:73], off offset:256 sc1
	global_store_dwordx4 v[66:67], v[62:65], off sc1
	global_store_dwordx4 v[46:47], v[42:45], off sc1
	global_store_dwordx4 v[30:31], v[26:29], off sc1
	global_store_dwordx4 v[14:15], v[10:13], off sc1
	global_store_dwordx4 v[14:15], v[6:9], off offset:256 sc1
	s_branch .LBB0_407

;     __device__ __forceinline__ void operator()(const f32x4 (&acc)[2][2][4][2], const Unit& u, int wr, int wc, int fr, int fq) const {
;     ...
;             const int col0 = u.pn * BM + wc * 32 + 8 * fq;
; #pragma unroll
;             for (int ai = 0; ai < 2; ++ai)
; #pragma unroll
;                 for (int m = 0; m < 4; ++m) {
;                     const size_t row = (size_t)(row0 + ai * HALF + m * 16);
; #pragma unroll
;                     for (int bj = 0; bj < 2; ++bj) {
;                         const int col = col0 + bj * HALF;
;                         f32x4 v0 = acc[ai][bj][m][0], v1 = acc[ai][bj][m][1];
;                         bf16_t* dst = O + row * ldc + col;
;                         if constexpr (MODE == 2) {
; #pragma unroll
;                             for (int e = 0; e < 4; ++e) { v0[e] = sigm(v0[e]); v1[e] = sigm(v1[e]); }
;                         }
;                         if constexpr (MODE == 4) {
;                             const f32x4 b0 = *(const f32x4*)(bias + u.tag * 256 + col), b1 = *(const f32x4*)(bias + u.tag * 256 + col + 4);
; #pragma unroll
;                             for (int e = 0; e < 4; ++e) { v0[e] = gelu_tanh(v0[e] + b0[e]); v1[e] = gelu_tanh(v1[e] + b1[e]); }
;                         }
;                         if constexpr (MODE == 3) {
;                             const u32x4 gv = *(const u32x4*)(G + row * GP + u.tag * 1024 + col);
;                             v0[0] *= bf_lo(gv.x); v0[1] *= bf_hi(gv.x); v0[2] *= bf_lo(gv.y); v0[3] *= bf_hi(gv.y);
;                             v1[0] *= bf_lo(gv.z); v1[1] *= bf_hi(gv.z); v1[2] *= bf_lo(gv.w); v1[3] *= bf_hi(gv.w);
;                             if (u.tag > 0) {
;                                 const u32x4 ov = *(const u32x4*)dst;
;                                 v0[0] += bf_lo(ov.x); v0[1] += bf_hi(ov.x); v0[2] += bf_lo(ov.y); v0[3] += bf_hi(ov.y);
;                                 v1[0] += bf_lo(ov.z); v1[1] += bf_hi(ov.z); v1[2] += bf_lo(ov.w); v1[3] += bf_hi(ov.w);
;                             }
;                         }
;                         *(u32x4*)dst = pack8(v0, v1);
;                     }
; template <class EpiT, class Sched>
; __device__ __forceinline__ void gemm_phase(LAS unsigned char* lds, int tid_in, const GemmDesc g, const Sched& S, const EpiT& E) {
;     ...
;         if (wr == 0) PG8_BAR;
;         E(acc, cur, wr, wc, fr, fq);
.LBB0_950:
	s_andn2_b64 vcc, exec, s[0:1]
	s_cbranch_vccnz .Lepi_last_8
	v_mul_f32_e32 v126, 0xbfb8aa3b, v126
	v_exp_f32_e32 v126, v126
	v_mul_f32_e32 v122, 0xbfb8aa3b, v122
	v_exp_f32_e32 v122, v122
	v_mul_f32_e32 v123, 0xbfb8aa3b, v123
	v_add_f32_e32 v126, 1.0, v126
	v_rcp_f32_e32 v145, v126
	v_mul_f32_e32 v126, 0xbfb8aa3b, v127
	v_exp_f32_e32 v126, v126
	v_exp_f32_e32 v123, v123
	v_add_f32_e32 v122, 1.0, v122
	v_rcp_f32_e32 v148, v122
	v_add_f32_e32 v122, 1.0, v126
	v_rcp_f32_e32 v149, v122
	v_add_f32_e32 v122, 1.0, v123
	v_mul_f32_e32 v123, 0xbfb8aa3b, v128
	v_exp_f32_e32 v123, v123
	v_mul_f32_e32 v124, 0xbfb8aa3b, v124
	v_exp_f32_e32 v124, v124
	v_rcp_f32_e32 v128, v122
	v_add_f32_e32 v122, 1.0, v123
	v_mul_f32_e32 v123, 0xbfb8aa3b, v129
	v_rcp_f32_e32 v150, v122
	v_add_f32_e32 v122, 1.0, v124
	v_exp_f32_e32 v123, v123
	v_mul_f32_e32 v124, 0xbfb8aa3b, v125
	v_exp_f32_e32 v124, v124
	v_rcp_f32_e32 v129, v122
	v_add_f32_e32 v122, 1.0, v123
	v_rcp_f32_e32 v151, v122
	v_add_f32_e32 v122, 1.0, v124
	v_mul_f32_e32 v114, 0xbfb8aa3b, v114
	v_rcp_f32_e32 v152, v122
	v_exp_f32_e32 v114, v114
	v_mul_f32_e32 v119, 0xbfb8aa3b, v119
	v_lshl_or_b32 v146, s58, 8, v142
	v_exp_f32_e32 v119, v119
	v_lshl_add_u32 v144, s30, 8, v140
	v_ashrrev_i32_e32 v147, 31, v146
	v_mov_b64_e32 v[122:123], s[18:19]
	v_mad_i64_i32 v[126:127], s[2:3], v144, s57, v[122:123]
	v_lshlrev_b64 v[124:125], 1, v[146:147]
	v_lshl_add_u64 v[146:147], v[126:127], 0, v[124:125]
	v_cvt_pk_bf16_f32 v126, v145, v149
	v_cvt_pk_bf16_f32 v127, v150, v151
	v_cvt_pk_bf16_f32 v128, v148, v128
	v_cvt_pk_bf16_f32 v129, v129, v152
	v_add_f32_e32 v114, 1.0, v114
	v_mul_f32_e32 v115, 0xbfb8aa3b, v115
	global_store_dwordx4 v[146:147], v[126:129], off
	v_exp_f32_e32 v115, v115
	v_mul_f32_e32 v116, 0xbfb8aa3b, v116
	v_rcp_f32_e32 v126, v114
	v_add_f32_e32 v114, 1.0, v119
	v_mul_f32_e32 v119, 0xbfb8aa3b, v120
	v_exp_f32_e32 v119, v119
	v_add_f32_e32 v115, 1.0, v115
	v_mul_f32_e32 v118, 0xbfb8aa3b, v118
	v_exp_f32_e32 v116, v116
	v_rcp_f32_e32 v120, v115
	v_add_f32_e32 v115, 1.0, v119
	v_mul_f32_e32 v119, 0xbfb8aa3b, v121
	v_mul_f32_e32 v117, 0xbfb8aa3b, v117
	v_exp_f32_e32 v118, v118
	v_exp_f32_e32 v119, v119
	v_exp_f32_e32 v117, v117
	v_add_f32_e32 v116, 1.0, v116
	v_add_f32_e32 v118, 1.0, v118
	v_rcp_f32_e32 v121, v116
	v_add_f32_e32 v116, 1.0, v119
	v_add_f32_e32 v117, 1.0, v117
	v_mul_f32_e32 v110, 0xbfb8aa3b, v110
	v_rcp_f32_e32 v118, v118
	v_rcp_f32_e32 v114, v114
	v_rcp_f32_e32 v115, v115
	v_rcp_f32_e32 v116, v116
	v_rcp_f32_e32 v117, v117
	v_exp_f32_e32 v110, v110
	v_cvt_pk_bf16_f32 v114, v118, v114
	v_cvt_pk_bf16_f32 v115, v115, v116
	v_cvt_pk_bf16_f32 v116, v126, v120
	v_cvt_pk_bf16_f32 v117, v121, v117
	v_mul_f32_e32 v106, 0xbfb8aa3b, v106
	v_add_f32_e32 v110, 1.0, v110
	global_store_dwordx4 v[146:147], v[114:117], off offset:256
	v_exp_f32_e32 v106, v106
	v_mul_f32_e32 v107, 0xbfb8aa3b, v107
	v_rcp_f32_e32 v115, v110
	v_mul_f32_e32 v110, 0xbfb8aa3b, v111
	v_exp_f32_e32 v110, v110
	v_exp_f32_e32 v107, v107
	v_add_f32_e32 v106, 1.0, v106
	v_rcp_f32_e32 v116, v106
	v_add_f32_e32 v106, 1.0, v110
	v_rcp_f32_e32 v117, v106
	v_add_f32_e32 v106, 1.0, v107
	v_mul_f32_e32 v107, 0xbfb8aa3b, v112
	v_exp_f32_e32 v107, v107
	v_mul_f32_e32 v108, 0xbfb8aa3b, v108
	v_exp_f32_e32 v108, v108
	v_rcp_f32_e32 v112, v106
	v_add_f32_e32 v106, 1.0, v107
	v_mul_f32_e32 v107, 0xbfb8aa3b, v113
	v_rcp_f32_e32 v118, v106
	v_add_f32_e32 v106, 1.0, v108
	v_exp_f32_e32 v107, v107
	v_mul_f32_e32 v108, 0xbfb8aa3b, v109
	v_exp_f32_e32 v108, v108
	v_rcp_f32_e32 v109, v106
	v_add_f32_e32 v106, 1.0, v107
	v_rcp_f32_e32 v113, v106
	v_add_f32_e32 v106, 1.0, v108
	v_mul_f32_e32 v98, 0xbfb8aa3b, v98
	v_rcp_f32_e32 v119, v106
	v_exp_f32_e32 v98, v98
	v_mul_f32_e32 v103, 0xbfb8aa3b, v103
	v_exp_f32_e32 v103, v103
	v_or_b32_e32 v114, 16, v144
	v_mad_i64_i32 v[106:107], s[2:3], v114, s57, v[122:123]
	v_lshl_add_u64 v[110:111], v[106:107], 0, v[124:125]
	v_cvt_pk_bf16_f32 v106, v115, v117
	v_cvt_pk_bf16_f32 v107, v118, v113
	v_cvt_pk_bf16_f32 v108, v116, v112
	v_cvt_pk_bf16_f32 v109, v109, v119
	v_add_f32_e32 v98, 1.0, v98
	v_mul_f32_e32 v99, 0xbfb8aa3b, v99
	global_store_dwordx4 v[110:111], v[106:109], off
	v_exp_f32_e32 v99, v99
	v_mul_f32_e32 v100, 0xbfb8aa3b, v100
	v_rcp_f32_e32 v106, v98
	v_add_f32_e32 v98, 1.0, v103
	v_mul_f32_e32 v103, 0xbfb8aa3b, v104
	v_exp_f32_e32 v103, v103
	v_add_f32_e32 v99, 1.0, v99
	v_mul_f32_e32 v102, 0xbfb8aa3b, v102
	v_exp_f32_e32 v100, v100
	v_rcp_f32_e32 v104, v99
	v_add_f32_e32 v99, 1.0, v103
	v_mul_f32_e32 v103, 0xbfb8aa3b, v105
	v_mul_f32_e32 v101, 0xbfb8aa3b, v101
	v_exp_f32_e32 v102, v102
	v_exp_f32_e32 v103, v103
	v_exp_f32_e32 v101, v101
	v_add_f32_e32 v100, 1.0, v100
	v_add_f32_e32 v102, 1.0, v102
	v_rcp_f32_e32 v105, v100
	v_add_f32_e32 v100, 1.0, v103
	v_add_f32_e32 v101, 1.0, v101
	v_mul_f32_e32 v94, 0xbfb8aa3b, v94
	v_rcp_f32_e32 v102, v102
	v_rcp_f32_e32 v98, v98
	v_rcp_f32_e32 v99, v99
	v_rcp_f32_e32 v100, v100
	v_rcp_f32_e32 v101, v101
	v_exp_f32_e32 v94, v94
	v_cvt_pk_bf16_f32 v98, v102, v98
	v_cvt_pk_bf16_f32 v99, v99, v100
	v_cvt_pk_bf16_f32 v100, v106, v104
	v_cvt_pk_bf16_f32 v101, v105, v101
	v_mul_f32_e32 v90, 0xbfb8aa3b, v90
	v_add_f32_e32 v94, 1.0, v94
	global_store_dwordx4 v[110:111], v[98:101], off offset:256
	v_exp_f32_e32 v90, v90
	v_mul_f32_e32 v91, 0xbfb8aa3b, v91
	v_rcp_f32_e32 v99, v94
	v_mul_f32_e32 v94, 0xbfb8aa3b, v95
	v_exp_f32_e32 v94, v94
	v_exp_f32_e32 v91, v91
	v_add_f32_e32 v90, 1.0, v90
	v_rcp_f32_e32 v100, v90
	v_add_f32_e32 v90, 1.0, v94
	v_rcp_f32_e32 v101, v90
	v_add_f32_e32 v90, 1.0, v91
	v_mul_f32_e32 v91, 0xbfb8aa3b, v96
	v_exp_f32_e32 v91, v91
; __device__ __forceinline__ float bf_lo(unsigned u) { return __uint_as_float(u << 16); }
; __device__ __forceinline__ float bf_hi(unsigned u) { return __uint_as_float(u & 0xffff0000u); }
;     __device__ __forceinline__ void operator()(const f32x4 (&acc)[2][2][4][2], const Unit& u, int wr, int wc, int fr, int fq) const {
;     ...
;             const int col0 = u.pn * BM + wc * 32 + 8 * fq;
; #pragma unroll
;             for (int ai = 0; ai < 2; ++ai)
; #pragma unroll
;                 for (int m = 0; m < 4; ++m) {
;                     const size_t row = (size_t)(row0 + ai * HALF + m * 16);
; #pragma unroll
;                     for (int bj = 0; bj < 2; ++bj) {
;                         const int col = col0 + bj * HALF;
;                         f32x4 v0 = acc[ai][bj][m][0], v1 = acc[ai][bj][m][1];
;                         bf16_t* dst = O + row * ldc + col;
;                         if constexpr (MODE == 2) {
; #pragma unroll
;                             for (int e = 0; e < 4; ++e) { v0[e] = sigm(v0[e]); v1[e] = sigm(v1[e]); }
;                         }
;                         if constexpr (MODE == 4) {
;                             const f32x4 b0 = *(const f32x4*)(bias + u.tag * 256 + col), b1 = *(const f32x4*)(bias + u.tag * 256 + col + 4);
; #pragma unroll
;                             for (int e = 0; e < 4; ++e) { v0[e] = gelu_tanh(v0[e] + b0[e]); v1[e] = gelu_tanh(v1[e] + b1[e]); }
;                         }
;                         if constexpr (MODE == 3) {
;                             const u32x4 gv = *(const u32x4*)(G + row * GP + u.tag * 1024 + col);
;                             v0[0] *= bf_lo(gv.x); v0[1] *= bf_hi(gv.x); v0[2] *= bf_lo(gv.y); v0[3] *= bf_hi(gv.y);
;                             v1[0] *= bf_lo(gv.z); v1[1] *= bf_hi(gv.z); v1[2] *= bf_lo(gv.w); v1[3] *= bf_hi(gv.w);
;                             if (u.tag > 0) {
;                                 const u32x4 ov = *(const u32x4*)dst;
;                                 v0[0] += bf_lo(ov.x); v0[1] += bf_hi(ov.x); v0[2] += bf_lo(ov.y); v0[3] += bf_hi(ov.y);
;                                 v1[0] += bf_lo(ov.z); v1[1] += bf_hi(ov.z); v1[2] += bf_lo(ov.w); v1[3] += bf_hi(ov.w);
;                             }
;                         }
;                         *(u32x4*)dst = pack8(v0, v1);
;                     }
	v_mul_f32_e32 v92, 0xbfb8aa3b, v92
	v_exp_f32_e32 v92, v92
	v_rcp_f32_e32 v96, v90
	v_add_f32_e32 v90, 1.0, v91
	v_mul_f32_e32 v91, 0xbfb8aa3b, v97
	v_rcp_f32_e32 v102, v90
	v_add_f32_e32 v90, 1.0, v92
	v_exp_f32_e32 v91, v91
	v_mul_f32_e32 v92, 0xbfb8aa3b, v93
	v_exp_f32_e32 v92, v92
	v_rcp_f32_e32 v93, v90
	v_add_f32_e32 v90, 1.0, v91
	v_rcp_f32_e32 v97, v90
	v_add_f32_e32 v90, 1.0, v92
	v_mul_f32_e32 v82, 0xbfb8aa3b, v82
	v_rcp_f32_e32 v103, v90
	v_exp_f32_e32 v82, v82
	v_mul_f32_e32 v87, 0xbfb8aa3b, v87
	v_exp_f32_e32 v87, v87
	v_or_b32_e32 v98, 32, v144
	v_mad_i64_i32 v[90:91], s[2:3], v98, s57, v[122:123]
	v_lshl_add_u64 v[94:95], v[90:91], 0, v[124:125]
	v_cvt_pk_bf16_f32 v90, v99, v101
	v_cvt_pk_bf16_f32 v91, v102, v97
	v_cvt_pk_bf16_f32 v92, v100, v96
	v_cvt_pk_bf16_f32 v93, v93, v103
	v_add_f32_e32 v82, 1.0, v82
	v_mul_f32_e32 v83, 0xbfb8aa3b, v83
	global_store_dwordx4 v[94:95], v[90:93], off
	v_exp_f32_e32 v83, v83
	v_mul_f32_e32 v84, 0xbfb8aa3b, v84
	v_rcp_f32_e32 v90, v82
	v_add_f32_e32 v82, 1.0, v87
	v_mul_f32_e32 v87, 0xbfb8aa3b, v88
	v_exp_f32_e32 v87, v87
	v_add_f32_e32 v83, 1.0, v83
	v_mul_f32_e32 v86, 0xbfb8aa3b, v86
	v_exp_f32_e32 v84, v84
	v_rcp_f32_e32 v88, v83
	v_add_f32_e32 v83, 1.0, v87
	v_mul_f32_e32 v87, 0xbfb8aa3b, v89
	v_mul_f32_e32 v85, 0xbfb8aa3b, v85
	v_exp_f32_e32 v86, v86
	v_exp_f32_e32 v87, v87
	v_exp_f32_e32 v85, v85
	v_add_f32_e32 v84, 1.0, v84
	v_add_f32_e32 v86, 1.0, v86
	v_rcp_f32_e32 v89, v84
	v_add_f32_e32 v84, 1.0, v87
	v_add_f32_e32 v85, 1.0, v85
	v_mul_f32_e32 v78, 0xbfb8aa3b, v78
	v_rcp_f32_e32 v86, v86
	v_rcp_f32_e32 v82, v82
	v_rcp_f32_e32 v83, v83
	v_rcp_f32_e32 v84, v84
	v_rcp_f32_e32 v85, v85
	v_exp_f32_e32 v78, v78
	v_cvt_pk_bf16_f32 v82, v86, v82
	v_cvt_pk_bf16_f32 v83, v83, v84
	v_cvt_pk_bf16_f32 v84, v90, v88
	v_cvt_pk_bf16_f32 v85, v89, v85
	v_mul_f32_e32 v74, 0xbfb8aa3b, v74
	v_add_f32_e32 v78, 1.0, v78
	global_store_dwordx4 v[94:95], v[82:85], off offset:256
	v_exp_f32_e32 v74, v74
	v_mul_f32_e32 v75, 0xbfb8aa3b, v75
	v_rcp_f32_e32 v83, v78
	v_mul_f32_e32 v78, 0xbfb8aa3b, v79
	v_exp_f32_e32 v78, v78
	v_exp_f32_e32 v75, v75
	v_add_f32_e32 v74, 1.0, v74
	v_rcp_f32_e32 v84, v74
	v_add_f32_e32 v74, 1.0, v78
	v_rcp_f32_e32 v85, v74
	v_add_f32_e32 v74, 1.0, v75
	v_mul_f32_e32 v75, 0xbfb8aa3b, v80
	v_exp_f32_e32 v75, v75
	v_mul_f32_e32 v76, 0xbfb8aa3b, v76
	v_exp_f32_e32 v76, v76
	v_rcp_f32_e32 v80, v74
	v_add_f32_e32 v74, 1.0, v75
	v_mul_f32_e32 v75, 0xbfb8aa3b, v81
	v_rcp_f32_e32 v86, v74
	v_add_f32_e32 v74, 1.0, v76
	v_exp_f32_e32 v75, v75
	v_mul_f32_e32 v76, 0xbfb8aa3b, v77
	v_exp_f32_e32 v76, v76
	v_rcp_f32_e32 v77, v74
	v_add_f32_e32 v74, 1.0, v75
	v_rcp_f32_e32 v81, v74
	v_add_f32_e32 v74, 1.0, v76
	v_mul_f32_e32 v66, 0xbfb8aa3b, v66
	v_rcp_f32_e32 v87, v74
	v_exp_f32_e32 v66, v66
	v_mul_f32_e32 v71, 0xbfb8aa3b, v71
	v_exp_f32_e32 v71, v71
	v_or_b32_e32 v82, 48, v144
	v_mad_i64_i32 v[74:75], s[2:3], v82, s57, v[122:123]
	v_lshl_add_u64 v[78:79], v[74:75], 0, v[124:125]
	v_cvt_pk_bf16_f32 v74, v83, v85
	v_cvt_pk_bf16_f32 v75, v86, v81
	v_cvt_pk_bf16_f32 v76, v84, v80
	v_cvt_pk_bf16_f32 v77, v77, v87
	v_add_f32_e32 v66, 1.0, v66
	v_mul_f32_e32 v67, 0xbfb8aa3b, v67
	global_store_dwordx4 v[78:79], v[74:77], off
	v_exp_f32_e32 v67, v67
	v_mul_f32_e32 v68, 0xbfb8aa3b, v68
	v_rcp_f32_e32 v74, v66
	v_add_f32_e32 v66, 1.0, v71
	v_mul_f32_e32 v71, 0xbfb8aa3b, v72
	v_exp_f32_e32 v71, v71
	v_add_f32_e32 v67, 1.0, v67
	v_mul_f32_e32 v70, 0xbfb8aa3b, v70
	v_exp_f32_e32 v68, v68
	v_rcp_f32_e32 v72, v67
	v_add_f32_e32 v67, 1.0, v71
	v_mul_f32_e32 v71, 0xbfb8aa3b, v73
	v_mul_f32_e32 v69, 0xbfb8aa3b, v69
	v_exp_f32_e32 v70, v70
	v_exp_f32_e32 v71, v71
	v_exp_f32_e32 v69, v69
	v_add_f32_e32 v68, 1.0, v68
	v_add_f32_e32 v70, 1.0, v70
	v_rcp_f32_e32 v73, v68
	v_add_f32_e32 v68, 1.0, v71
	v_add_f32_e32 v69, 1.0, v69
	v_mul_f32_e32 v62, 0xbfb8aa3b, v62
	v_rcp_f32_e32 v70, v70
	v_rcp_f32_e32 v66, v66
	v_rcp_f32_e32 v67, v67
	v_rcp_f32_e32 v68, v68
	v_rcp_f32_e32 v69, v69
	v_exp_f32_e32 v62, v62
	v_cvt_pk_bf16_f32 v66, v70, v66
	v_cvt_pk_bf16_f32 v67, v67, v68
	v_cvt_pk_bf16_f32 v68, v74, v72
	v_cvt_pk_bf16_f32 v69, v73, v69
	v_mul_f32_e32 v58, 0xbfb8aa3b, v58
	v_add_f32_e32 v62, 1.0, v62
	global_store_dwordx4 v[78:79], v[66:69], off offset:256
	v_exp_f32_e32 v58, v58
	v_mul_f32_e32 v59, 0xbfb8aa3b, v59
	v_rcp_f32_e32 v67, v62
	v_mul_f32_e32 v62, 0xbfb8aa3b, v63
	v_exp_f32_e32 v62, v62
	v_exp_f32_e32 v59, v59
	v_add_f32_e32 v58, 1.0, v58
	v_rcp_f32_e32 v68, v58
	v_add_f32_e32 v58, 1.0, v62
	v_rcp_f32_e32 v69, v58
	v_add_f32_e32 v58, 1.0, v59
	v_mul_f32_e32 v59, 0xbfb8aa3b, v64
	v_exp_f32_e32 v59, v59
	v_mul_f32_e32 v60, 0xbfb8aa3b, v60
	v_exp_f32_e32 v60, v60
	v_rcp_f32_e32 v64, v58
	v_add_f32_e32 v58, 1.0, v59
	v_mul_f32_e32 v59, 0xbfb8aa3b, v65
	v_rcp_f32_e32 v70, v58
	v_add_f32_e32 v58, 1.0, v60
	v_exp_f32_e32 v59, v59
	v_mul_f32_e32 v60, 0xbfb8aa3b, v61
	v_exp_f32_e32 v60, v60
	v_rcp_f32_e32 v61, v58
	v_add_f32_e32 v58, 1.0, v59
	v_rcp_f32_e32 v65, v58
	v_add_f32_e32 v58, 1.0, v60
	v_mul_f32_e32 v50, 0xbfb8aa3b, v50
	v_rcp_f32_e32 v71, v58
	v_exp_f32_e32 v50, v50
	v_mul_f32_e32 v55, 0xbfb8aa3b, v55
	v_exp_f32_e32 v55, v55
	v_add_u32_e32 v66, 0x80, v144
	v_mad_i64_i32 v[58:59], s[2:3], v66, s57, v[122:123]
	v_lshl_add_u64 v[62:63], v[58:59], 0, v[124:125]
	v_cvt_pk_bf16_f32 v58, v67, v69
	v_cvt_pk_bf16_f32 v59, v70, v65
	v_cvt_pk_bf16_f32 v60, v68, v64
	v_cvt_pk_bf16_f32 v61, v61, v71
	v_add_f32_e32 v50, 1.0, v50
	v_mul_f32_e32 v51, 0xbfb8aa3b, v51
	global_store_dwordx4 v[62:63], v[58:61], off
	v_exp_f32_e32 v51, v51
	v_mul_f32_e32 v52, 0xbfb8aa3b, v52
	v_rcp_f32_e32 v58, v50
	v_add_f32_e32 v50, 1.0, v55
; __device__ __forceinline__ float bf_lo(unsigned u) { return __uint_as_float(u << 16); }
; __device__ __forceinline__ float bf_hi(unsigned u) { return __uint_as_float(u & 0xffff0000u); }
;     __device__ __forceinline__ void operator()(const f32x4 (&acc)[2][2][4][2], const Unit& u, int wr, int wc, int fr, int fq) const {
;     ...
;             const int col0 = u.pn * BM + wc * 32 + 8 * fq;
; #pragma unroll
;             for (int ai = 0; ai < 2; ++ai)
; #pragma unroll
;                 for (int m = 0; m < 4; ++m) {
;                     const size_t row = (size_t)(row0 + ai * HALF + m * 16);
; #pragma unroll
;                     for (int bj = 0; bj < 2; ++bj) {
;                         const int col = col0 + bj * HALF;
;                         f32x4 v0 = acc[ai][bj][m][0], v1 = acc[ai][bj][m][1];
;                         bf16_t* dst = O + row * ldc + col;
;                         if constexpr (MODE == 2) {
; #pragma unroll
;                             for (int e = 0; e < 4; ++e) { v0[e] = sigm(v0[e]); v1[e] = sigm(v1[e]); }
;                         }
;                         if constexpr (MODE == 4) {
;                             const f32x4 b0 = *(const f32x4*)(bias + u.tag * 256 + col), b1 = *(const f32x4*)(bias + u.tag * 256 + col + 4);
; #pragma unroll
;                             for (int e = 0; e < 4; ++e) { v0[e] = gelu_tanh(v0[e] + b0[e]); v1[e] = gelu_tanh(v1[e] + b1[e]); }
;                         }
;                         if constexpr (MODE == 3) {
;                             const u32x4 gv = *(const u32x4*)(G + row * GP + u.tag * 1024 + col);
;                             v0[0] *= bf_lo(gv.x); v0[1] *= bf_hi(gv.x); v0[2] *= bf_lo(gv.y); v0[3] *= bf_hi(gv.y);
;                             v1[0] *= bf_lo(gv.z); v1[1] *= bf_hi(gv.z); v1[2] *= bf_lo(gv.w); v1[3] *= bf_hi(gv.w);
;                             if (u.tag > 0) {
;                                 const u32x4 ov = *(const u32x4*)dst;
;                                 v0[0] += bf_lo(ov.x); v0[1] += bf_hi(ov.x); v0[2] += bf_lo(ov.y); v0[3] += bf_hi(ov.y);
;                                 v1[0] += bf_lo(ov.z); v1[1] += bf_hi(ov.z); v1[2] += bf_lo(ov.w); v1[3] += bf_hi(ov.w);
;                             }
;                         }
;                         *(u32x4*)dst = pack8(v0, v1);
;                     }
	v_mul_f32_e32 v55, 0xbfb8aa3b, v56
	v_exp_f32_e32 v55, v55
	v_add_f32_e32 v51, 1.0, v51
	v_mul_f32_e32 v54, 0xbfb8aa3b, v54
	v_exp_f32_e32 v52, v52
	v_rcp_f32_e32 v56, v51
	v_add_f32_e32 v51, 1.0, v55
	v_mul_f32_e32 v55, 0xbfb8aa3b, v57
	v_mul_f32_e32 v53, 0xbfb8aa3b, v53
	v_exp_f32_e32 v54, v54
	v_exp_f32_e32 v55, v55
	v_exp_f32_e32 v53, v53
	v_add_f32_e32 v52, 1.0, v52
	v_add_f32_e32 v54, 1.0, v54
	v_rcp_f32_e32 v57, v52
	v_add_f32_e32 v52, 1.0, v55
	v_add_f32_e32 v53, 1.0, v53
	v_mul_f32_e32 v46, 0xbfb8aa3b, v46
	v_rcp_f32_e32 v54, v54
	v_rcp_f32_e32 v50, v50
	v_rcp_f32_e32 v51, v51
	v_rcp_f32_e32 v52, v52
	v_rcp_f32_e32 v53, v53
	v_exp_f32_e32 v46, v46
	v_cvt_pk_bf16_f32 v50, v54, v50
	v_cvt_pk_bf16_f32 v51, v51, v52
	v_cvt_pk_bf16_f32 v52, v58, v56
	v_cvt_pk_bf16_f32 v53, v57, v53
	v_mul_f32_e32 v42, 0xbfb8aa3b, v42
	v_add_f32_e32 v46, 1.0, v46
	global_store_dwordx4 v[62:63], v[50:53], off offset:256
	v_exp_f32_e32 v42, v42
	v_mul_f32_e32 v43, 0xbfb8aa3b, v43
	v_rcp_f32_e32 v51, v46
	v_mul_f32_e32 v46, 0xbfb8aa3b, v47
	v_exp_f32_e32 v46, v46
	v_exp_f32_e32 v43, v43
	v_add_f32_e32 v42, 1.0, v42
	v_rcp_f32_e32 v52, v42
	v_add_f32_e32 v42, 1.0, v46
	v_rcp_f32_e32 v53, v42
	v_add_f32_e32 v42, 1.0, v43
	v_mul_f32_e32 v43, 0xbfb8aa3b, v48
	v_exp_f32_e32 v43, v43
	v_mul_f32_e32 v44, 0xbfb8aa3b, v44
	v_exp_f32_e32 v44, v44
	v_rcp_f32_e32 v48, v42
	v_add_f32_e32 v42, 1.0, v43
	v_mul_f32_e32 v43, 0xbfb8aa3b, v49
	v_rcp_f32_e32 v54, v42
	v_add_f32_e32 v42, 1.0, v44
	v_exp_f32_e32 v43, v43
	v_mul_f32_e32 v44, 0xbfb8aa3b, v45
	v_exp_f32_e32 v44, v44
	v_rcp_f32_e32 v45, v42
	v_add_f32_e32 v42, 1.0, v43
	v_rcp_f32_e32 v49, v42
	v_add_f32_e32 v42, 1.0, v44
	v_mul_f32_e32 v34, 0xbfb8aa3b, v34
	v_rcp_f32_e32 v55, v42
	v_exp_f32_e32 v34, v34
	v_mul_f32_e32 v39, 0xbfb8aa3b, v39
	v_exp_f32_e32 v39, v39
	v_add_u32_e32 v50, 0x90, v144
	v_mad_i64_i32 v[42:43], s[2:3], v50, s57, v[122:123]
	v_lshl_add_u64 v[46:47], v[42:43], 0, v[124:125]
	v_cvt_pk_bf16_f32 v42, v51, v53
	v_cvt_pk_bf16_f32 v43, v54, v49
	v_cvt_pk_bf16_f32 v44, v52, v48
	v_cvt_pk_bf16_f32 v45, v45, v55
	v_add_f32_e32 v34, 1.0, v34
	v_mul_f32_e32 v35, 0xbfb8aa3b, v35
	global_store_dwordx4 v[46:47], v[42:45], off
	v_exp_f32_e32 v35, v35
	v_mul_f32_e32 v36, 0xbfb8aa3b, v36
	v_rcp_f32_e32 v42, v34
	v_add_f32_e32 v34, 1.0, v39
	v_mul_f32_e32 v39, 0xbfb8aa3b, v40
	v_exp_f32_e32 v39, v39
	v_add_f32_e32 v35, 1.0, v35
	v_mul_f32_e32 v38, 0xbfb8aa3b, v38
	v_exp_f32_e32 v36, v36
	v_rcp_f32_e32 v40, v35
	v_add_f32_e32 v35, 1.0, v39
	v_mul_f32_e32 v39, 0xbfb8aa3b, v41
	v_mul_f32_e32 v37, 0xbfb8aa3b, v37
	v_exp_f32_e32 v38, v38
	v_exp_f32_e32 v39, v39
	v_exp_f32_e32 v37, v37
	v_add_f32_e32 v36, 1.0, v36
	v_add_f32_e32 v38, 1.0, v38
	v_rcp_f32_e32 v41, v36
	v_add_f32_e32 v36, 1.0, v39
	v_add_f32_e32 v37, 1.0, v37
	v_mul_f32_e32 v30, 0xbfb8aa3b, v30
	v_rcp_f32_e32 v38, v38
	v_rcp_f32_e32 v34, v34
	v_rcp_f32_e32 v35, v35
	v_rcp_f32_e32 v36, v36
	v_rcp_f32_e32 v37, v37
	v_exp_f32_e32 v30, v30
	v_cvt_pk_bf16_f32 v34, v38, v34
	v_cvt_pk_bf16_f32 v35, v35, v36
	v_cvt_pk_bf16_f32 v36, v42, v40
	v_cvt_pk_bf16_f32 v37, v41, v37
	v_mul_f32_e32 v26, 0xbfb8aa3b, v26
	v_add_f32_e32 v30, 1.0, v30
	global_store_dwordx4 v[46:47], v[34:37], off offset:256
	v_exp_f32_e32 v26, v26
	v_mul_f32_e32 v27, 0xbfb8aa3b, v27
	v_rcp_f32_e32 v35, v30
	v_mul_f32_e32 v30, 0xbfb8aa3b, v31
	v_exp_f32_e32 v30, v30
	v_exp_f32_e32 v27, v27
	v_add_f32_e32 v26, 1.0, v26
	v_rcp_f32_e32 v36, v26
	v_add_f32_e32 v26, 1.0, v30
	v_rcp_f32_e32 v37, v26
	v_add_f32_e32 v26, 1.0, v27
	v_mul_f32_e32 v27, 0xbfb8aa3b, v32
	v_exp_f32_e32 v27, v27
	v_mul_f32_e32 v28, 0xbfb8aa3b, v28
	v_exp_f32_e32 v28, v28
	v_rcp_f32_e32 v32, v26
	v_add_f32_e32 v26, 1.0, v27
	v_mul_f32_e32 v27, 0xbfb8aa3b, v33
	v_rcp_f32_e32 v38, v26
	v_add_f32_e32 v26, 1.0, v28
	v_exp_f32_e32 v27, v27
	v_mul_f32_e32 v28, 0xbfb8aa3b, v29
	v_exp_f32_e32 v28, v28
	v_rcp_f32_e32 v29, v26
	v_add_f32_e32 v26, 1.0, v27
	v_rcp_f32_e32 v33, v26
	v_add_f32_e32 v26, 1.0, v28
	v_mul_f32_e32 v18, 0xbfb8aa3b, v18
	v_rcp_f32_e32 v39, v26
	v_exp_f32_e32 v18, v18
	v_mul_f32_e32 v23, 0xbfb8aa3b, v23
	v_exp_f32_e32 v23, v23
	v_add_u32_e32 v34, 0xa0, v144
	v_mad_i64_i32 v[26:27], s[2:3], v34, s57, v[122:123]
	v_lshl_add_u64 v[30:31], v[26:27], 0, v[124:125]
	v_cvt_pk_bf16_f32 v26, v35, v37
	v_cvt_pk_bf16_f32 v27, v38, v33
	v_cvt_pk_bf16_f32 v28, v36, v32
	v_cvt_pk_bf16_f32 v29, v29, v39
	v_add_f32_e32 v18, 1.0, v18
	v_mul_f32_e32 v19, 0xbfb8aa3b, v19
	global_store_dwordx4 v[30:31], v[26:29], off
	v_exp_f32_e32 v19, v19
	v_mul_f32_e32 v20, 0xbfb8aa3b, v20
	v_rcp_f32_e32 v26, v18
	v_add_f32_e32 v18, 1.0, v23
	v_mul_f32_e32 v23, 0xbfb8aa3b, v24
	v_exp_f32_e32 v23, v23
	v_add_f32_e32 v19, 1.0, v19
	v_mul_f32_e32 v22, 0xbfb8aa3b, v22
	v_exp_f32_e32 v20, v20
	v_rcp_f32_e32 v24, v19
	v_add_f32_e32 v19, 1.0, v23
	v_mul_f32_e32 v23, 0xbfb8aa3b, v25
	v_mul_f32_e32 v21, 0xbfb8aa3b, v21
	v_exp_f32_e32 v22, v22
	v_exp_f32_e32 v23, v23
	v_exp_f32_e32 v21, v21
	v_add_f32_e32 v20, 1.0, v20
	v_add_f32_e32 v22, 1.0, v22
	v_rcp_f32_e32 v25, v20
	v_add_f32_e32 v20, 1.0, v23
	v_add_f32_e32 v21, 1.0, v21
	v_mul_f32_e32 v14, 0xbfb8aa3b, v14
	v_rcp_f32_e32 v22, v22
	v_rcp_f32_e32 v18, v18
	v_rcp_f32_e32 v19, v19
	v_rcp_f32_e32 v20, v20
	v_rcp_f32_e32 v21, v21
	v_exp_f32_e32 v14, v14
	v_cvt_pk_bf16_f32 v18, v22, v18
	v_cvt_pk_bf16_f32 v19, v19, v20
	v_cvt_pk_bf16_f32 v20, v26, v24
	v_cvt_pk_bf16_f32 v21, v25, v21
	v_mul_f32_e32 v10, 0xbfb8aa3b, v10
	v_add_f32_e32 v14, 1.0, v14
	global_store_dwordx4 v[30:31], v[18:21], off offset:256
	v_exp_f32_e32 v10, v10
	v_mul_f32_e32 v11, 0xbfb8aa3b, v11
	v_rcp_f32_e32 v19, v14
;     __device__ __forceinline__ void operator()(const f32x4 (&acc)[2][2][4][2], const Unit& u, int wr, int wc, int fr, int fq) const {
;     ...
;         } else {
;             const int col0 = u.pn * BM + wc * 32 + 8 * fq;
; #pragma unroll
;             for (int ai = 0; ai < 2; ++ai)
; #pragma unroll
;                 for (int m = 0; m < 4; ++m) {
;                     const size_t row = (size_t)(row0 + ai * HALF + m * 16);
; #pragma unroll
;                     for (int bj = 0; bj < 2; ++bj) {
;                         const int col = col0 + bj * HALF;
;                         f32x4 v0 = acc[ai][bj][m][0], v1 = acc[ai][bj][m][1];
;                         bf16_t* dst = O + row * ldc + col;
;                         if constexpr (MODE == 2) {
; #pragma unroll
;                             for (int e = 0; e < 4; ++e) { v0[e] = sigm(v0[e]); v1[e] = sigm(v1[e]); }
;                         }
;                         if constexpr (MODE == 4) {
;                             const f32x4 b0 = *(const f32x4*)(bias + u.tag * 256 + col), b1 = *(const f32x4*)(bias + u.tag * 256 + col + 4);
; #pragma unroll
;                             for (int e = 0; e < 4; ++e) { v0[e] = gelu_tanh(v0[e] + b0[e]); v1[e] = gelu_tanh(v1[e] + b1[e]); }
;                         }
;                         if constexpr (MODE == 3) {
;                             const u32x4 gv = *(const u32x4*)(G + row * GP + u.tag * 1024 + col);
;                             v0[0] *= bf_lo(gv.x); v0[1] *= bf_hi(gv.x); v0[2] *= bf_lo(gv.y); v0[3] *= bf_hi(gv.y);
;                             v1[0] *= bf_lo(gv.z); v1[1] *= bf_hi(gv.z); v1[2] *= bf_lo(gv.w); v1[3] *= bf_hi(gv.w);
;                             if (u.tag > 0) {
;                                 const u32x4 ov = *(const u32x4*)dst;
;                                 v0[0] += bf_lo(ov.x); v0[1] += bf_hi(ov.x); v0[2] += bf_lo(ov.y); v0[3] += bf_hi(ov.y);
;                                 v1[0] += bf_lo(ov.z); v1[1] += bf_hi(ov.z); v1[2] += bf_lo(ov.w); v1[3] += bf_hi(ov.w);
;                             }
;                         }
;                         *(u32x4*)dst = pack8(v0, v1);
;                     }
; template <class EpiT, class Sched>
; __device__ __forceinline__ void gemm_phase(LAS unsigned char* lds, int tid_in, const GemmDesc g, const Sched& S, const EpiT& E) {
;     ...
;         if (wr == 0) PG8_BAR;
;         E(acc, cur, wr, wc, fr, fq);
	v_mul_f32_e32 v14, 0xbfb8aa3b, v15
	v_exp_f32_e32 v14, v14
	v_exp_f32_e32 v11, v11
	v_add_f32_e32 v10, 1.0, v10
	v_rcp_f32_e32 v20, v10
	v_add_f32_e32 v10, 1.0, v14
	v_rcp_f32_e32 v21, v10
	v_add_f32_e32 v10, 1.0, v11
	v_mul_f32_e32 v11, 0xbfb8aa3b, v16
	v_exp_f32_e32 v11, v11
	v_mul_f32_e32 v12, 0xbfb8aa3b, v12
	v_exp_f32_e32 v12, v12
	v_rcp_f32_e32 v16, v10
	v_add_f32_e32 v10, 1.0, v11
	v_mul_f32_e32 v11, 0xbfb8aa3b, v17
	v_rcp_f32_e32 v22, v10
	v_add_f32_e32 v10, 1.0, v12
	v_exp_f32_e32 v11, v11
	v_mul_f32_e32 v12, 0xbfb8aa3b, v13
	v_exp_f32_e32 v12, v12
	v_rcp_f32_e32 v13, v10
	v_add_f32_e32 v10, 1.0, v11
	v_rcp_f32_e32 v17, v10
	v_add_f32_e32 v10, 1.0, v12
	v_mul_f32_e32 v2, 0xbfb8aa3b, v2
	v_rcp_f32_e32 v23, v10
	v_exp_f32_e32 v2, v2
	v_mul_f32_e32 v7, 0xbfb8aa3b, v7
	v_exp_f32_e32 v7, v7
	v_add_u32_e32 v18, 0xb0, v144
	v_mad_i64_i32 v[10:11], s[2:3], v18, s57, v[122:123]
	v_lshl_add_u64 v[14:15], v[10:11], 0, v[124:125]
	v_cvt_pk_bf16_f32 v10, v19, v21
	v_cvt_pk_bf16_f32 v11, v22, v17
	v_cvt_pk_bf16_f32 v12, v20, v16
	v_cvt_pk_bf16_f32 v13, v13, v23
	v_add_f32_e32 v2, 1.0, v2
	v_mul_f32_e32 v3, 0xbfb8aa3b, v3
	global_store_dwordx4 v[14:15], v[10:13], off
	v_exp_f32_e32 v3, v3
	v_mul_f32_e32 v4, 0xbfb8aa3b, v4
	v_rcp_f32_e32 v10, v2
	v_add_f32_e32 v2, 1.0, v7
	v_mul_f32_e32 v7, 0xbfb8aa3b, v8
	v_exp_f32_e32 v7, v7
	v_add_f32_e32 v3, 1.0, v3
	v_mul_f32_e32 v6, 0xbfb8aa3b, v6
	v_exp_f32_e32 v4, v4
	v_rcp_f32_e32 v8, v3
	v_add_f32_e32 v3, 1.0, v7
	v_mul_f32_e32 v7, 0xbfb8aa3b, v9
	v_mul_f32_e32 v5, 0xbfb8aa3b, v5
	v_exp_f32_e32 v6, v6
	v_exp_f32_e32 v7, v7
	v_exp_f32_e32 v5, v5
	v_add_f32_e32 v4, 1.0, v4
	v_add_f32_e32 v6, 1.0, v6
	v_rcp_f32_e32 v9, v4
	v_add_f32_e32 v4, 1.0, v7
	v_add_f32_e32 v5, 1.0, v5
	v_rcp_f32_e32 v6, v6
	v_rcp_f32_e32 v2, v2
	v_rcp_f32_e32 v3, v3
	v_rcp_f32_e32 v4, v4
	v_rcp_f32_e32 v5, v5
	v_cvt_pk_bf16_f32 v2, v6, v2
	s_andn2_b64 vcc, exec, s[0:1]
	v_cvt_pk_bf16_f32 v3, v3, v4
	v_cvt_pk_bf16_f32 v4, v10, v8
	v_cvt_pk_bf16_f32 v5, v9, v5
	s_mov_b64 s[0:1], -1
	global_store_dwordx4 v[14:15], v[2:5], off offset:256
	s_cbranch_vccnz .LBB0_943
	s_andn2_b64 vcc, exec, s[12:13]
	s_cbranch_vccnz .LBB0_942
	s_barrier
	s_branch .LBB0_942
.Lepi_last_8:
	v_mul_f32_e32 v126, 0xbfb8aa3b, v126
	v_exp_f32_e32 v126, v126
	v_mul_f32_e32 v122, 0xbfb8aa3b, v122
	v_exp_f32_e32 v122, v122
	v_mul_f32_e32 v123, 0xbfb8aa3b, v123
	v_add_f32_e32 v126, 1.0, v126
	v_rcp_f32_e32 v145, v126
	v_mul_f32_e32 v126, 0xbfb8aa3b, v127
	v_exp_f32_e32 v126, v126
	v_exp_f32_e32 v123, v123
	v_add_f32_e32 v122, 1.0, v122
	v_rcp_f32_e32 v148, v122
	v_add_f32_e32 v122, 1.0, v126
	v_rcp_f32_e32 v149, v122
	v_add_f32_e32 v122, 1.0, v123
	v_mul_f32_e32 v123, 0xbfb8aa3b, v128
	v_exp_f32_e32 v123, v123
	v_mul_f32_e32 v124, 0xbfb8aa3b, v124
	v_exp_f32_e32 v124, v124
	v_rcp_f32_e32 v128, v122
	v_add_f32_e32 v122, 1.0, v123
	v_mul_f32_e32 v123, 0xbfb8aa3b, v129
	v_rcp_f32_e32 v150, v122
	v_add_f32_e32 v122, 1.0, v124
	v_exp_f32_e32 v123, v123
	v_mul_f32_e32 v124, 0xbfb8aa3b, v125
	v_exp_f32_e32 v124, v124
	v_rcp_f32_e32 v129, v122
	v_add_f32_e32 v122, 1.0, v123
	v_rcp_f32_e32 v151, v122
	v_add_f32_e32 v122, 1.0, v124
	v_mul_f32_e32 v114, 0xbfb8aa3b, v114
	v_rcp_f32_e32 v152, v122
	v_exp_f32_e32 v114, v114
	v_mul_f32_e32 v119, 0xbfb8aa3b, v119
	v_lshl_or_b32 v146, s58, 8, v142
	v_exp_f32_e32 v119, v119
	v_lshl_add_u32 v144, s30, 8, v140
	v_ashrrev_i32_e32 v147, 31, v146
	v_mov_b64_e32 v[122:123], s[18:19]
	v_mad_i64_i32 v[126:127], s[2:3], v144, s57, v[122:123]
	v_lshlrev_b64 v[124:125], 1, v[146:147]
	v_lshl_add_u64 v[146:147], v[126:127], 0, v[124:125]
	v_cvt_pk_bf16_f32 v126, v145, v149
	v_cvt_pk_bf16_f32 v127, v150, v151
	v_cvt_pk_bf16_f32 v128, v148, v128
	v_cvt_pk_bf16_f32 v129, v129, v152
	v_add_f32_e32 v114, 1.0, v114
	v_mul_f32_e32 v115, 0xbfb8aa3b, v115
	global_store_dwordx4 v[146:147], v[126:129], off sc1
	v_exp_f32_e32 v115, v115
	v_mul_f32_e32 v116, 0xbfb8aa3b, v116
	v_rcp_f32_e32 v126, v114
	v_add_f32_e32 v114, 1.0, v119
	v_mul_f32_e32 v119, 0xbfb8aa3b, v120
	v_exp_f32_e32 v119, v119
	v_add_f32_e32 v115, 1.0, v115
	v_mul_f32_e32 v118, 0xbfb8aa3b, v118
	v_exp_f32_e32 v116, v116
	v_rcp_f32_e32 v120, v115
	v_add_f32_e32 v115, 1.0, v119
	v_mul_f32_e32 v119, 0xbfb8aa3b, v121
	v_mul_f32_e32 v117, 0xbfb8aa3b, v117
	v_exp_f32_e32 v118, v118
	v_exp_f32_e32 v119, v119
	v_exp_f32_e32 v117, v117
	v_add_f32_e32 v116, 1.0, v116
	v_add_f32_e32 v118, 1.0, v118
	v_rcp_f32_e32 v121, v116
	v_add_f32_e32 v116, 1.0, v119
	v_add_f32_e32 v117, 1.0, v117
	v_mul_f32_e32 v110, 0xbfb8aa3b, v110
	v_rcp_f32_e32 v118, v118
	v_rcp_f32_e32 v114, v114
	v_rcp_f32_e32 v115, v115
	v_rcp_f32_e32 v116, v116
	v_rcp_f32_e32 v117, v117
	v_exp_f32_e32 v110, v110
	v_cvt_pk_bf16_f32 v114, v118, v114
	v_cvt_pk_bf16_f32 v115, v115, v116
	v_cvt_pk_bf16_f32 v116, v126, v120
	v_cvt_pk_bf16_f32 v117, v121, v117
	v_mul_f32_e32 v106, 0xbfb8aa3b, v106
	v_add_f32_e32 v110, 1.0, v110
	global_store_dwordx4 v[146:147], v[114:117], off offset:256 sc1
	v_exp_f32_e32 v106, v106
	v_mul_f32_e32 v107, 0xbfb8aa3b, v107
	v_rcp_f32_e32 v115, v110
	v_mul_f32_e32 v110, 0xbfb8aa3b, v111
	v_exp_f32_e32 v110, v110
	v_exp_f32_e32 v107, v107
	v_add_f32_e32 v106, 1.0, v106
	v_rcp_f32_e32 v116, v106
	v_add_f32_e32 v106, 1.0, v110
	v_rcp_f32_e32 v117, v106
	v_add_f32_e32 v106, 1.0, v107
	v_mul_f32_e32 v107, 0xbfb8aa3b, v112
	v_exp_f32_e32 v107, v107
	v_mul_f32_e32 v108, 0xbfb8aa3b, v108
	v_exp_f32_e32 v108, v108
	v_rcp_f32_e32 v112, v106
	v_add_f32_e32 v106, 1.0, v107
	v_mul_f32_e32 v107, 0xbfb8aa3b, v113
	v_rcp_f32_e32 v118, v106
	v_add_f32_e32 v106, 1.0, v108
	v_exp_f32_e32 v107, v107
	v_mul_f32_e32 v108, 0xbfb8aa3b, v109
; __device__ __forceinline__ float bf_lo(unsigned u) { return __uint_as_float(u << 16); }
; __device__ __forceinline__ float bf_hi(unsigned u) { return __uint_as_float(u & 0xffff0000u); }
;     __device__ __forceinline__ void operator()(const f32x4 (&acc)[2][2][4][2], const Unit& u, int wr, int wc, int fr, int fq) const {
;     ...
;         } else {
;             const int col0 = u.pn * BM + wc * 32 + 8 * fq;
; #pragma unroll
;             for (int ai = 0; ai < 2; ++ai)
; #pragma unroll
;                 for (int m = 0; m < 4; ++m) {
;                     const size_t row = (size_t)(row0 + ai * HALF + m * 16);
; #pragma unroll
;                     for (int bj = 0; bj < 2; ++bj) {
;                         const int col = col0 + bj * HALF;
;                         f32x4 v0 = acc[ai][bj][m][0], v1 = acc[ai][bj][m][1];
;                         bf16_t* dst = O + row * ldc + col;
;                         if constexpr (MODE == 2) {
; #pragma unroll
;                             for (int e = 0; e < 4; ++e) { v0[e] = sigm(v0[e]); v1[e] = sigm(v1[e]); }
;                         }
;                         if constexpr (MODE == 4) {
;                             const f32x4 b0 = *(const f32x4*)(bias + u.tag * 256 + col), b1 = *(const f32x4*)(bias + u.tag * 256 + col + 4);
; #pragma unroll
;                             for (int e = 0; e < 4; ++e) { v0[e] = gelu_tanh(v0[e] + b0[e]); v1[e] = gelu_tanh(v1[e] + b1[e]); }
;                         }
;                         if constexpr (MODE == 3) {
;                             const u32x4 gv = *(const u32x4*)(G + row * GP + u.tag * 1024 + col);
;                             v0[0] *= bf_lo(gv.x); v0[1] *= bf_hi(gv.x); v0[2] *= bf_lo(gv.y); v0[3] *= bf_hi(gv.y);
;                             v1[0] *= bf_lo(gv.z); v1[1] *= bf_hi(gv.z); v1[2] *= bf_lo(gv.w); v1[3] *= bf_hi(gv.w);
;                             if (u.tag > 0) {
;                                 const u32x4 ov = *(const u32x4*)dst;
;                                 v0[0] += bf_lo(ov.x); v0[1] += bf_hi(ov.x); v0[2] += bf_lo(ov.y); v0[3] += bf_hi(ov.y);
;                                 v1[0] += bf_lo(ov.z); v1[1] += bf_hi(ov.z); v1[2] += bf_lo(ov.w); v1[3] += bf_hi(ov.w);
;                             }
;                         }
;                         *(u32x4*)dst = pack8(v0, v1);
;                     }
	v_exp_f32_e32 v108, v108
	v_rcp_f32_e32 v109, v106
	v_add_f32_e32 v106, 1.0, v107
	v_rcp_f32_e32 v113, v106
	v_add_f32_e32 v106, 1.0, v108
	v_mul_f32_e32 v98, 0xbfb8aa3b, v98
	v_rcp_f32_e32 v119, v106
	v_exp_f32_e32 v98, v98
	v_mul_f32_e32 v103, 0xbfb8aa3b, v103
	v_exp_f32_e32 v103, v103
	v_or_b32_e32 v114, 16, v144
	v_mad_i64_i32 v[106:107], s[2:3], v114, s57, v[122:123]
	v_lshl_add_u64 v[110:111], v[106:107], 0, v[124:125]
	v_cvt_pk_bf16_f32 v106, v115, v117
	v_cvt_pk_bf16_f32 v107, v118, v113
	v_cvt_pk_bf16_f32 v108, v116, v112
	v_cvt_pk_bf16_f32 v109, v109, v119
	v_add_f32_e32 v98, 1.0, v98
	v_mul_f32_e32 v99, 0xbfb8aa3b, v99
	global_store_dwordx4 v[110:111], v[106:109], off sc1
	v_exp_f32_e32 v99, v99
	v_mul_f32_e32 v100, 0xbfb8aa3b, v100
	v_rcp_f32_e32 v106, v98
	v_add_f32_e32 v98, 1.0, v103
	v_mul_f32_e32 v103, 0xbfb8aa3b, v104
	v_exp_f32_e32 v103, v103
	v_add_f32_e32 v99, 1.0, v99
	v_mul_f32_e32 v102, 0xbfb8aa3b, v102
	v_exp_f32_e32 v100, v100
	v_rcp_f32_e32 v104, v99
	v_add_f32_e32 v99, 1.0, v103
	v_mul_f32_e32 v103, 0xbfb8aa3b, v105
	v_mul_f32_e32 v101, 0xbfb8aa3b, v101
	v_exp_f32_e32 v102, v102
	v_exp_f32_e32 v103, v103
	v_exp_f32_e32 v101, v101
	v_add_f32_e32 v100, 1.0, v100
	v_add_f32_e32 v102, 1.0, v102
	v_rcp_f32_e32 v105, v100
	v_add_f32_e32 v100, 1.0, v103
	v_add_f32_e32 v101, 1.0, v101
	v_mul_f32_e32 v94, 0xbfb8aa3b, v94
	v_rcp_f32_e32 v102, v102
	v_rcp_f32_e32 v98, v98
	v_rcp_f32_e32 v99, v99
	v_rcp_f32_e32 v100, v100
	v_rcp_f32_e32 v101, v101
	v_exp_f32_e32 v94, v94
	v_cvt_pk_bf16_f32 v98, v102, v98
	v_cvt_pk_bf16_f32 v99, v99, v100
	v_cvt_pk_bf16_f32 v100, v106, v104
	v_cvt_pk_bf16_f32 v101, v105, v101
	v_mul_f32_e32 v90, 0xbfb8aa3b, v90
	v_add_f32_e32 v94, 1.0, v94
	global_store_dwordx4 v[110:111], v[98:101], off offset:256 sc1
	v_exp_f32_e32 v90, v90
	v_mul_f32_e32 v91, 0xbfb8aa3b, v91
	v_rcp_f32_e32 v99, v94
	v_mul_f32_e32 v94, 0xbfb8aa3b, v95
	v_exp_f32_e32 v94, v94
	v_exp_f32_e32 v91, v91
	v_add_f32_e32 v90, 1.0, v90
	v_rcp_f32_e32 v100, v90
	v_add_f32_e32 v90, 1.0, v94
	v_rcp_f32_e32 v101, v90
	v_add_f32_e32 v90, 1.0, v91
	v_mul_f32_e32 v91, 0xbfb8aa3b, v96
	v_exp_f32_e32 v91, v91
	v_mul_f32_e32 v92, 0xbfb8aa3b, v92
	v_exp_f32_e32 v92, v92
	v_rcp_f32_e32 v96, v90
	v_add_f32_e32 v90, 1.0, v91
	v_mul_f32_e32 v91, 0xbfb8aa3b, v97
	v_rcp_f32_e32 v102, v90
	v_add_f32_e32 v90, 1.0, v92
	v_exp_f32_e32 v91, v91
	v_mul_f32_e32 v92, 0xbfb8aa3b, v93
	v_exp_f32_e32 v92, v92
	v_rcp_f32_e32 v93, v90
	v_add_f32_e32 v90, 1.0, v91
	v_rcp_f32_e32 v97, v90
	v_add_f32_e32 v90, 1.0, v92
	v_mul_f32_e32 v82, 0xbfb8aa3b, v82
	v_rcp_f32_e32 v103, v90
	v_exp_f32_e32 v82, v82
	v_mul_f32_e32 v87, 0xbfb8aa3b, v87
	v_exp_f32_e32 v87, v87
	v_or_b32_e32 v98, 32, v144
	v_mad_i64_i32 v[90:91], s[2:3], v98, s57, v[122:123]
	v_lshl_add_u64 v[94:95], v[90:91], 0, v[124:125]
	v_cvt_pk_bf16_f32 v90, v99, v101
	v_cvt_pk_bf16_f32 v91, v102, v97
	v_cvt_pk_bf16_f32 v92, v100, v96
	v_cvt_pk_bf16_f32 v93, v93, v103
	v_add_f32_e32 v82, 1.0, v82
	v_mul_f32_e32 v83, 0xbfb8aa3b, v83
	global_store_dwordx4 v[94:95], v[90:93], off sc1
	v_exp_f32_e32 v83, v83
	v_mul_f32_e32 v84, 0xbfb8aa3b, v84
	v_rcp_f32_e32 v90, v82
	v_add_f32_e32 v82, 1.0, v87
	v_mul_f32_e32 v87, 0xbfb8aa3b, v88
	v_exp_f32_e32 v87, v87
	v_add_f32_e32 v83, 1.0, v83
	v_mul_f32_e32 v86, 0xbfb8aa3b, v86
	v_exp_f32_e32 v84, v84
	v_rcp_f32_e32 v88, v83
	v_add_f32_e32 v83, 1.0, v87
	v_mul_f32_e32 v87, 0xbfb8aa3b, v89
	v_mul_f32_e32 v85, 0xbfb8aa3b, v85
	v_exp_f32_e32 v86, v86
	v_exp_f32_e32 v87, v87
	v_exp_f32_e32 v85, v85
	v_add_f32_e32 v84, 1.0, v84
	v_add_f32_e32 v86, 1.0, v86
	v_rcp_f32_e32 v89, v84
	v_add_f32_e32 v84, 1.0, v87
	v_add_f32_e32 v85, 1.0, v85
	v_mul_f32_e32 v78, 0xbfb8aa3b, v78
	v_rcp_f32_e32 v86, v86
	v_rcp_f32_e32 v82, v82
	v_rcp_f32_e32 v83, v83
	v_rcp_f32_e32 v84, v84
	v_rcp_f32_e32 v85, v85
	v_exp_f32_e32 v78, v78
	v_cvt_pk_bf16_f32 v82, v86, v82
	v_cvt_pk_bf16_f32 v83, v83, v84
	v_cvt_pk_bf16_f32 v84, v90, v88
	v_cvt_pk_bf16_f32 v85, v89, v85
	v_mul_f32_e32 v74, 0xbfb8aa3b, v74
	v_add_f32_e32 v78, 1.0, v78
	global_store_dwordx4 v[94:95], v[82:85], off offset:256 sc1
	v_exp_f32_e32 v74, v74
	v_mul_f32_e32 v75, 0xbfb8aa3b, v75
	v_rcp_f32_e32 v83, v78
	v_mul_f32_e32 v78, 0xbfb8aa3b, v79
	v_exp_f32_e32 v78, v78
	v_exp_f32_e32 v75, v75
	v_add_f32_e32 v74, 1.0, v74
	v_rcp_f32_e32 v84, v74
	v_add_f32_e32 v74, 1.0, v78
	v_rcp_f32_e32 v85, v74
	v_add_f32_e32 v74, 1.0, v75
	v_mul_f32_e32 v75, 0xbfb8aa3b, v80
	v_exp_f32_e32 v75, v75
	v_mul_f32_e32 v76, 0xbfb8aa3b, v76
	v_exp_f32_e32 v76, v76
	v_rcp_f32_e32 v80, v74
	v_add_f32_e32 v74, 1.0, v75
	v_mul_f32_e32 v75, 0xbfb8aa3b, v81
	v_rcp_f32_e32 v86, v74
	v_add_f32_e32 v74, 1.0, v76
	v_exp_f32_e32 v75, v75
	v_mul_f32_e32 v76, 0xbfb8aa3b, v77
	v_exp_f32_e32 v76, v76
	v_rcp_f32_e32 v77, v74
	v_add_f32_e32 v74, 1.0, v75
	v_rcp_f32_e32 v81, v74
	v_add_f32_e32 v74, 1.0, v76
	v_mul_f32_e32 v66, 0xbfb8aa3b, v66
	v_rcp_f32_e32 v87, v74
	v_exp_f32_e32 v66, v66
	v_mul_f32_e32 v71, 0xbfb8aa3b, v71
	v_exp_f32_e32 v71, v71
	v_or_b32_e32 v82, 48, v144
	v_mad_i64_i32 v[74:75], s[2:3], v82, s57, v[122:123]
	v_lshl_add_u64 v[78:79], v[74:75], 0, v[124:125]
	v_cvt_pk_bf16_f32 v74, v83, v85
	v_cvt_pk_bf16_f32 v75, v86, v81
	v_cvt_pk_bf16_f32 v76, v84, v80
	v_cvt_pk_bf16_f32 v77, v77, v87
	v_add_f32_e32 v66, 1.0, v66
	v_mul_f32_e32 v67, 0xbfb8aa3b, v67
	global_store_dwordx4 v[78:79], v[74:77], off sc1
	v_exp_f32_e32 v67, v67
	v_mul_f32_e32 v68, 0xbfb8aa3b, v68
	v_rcp_f32_e32 v74, v66
	v_add_f32_e32 v66, 1.0, v71
	v_mul_f32_e32 v71, 0xbfb8aa3b, v72
	v_exp_f32_e32 v71, v71
	v_add_f32_e32 v67, 1.0, v67
	v_mul_f32_e32 v70, 0xbfb8aa3b, v70
	v_exp_f32_e32 v68, v68
; __device__ __forceinline__ float bf_lo(unsigned u) { return __uint_as_float(u << 16); }
; __device__ __forceinline__ float bf_hi(unsigned u) { return __uint_as_float(u & 0xffff0000u); }
;     __device__ __forceinline__ void operator()(const f32x4 (&acc)[2][2][4][2], const Unit& u, int wr, int wc, int fr, int fq) const {
;     ...
;         } else {
;             const int col0 = u.pn * BM + wc * 32 + 8 * fq;
; #pragma unroll
;             for (int ai = 0; ai < 2; ++ai)
; #pragma unroll
;                 for (int m = 0; m < 4; ++m) {
;                     const size_t row = (size_t)(row0 + ai * HALF + m * 16);
; #pragma unroll
;                     for (int bj = 0; bj < 2; ++bj) {
;                         const int col = col0 + bj * HALF;
;                         f32x4 v0 = acc[ai][bj][m][0], v1 = acc[ai][bj][m][1];
;                         bf16_t* dst = O + row * ldc + col;
;                         if constexpr (MODE == 2) {
; #pragma unroll
;                             for (int e = 0; e < 4; ++e) { v0[e] = sigm(v0[e]); v1[e] = sigm(v1[e]); }
;                         }
;                         if constexpr (MODE == 4) {
;                             const f32x4 b0 = *(const f32x4*)(bias + u.tag * 256 + col), b1 = *(const f32x4*)(bias + u.tag * 256 + col + 4);
; #pragma unroll
;                             for (int e = 0; e < 4; ++e) { v0[e] = gelu_tanh(v0[e] + b0[e]); v1[e] = gelu_tanh(v1[e] + b1[e]); }
;                         }
;                         if constexpr (MODE == 3) {
;                             const u32x4 gv = *(const u32x4*)(G + row * GP + u.tag * 1024 + col);
;                             v0[0] *= bf_lo(gv.x); v0[1] *= bf_hi(gv.x); v0[2] *= bf_lo(gv.y); v0[3] *= bf_hi(gv.y);
;                             v1[0] *= bf_lo(gv.z); v1[1] *= bf_hi(gv.z); v1[2] *= bf_lo(gv.w); v1[3] *= bf_hi(gv.w);
;                             if (u.tag > 0) {
;                                 const u32x4 ov = *(const u32x4*)dst;
;                                 v0[0] += bf_lo(ov.x); v0[1] += bf_hi(ov.x); v0[2] += bf_lo(ov.y); v0[3] += bf_hi(ov.y);
;                                 v1[0] += bf_lo(ov.z); v1[1] += bf_hi(ov.z); v1[2] += bf_lo(ov.w); v1[3] += bf_hi(ov.w);
;                             }
;                         }
;                         *(u32x4*)dst = pack8(v0, v1);
;                     }
	v_rcp_f32_e32 v72, v67
	v_add_f32_e32 v67, 1.0, v71
	v_mul_f32_e32 v71, 0xbfb8aa3b, v73
	v_mul_f32_e32 v69, 0xbfb8aa3b, v69
	v_exp_f32_e32 v70, v70
	v_exp_f32_e32 v71, v71
	v_exp_f32_e32 v69, v69
	v_add_f32_e32 v68, 1.0, v68
	v_add_f32_e32 v70, 1.0, v70
	v_rcp_f32_e32 v73, v68
	v_add_f32_e32 v68, 1.0, v71
	v_add_f32_e32 v69, 1.0, v69
	v_mul_f32_e32 v62, 0xbfb8aa3b, v62
	v_rcp_f32_e32 v70, v70
	v_rcp_f32_e32 v66, v66
	v_rcp_f32_e32 v67, v67
	v_rcp_f32_e32 v68, v68
	v_rcp_f32_e32 v69, v69
	v_exp_f32_e32 v62, v62
	v_cvt_pk_bf16_f32 v66, v70, v66
	v_cvt_pk_bf16_f32 v67, v67, v68
	v_cvt_pk_bf16_f32 v68, v74, v72
	v_cvt_pk_bf16_f32 v69, v73, v69
	v_mul_f32_e32 v58, 0xbfb8aa3b, v58
	v_add_f32_e32 v62, 1.0, v62
	global_store_dwordx4 v[78:79], v[66:69], off offset:256 sc1
	v_exp_f32_e32 v58, v58
	v_mul_f32_e32 v59, 0xbfb8aa3b, v59
	v_rcp_f32_e32 v67, v62
	v_mul_f32_e32 v62, 0xbfb8aa3b, v63
	v_exp_f32_e32 v62, v62
	v_exp_f32_e32 v59, v59
	v_add_f32_e32 v58, 1.0, v58
	v_rcp_f32_e32 v68, v58
	v_add_f32_e32 v58, 1.0, v62
	v_rcp_f32_e32 v69, v58
	v_add_f32_e32 v58, 1.0, v59
	v_mul_f32_e32 v59, 0xbfb8aa3b, v64
	v_exp_f32_e32 v59, v59
	v_mul_f32_e32 v60, 0xbfb8aa3b, v60
	v_exp_f32_e32 v60, v60
	v_rcp_f32_e32 v64, v58
	v_add_f32_e32 v58, 1.0, v59
	v_mul_f32_e32 v59, 0xbfb8aa3b, v65
	v_rcp_f32_e32 v70, v58
	v_add_f32_e32 v58, 1.0, v60
	v_exp_f32_e32 v59, v59
	v_mul_f32_e32 v60, 0xbfb8aa3b, v61
	v_exp_f32_e32 v60, v60
	v_rcp_f32_e32 v61, v58
	v_add_f32_e32 v58, 1.0, v59
	v_rcp_f32_e32 v65, v58
	v_add_f32_e32 v58, 1.0, v60
	v_mul_f32_e32 v50, 0xbfb8aa3b, v50
	v_rcp_f32_e32 v71, v58
	v_exp_f32_e32 v50, v50
	v_mul_f32_e32 v55, 0xbfb8aa3b, v55
	v_exp_f32_e32 v55, v55
	v_add_u32_e32 v66, 0x80, v144
	v_mad_i64_i32 v[58:59], s[2:3], v66, s57, v[122:123]
	v_lshl_add_u64 v[62:63], v[58:59], 0, v[124:125]
	v_cvt_pk_bf16_f32 v58, v67, v69
	v_cvt_pk_bf16_f32 v59, v70, v65
	v_cvt_pk_bf16_f32 v60, v68, v64
	v_cvt_pk_bf16_f32 v61, v61, v71
	v_add_f32_e32 v50, 1.0, v50
	v_mul_f32_e32 v51, 0xbfb8aa3b, v51
	global_store_dwordx4 v[62:63], v[58:61], off sc1
	v_exp_f32_e32 v51, v51
	v_mul_f32_e32 v52, 0xbfb8aa3b, v52
	v_rcp_f32_e32 v58, v50
	v_add_f32_e32 v50, 1.0, v55
	v_mul_f32_e32 v55, 0xbfb8aa3b, v56
	v_exp_f32_e32 v55, v55
	v_add_f32_e32 v51, 1.0, v51
	v_mul_f32_e32 v54, 0xbfb8aa3b, v54
	v_exp_f32_e32 v52, v52
	v_rcp_f32_e32 v56, v51
	v_add_f32_e32 v51, 1.0, v55
	v_mul_f32_e32 v55, 0xbfb8aa3b, v57
	v_mul_f32_e32 v53, 0xbfb8aa3b, v53
	v_exp_f32_e32 v54, v54
	v_exp_f32_e32 v55, v55
	v_exp_f32_e32 v53, v53
	v_add_f32_e32 v52, 1.0, v52
	v_add_f32_e32 v54, 1.0, v54
	v_rcp_f32_e32 v57, v52
	v_add_f32_e32 v52, 1.0, v55
	v_add_f32_e32 v53, 1.0, v53
	v_mul_f32_e32 v46, 0xbfb8aa3b, v46
	v_rcp_f32_e32 v54, v54
	v_rcp_f32_e32 v50, v50
	v_rcp_f32_e32 v51, v51
	v_rcp_f32_e32 v52, v52
	v_rcp_f32_e32 v53, v53
	v_exp_f32_e32 v46, v46
	v_cvt_pk_bf16_f32 v50, v54, v50
	v_cvt_pk_bf16_f32 v51, v51, v52
	v_cvt_pk_bf16_f32 v52, v58, v56
	v_cvt_pk_bf16_f32 v53, v57, v53
	v_mul_f32_e32 v42, 0xbfb8aa3b, v42
	v_add_f32_e32 v46, 1.0, v46
	global_store_dwordx4 v[62:63], v[50:53], off offset:256 sc1
	v_exp_f32_e32 v42, v42
	v_mul_f32_e32 v43, 0xbfb8aa3b, v43
	v_rcp_f32_e32 v51, v46
	v_mul_f32_e32 v46, 0xbfb8aa3b, v47
	v_exp_f32_e32 v46, v46
	v_exp_f32_e32 v43, v43
	v_add_f32_e32 v42, 1.0, v42
	v_rcp_f32_e32 v52, v42
	v_add_f32_e32 v42, 1.0, v46
	v_rcp_f32_e32 v53, v42
	v_add_f32_e32 v42, 1.0, v43
	v_mul_f32_e32 v43, 0xbfb8aa3b, v48
	v_exp_f32_e32 v43, v43
	v_mul_f32_e32 v44, 0xbfb8aa3b, v44
	v_exp_f32_e32 v44, v44
	v_rcp_f32_e32 v48, v42
	v_add_f32_e32 v42, 1.0, v43
	v_mul_f32_e32 v43, 0xbfb8aa3b, v49
	v_rcp_f32_e32 v54, v42
	v_add_f32_e32 v42, 1.0, v44
	v_exp_f32_e32 v43, v43
	v_mul_f32_e32 v44, 0xbfb8aa3b, v45
	v_exp_f32_e32 v44, v44
	v_rcp_f32_e32 v45, v42
	v_add_f32_e32 v42, 1.0, v43
	v_rcp_f32_e32 v49, v42
	v_add_f32_e32 v42, 1.0, v44
	v_mul_f32_e32 v34, 0xbfb8aa3b, v34
	v_rcp_f32_e32 v55, v42
	v_exp_f32_e32 v34, v34
	v_mul_f32_e32 v39, 0xbfb8aa3b, v39
	v_exp_f32_e32 v39, v39
	v_add_u32_e32 v50, 0x90, v144
	v_mad_i64_i32 v[42:43], s[2:3], v50, s57, v[122:123]
	v_lshl_add_u64 v[46:47], v[42:43], 0, v[124:125]
	v_cvt_pk_bf16_f32 v42, v51, v53
	v_cvt_pk_bf16_f32 v43, v54, v49
	v_cvt_pk_bf16_f32 v44, v52, v48
	v_cvt_pk_bf16_f32 v45, v45, v55
	v_add_f32_e32 v34, 1.0, v34
	v_mul_f32_e32 v35, 0xbfb8aa3b, v35
	global_store_dwordx4 v[46:47], v[42:45], off sc1
	v_exp_f32_e32 v35, v35
	v_mul_f32_e32 v36, 0xbfb8aa3b, v36
	v_rcp_f32_e32 v42, v34
	v_add_f32_e32 v34, 1.0, v39
	v_mul_f32_e32 v39, 0xbfb8aa3b, v40
	v_exp_f32_e32 v39, v39
	v_add_f32_e32 v35, 1.0, v35
	v_mul_f32_e32 v38, 0xbfb8aa3b, v38
	v_exp_f32_e32 v36, v36
	v_rcp_f32_e32 v40, v35
	v_add_f32_e32 v35, 1.0, v39
	v_mul_f32_e32 v39, 0xbfb8aa3b, v41
	v_mul_f32_e32 v37, 0xbfb8aa3b, v37
	v_exp_f32_e32 v38, v38
	v_exp_f32_e32 v39, v39
	v_exp_f32_e32 v37, v37
	v_add_f32_e32 v36, 1.0, v36
	v_add_f32_e32 v38, 1.0, v38
	v_rcp_f32_e32 v41, v36
	v_add_f32_e32 v36, 1.0, v39
	v_add_f32_e32 v37, 1.0, v37
;     __device__ __forceinline__ void operator()(const f32x4 (&acc)[2][2][4][2], const Unit& u, int wr, int wc, int fr, int fq) const {
;     ...
;         } else {
;             const int col0 = u.pn * BM + wc * 32 + 8 * fq;
; #pragma unroll
;             for (int ai = 0; ai < 2; ++ai)
; #pragma unroll
;                 for (int m = 0; m < 4; ++m) {
;                     const size_t row = (size_t)(row0 + ai * HALF + m * 16);
; #pragma unroll
;                     for (int bj = 0; bj < 2; ++bj) {
;                         const int col = col0 + bj * HALF;
;                         f32x4 v0 = acc[ai][bj][m][0], v1 = acc[ai][bj][m][1];
;                         bf16_t* dst = O + row * ldc + col;
;                         if constexpr (MODE == 2) {
; #pragma unroll
;                             for (int e = 0; e < 4; ++e) { v0[e] = sigm(v0[e]); v1[e] = sigm(v1[e]); }
;                         }
;                         if constexpr (MODE == 4) {
;                             const f32x4 b0 = *(const f32x4*)(bias + u.tag * 256 + col), b1 = *(const f32x4*)(bias + u.tag * 256 + col + 4);
; #pragma unroll
;                             for (int e = 0; e < 4; ++e) { v0[e] = gelu_tanh(v0[e] + b0[e]); v1[e] = gelu_tanh(v1[e] + b1[e]); }
;                         }
;                         if constexpr (MODE == 3) {
;                             const u32x4 gv = *(const u32x4*)(G + row * GP + u.tag * 1024 + col);
;                             v0[0] *= bf_lo(gv.x); v0[1] *= bf_hi(gv.x); v0[2] *= bf_lo(gv.y); v0[3] *= bf_hi(gv.y);
;                             v1[0] *= bf_lo(gv.z); v1[1] *= bf_hi(gv.z); v1[2] *= bf_lo(gv.w); v1[3] *= bf_hi(gv.w);
;                             if (u.tag > 0) {
;                                 const u32x4 ov = *(const u32x4*)dst;
;                                 v0[0] += bf_lo(ov.x); v0[1] += bf_hi(ov.x); v0[2] += bf_lo(ov.y); v0[3] += bf_hi(ov.y);
;                                 v1[0] += bf_lo(ov.z); v1[1] += bf_hi(ov.z); v1[2] += bf_lo(ov.w); v1[3] += bf_hi(ov.w);
;                             }
;                         }
;                         *(u32x4*)dst = pack8(v0, v1);
;                     }
; template <class EpiT, class Sched>
; __device__ __forceinline__ void gemm_phase(LAS unsigned char* lds, int tid_in, const GemmDesc g, const Sched& S, const EpiT& E) {
;     ...
;         if (wr == 0) PG8_BAR;
;         E(acc, cur, wr, wc, fr, fq);
	v_mul_f32_e32 v30, 0xbfb8aa3b, v30
	v_rcp_f32_e32 v38, v38
	v_rcp_f32_e32 v34, v34
	v_rcp_f32_e32 v35, v35
	v_rcp_f32_e32 v36, v36
	v_rcp_f32_e32 v37, v37
	v_exp_f32_e32 v30, v30
	v_cvt_pk_bf16_f32 v34, v38, v34
	v_cvt_pk_bf16_f32 v35, v35, v36
	v_cvt_pk_bf16_f32 v36, v42, v40
	v_cvt_pk_bf16_f32 v37, v41, v37
	v_mul_f32_e32 v26, 0xbfb8aa3b, v26
	v_add_f32_e32 v30, 1.0, v30
	global_store_dwordx4 v[46:47], v[34:37], off offset:256 sc1
	v_exp_f32_e32 v26, v26
	v_mul_f32_e32 v27, 0xbfb8aa3b, v27
	v_rcp_f32_e32 v35, v30
	v_mul_f32_e32 v30, 0xbfb8aa3b, v31
	v_exp_f32_e32 v30, v30
	v_exp_f32_e32 v27, v27
	v_add_f32_e32 v26, 1.0, v26
	v_rcp_f32_e32 v36, v26
	v_add_f32_e32 v26, 1.0, v30
	v_rcp_f32_e32 v37, v26
	v_add_f32_e32 v26, 1.0, v27
	v_mul_f32_e32 v27, 0xbfb8aa3b, v32
	v_exp_f32_e32 v27, v27
	v_mul_f32_e32 v28, 0xbfb8aa3b, v28
	v_exp_f32_e32 v28, v28
	v_rcp_f32_e32 v32, v26
	v_add_f32_e32 v26, 1.0, v27
	v_mul_f32_e32 v27, 0xbfb8aa3b, v33
	v_rcp_f32_e32 v38, v26
	v_add_f32_e32 v26, 1.0, v28
	v_exp_f32_e32 v27, v27
	v_mul_f32_e32 v28, 0xbfb8aa3b, v29
	v_exp_f32_e32 v28, v28
	v_rcp_f32_e32 v29, v26
	v_add_f32_e32 v26, 1.0, v27
	v_rcp_f32_e32 v33, v26
	v_add_f32_e32 v26, 1.0, v28
	v_mul_f32_e32 v18, 0xbfb8aa3b, v18
	v_rcp_f32_e32 v39, v26
	v_exp_f32_e32 v18, v18
	v_mul_f32_e32 v23, 0xbfb8aa3b, v23
	v_exp_f32_e32 v23, v23
	v_add_u32_e32 v34, 0xa0, v144
	v_mad_i64_i32 v[26:27], s[2:3], v34, s57, v[122:123]
	v_lshl_add_u64 v[30:31], v[26:27], 0, v[124:125]
	v_cvt_pk_bf16_f32 v26, v35, v37
	v_cvt_pk_bf16_f32 v27, v38, v33
	v_cvt_pk_bf16_f32 v28, v36, v32
	v_cvt_pk_bf16_f32 v29, v29, v39
	v_add_f32_e32 v18, 1.0, v18
	v_mul_f32_e32 v19, 0xbfb8aa3b, v19
	global_store_dwordx4 v[30:31], v[26:29], off sc1
	v_exp_f32_e32 v19, v19
	v_mul_f32_e32 v20, 0xbfb8aa3b, v20
	v_rcp_f32_e32 v26, v18
	v_add_f32_e32 v18, 1.0, v23
	v_mul_f32_e32 v23, 0xbfb8aa3b, v24
	v_exp_f32_e32 v23, v23
	v_add_f32_e32 v19, 1.0, v19
	v_mul_f32_e32 v22, 0xbfb8aa3b, v22
	v_exp_f32_e32 v20, v20
	v_rcp_f32_e32 v24, v19
	v_add_f32_e32 v19, 1.0, v23
	v_mul_f32_e32 v23, 0xbfb8aa3b, v25
	v_mul_f32_e32 v21, 0xbfb8aa3b, v21
	v_exp_f32_e32 v22, v22
	v_exp_f32_e32 v23, v23
	v_exp_f32_e32 v21, v21
	v_add_f32_e32 v20, 1.0, v20
	v_add_f32_e32 v22, 1.0, v22
	v_rcp_f32_e32 v25, v20
	v_add_f32_e32 v20, 1.0, v23
	v_add_f32_e32 v21, 1.0, v21
	v_mul_f32_e32 v14, 0xbfb8aa3b, v14
	v_rcp_f32_e32 v22, v22
	v_rcp_f32_e32 v18, v18
	v_rcp_f32_e32 v19, v19
	v_rcp_f32_e32 v20, v20
	v_rcp_f32_e32 v21, v21
	v_exp_f32_e32 v14, v14
	v_cvt_pk_bf16_f32 v18, v22, v18
	v_cvt_pk_bf16_f32 v19, v19, v20
	v_cvt_pk_bf16_f32 v20, v26, v24
	v_cvt_pk_bf16_f32 v21, v25, v21
	v_mul_f32_e32 v10, 0xbfb8aa3b, v10
	v_add_f32_e32 v14, 1.0, v14
	global_store_dwordx4 v[30:31], v[18:21], off offset:256 sc1
	v_exp_f32_e32 v10, v10
	v_mul_f32_e32 v11, 0xbfb8aa3b, v11
	v_rcp_f32_e32 v19, v14
	v_mul_f32_e32 v14, 0xbfb8aa3b, v15
	v_exp_f32_e32 v14, v14
	v_exp_f32_e32 v11, v11
	v_add_f32_e32 v10, 1.0, v10
	v_rcp_f32_e32 v20, v10
	v_add_f32_e32 v10, 1.0, v14
	v_rcp_f32_e32 v21, v10
	v_add_f32_e32 v10, 1.0, v11
	v_mul_f32_e32 v11, 0xbfb8aa3b, v16
	v_exp_f32_e32 v11, v11
	v_mul_f32_e32 v12, 0xbfb8aa3b, v12
	v_exp_f32_e32 v12, v12
	v_rcp_f32_e32 v16, v10
	v_add_f32_e32 v10, 1.0, v11
	v_mul_f32_e32 v11, 0xbfb8aa3b, v17
	v_rcp_f32_e32 v22, v10
	v_add_f32_e32 v10, 1.0, v12
	v_exp_f32_e32 v11, v11
	v_mul_f32_e32 v12, 0xbfb8aa3b, v13
	v_exp_f32_e32 v12, v12
	v_rcp_f32_e32 v13, v10
	v_add_f32_e32 v10, 1.0, v11
	v_rcp_f32_e32 v17, v10
	v_add_f32_e32 v10, 1.0, v12
	v_mul_f32_e32 v2, 0xbfb8aa3b, v2
	v_rcp_f32_e32 v23, v10
	v_exp_f32_e32 v2, v2
	v_mul_f32_e32 v7, 0xbfb8aa3b, v7
	v_exp_f32_e32 v7, v7
	v_add_u32_e32 v18, 0xb0, v144
	v_mad_i64_i32 v[10:11], s[2:3], v18, s57, v[122:123]
	v_lshl_add_u64 v[14:15], v[10:11], 0, v[124:125]
	v_cvt_pk_bf16_f32 v10, v19, v21
	v_cvt_pk_bf16_f32 v11, v22, v17
	v_cvt_pk_bf16_f32 v12, v20, v16
	v_cvt_pk_bf16_f32 v13, v13, v23
	v_add_f32_e32 v2, 1.0, v2
	v_mul_f32_e32 v3, 0xbfb8aa3b, v3
	global_store_dwordx4 v[14:15], v[10:13], off sc1
	v_exp_f32_e32 v3, v3
	v_mul_f32_e32 v4, 0xbfb8aa3b, v4
	v_rcp_f32_e32 v10, v2
	v_add_f32_e32 v2, 1.0, v7
	v_mul_f32_e32 v7, 0xbfb8aa3b, v8
	v_exp_f32_e32 v7, v7
	v_add_f32_e32 v3, 1.0, v3
	v_mul_f32_e32 v6, 0xbfb8aa3b, v6
	v_exp_f32_e32 v4, v4
	v_rcp_f32_e32 v8, v3
	v_add_f32_e32 v3, 1.0, v7
	v_mul_f32_e32 v7, 0xbfb8aa3b, v9
	v_mul_f32_e32 v5, 0xbfb8aa3b, v5
	v_exp_f32_e32 v6, v6
	v_exp_f32_e32 v7, v7
	v_exp_f32_e32 v5, v5
	v_add_f32_e32 v4, 1.0, v4
	v_add_f32_e32 v6, 1.0, v6
	v_rcp_f32_e32 v9, v4
	v_add_f32_e32 v4, 1.0, v7
	v_add_f32_e32 v5, 1.0, v5
	v_rcp_f32_e32 v6, v6
	v_rcp_f32_e32 v2, v2
	v_rcp_f32_e32 v3, v3
	v_rcp_f32_e32 v4, v4
	v_rcp_f32_e32 v5, v5
	v_cvt_pk_bf16_f32 v2, v6, v2
	s_andn2_b64 vcc, exec, s[0:1]
	v_cvt_pk_bf16_f32 v3, v3, v4
	v_cvt_pk_bf16_f32 v4, v10, v8
	v_cvt_pk_bf16_f32 v5, v9, v5
	s_mov_b64 s[0:1], -1
	global_store_dwordx4 v[14:15], v[2:5], off offset:256 sc1
	s_branch .LBB0_943

;     __device__ __forceinline__ void operator()(const f32x4 (&acc)[2][2][4][2], const Unit& u, int wr, int wc, int fr, int fq) const {
;     ...
;         } else {
;             const int col0 = u.pn * BM + wc * 32 + 8 * fq;
; #pragma unroll
;             for (int ai = 0; ai < 2; ++ai)
; #pragma unroll
;                 for (int m = 0; m < 4; ++m) {
;                     const size_t row = (size_t)(row0 + ai * HALF + m * 16);
; #pragma unroll
;                     for (int bj = 0; bj < 2; ++bj) {
;                         const int col = col0 + bj * HALF;
;                         f32x4 v0 = acc[ai][bj][m][0], v1 = acc[ai][bj][m][1];
;                         bf16_t* dst = O + row * ldc + col;
;                         if constexpr (MODE == 2) {
; #pragma unroll
;                             for (int e = 0; e < 4; ++e) { v0[e] = sigm(v0[e]); v1[e] = sigm(v1[e]); }
;                         }
;                         if constexpr (MODE == 4) {
;                             const f32x4 b0 = *(const f32x4*)(bias + u.tag * 256 + col), b1 = *(const f32x4*)(bias + u.tag * 256 + col + 4);
; #pragma unroll
;                             for (int e = 0; e < 4; ++e) { v0[e] = gelu_tanh(v0[e] + b0[e]); v1[e] = gelu_tanh(v1[e] + b1[e]); }
;                         }
;                         if constexpr (MODE == 3) {
;                             const u32x4 gv = *(const u32x4*)(G + row * GP + u.tag * 1024 + col);
;                             v0[0] *= bf_lo(gv.x); v0[1] *= bf_hi(gv.x); v0[2] *= bf_lo(gv.y); v0[3] *= bf_hi(gv.y);
;                             v1[0] *= bf_lo(gv.z); v1[1] *= bf_hi(gv.z); v1[2] *= bf_lo(gv.w); v1[3] *= bf_hi(gv.w);
;                             if (u.tag > 0) {
;                                 const u32x4 ov = *(const u32x4*)dst;
;                                 v0[0] += bf_lo(ov.x); v0[1] += bf_hi(ov.x); v0[2] += bf_lo(ov.y); v0[3] += bf_hi(ov.y);
;                                 v1[0] += bf_lo(ov.z); v1[1] += bf_hi(ov.z); v1[2] += bf_lo(ov.w); v1[3] += bf_hi(ov.w);
;                             }
;                         }
;                         *(u32x4*)dst = pack8(v0, v1);
;                     }
; template <class EpiT, class Sched>
; __device__ __forceinline__ void gemm_phase(LAS unsigned char* lds, int tid_in, const GemmDesc g, const Sched& S, const EpiT& E) {
;     ...
;         if (wr == 0) PG8_BAR;
;         E(acc, cur, wr, wc, fr, fq);
.LBB0_1138:
	s_andn2_b64 vcc, exec, s[0:1]
	s_cbranch_vccnz .Lepi_last_10
	v_lshl_add_u32 v144, s24, 8, v140
	v_lshl_or_b32 v146, s80, 8, v142
	v_ashrrev_i32_e32 v145, 31, v144
	v_lshlrev_b64 v[148:149], 11, v[144:145]
	v_ashrrev_i32_e32 v147, 31, v146
	v_lshl_add_u64 v[148:149], s[18:19], 0, v[148:149]
	v_lshlrev_b64 v[146:147], 1, v[146:147]
	v_lshl_add_u64 v[148:149], v[148:149], 0, v[146:147]
	s_mov_b64 s[2:3], 0x40000
	v_cvt_pk_bf16_f32 v70, v70, v71
	v_cvt_pk_bf16_f32 v71, v72, v73
	v_cvt_pk_bf16_f32 v72, v66, v67
	v_lshl_add_u64 v[66:67], v[148:149], 0, s[2:3]
	v_cvt_pk_bf16_f32 v62, v62, v63
	v_cvt_pk_bf16_f32 v63, v64, v65
	v_cvt_pk_bf16_f32 v64, v58, v59
	v_add_co_u32_e32 v58, vcc, s97, v148
	v_cvt_pk_bf16_f32 v46, v46, v47
	v_cvt_pk_bf16_f32 v47, v48, v49
	v_cvt_pk_bf16_f32 v48, v42, v43
	v_cvt_pk_bf16_f32 v49, v44, v45
	s_mov_b64 s[2:3], 0x48000
	v_addc_co_u32_e32 v59, vcc, 0, v149, vcc
	global_store_dwordx4 v[66:67], v[46:49], off offset:256
	v_cvt_pk_bf16_f32 v110, v110, v111
	v_cvt_pk_bf16_f32 v111, v112, v113
	v_lshl_add_u64 v[46:47], v[148:149], 0, s[2:3]
	s_mov_b32 s2, 0x48000
	v_cvt_pk_bf16_f32 v112, v106, v107
	v_or_b32_e32 v106, 16, v144
	v_add_co_u32_e32 v48, vcc, s2, v148
	v_cvt_pk_bf16_f32 v30, v30, v31
	v_cvt_pk_bf16_f32 v31, v32, v33
	v_cvt_pk_bf16_f32 v32, v26, v27
	v_cvt_pk_bf16_f32 v33, v28, v29
	s_mov_b64 s[2:3], 0x50000
	v_ashrrev_i32_e32 v107, 31, v106
	v_cvt_pk_bf16_f32 v94, v94, v95
	v_cvt_pk_bf16_f32 v95, v96, v97
	v_cvt_pk_bf16_f32 v96, v90, v91
	v_or_b32_e32 v90, 32, v144
	v_addc_co_u32_e32 v49, vcc, 0, v149, vcc
	global_store_dwordx4 v[46:47], v[30:33], off offset:256
	v_lshlrev_b64 v[106:107], 11, v[106:107]
	v_ashrrev_i32_e32 v91, 31, v90
	v_lshl_add_u64 v[30:31], v[148:149], 0, s[2:3]
	s_mov_b32 s2, 0x50000
	v_cvt_pk_bf16_f32 v78, v78, v79
	v_cvt_pk_bf16_f32 v79, v80, v81
	v_cvt_pk_bf16_f32 v80, v74, v75
	v_or_b32_e32 v74, 48, v144
	v_add_co_u32_e32 v32, vcc, s2, v148
	v_cvt_pk_bf16_f32 v14, v14, v15
	v_cvt_pk_bf16_f32 v15, v16, v17
	v_cvt_pk_bf16_f32 v16, v10, v11
	v_cvt_pk_bf16_f32 v17, v12, v13
	s_mov_b64 s[2:3], 0x58000
	v_cvt_pk_bf16_f32 v113, v108, v109
	v_lshl_add_u64 v[106:107], s[18:19], 0, v[106:107]
	v_lshlrev_b64 v[90:91], 11, v[90:91]
	v_ashrrev_i32_e32 v75, 31, v74
	v_addc_co_u32_e32 v33, vcc, 0, v149, vcc
	global_store_dwordx4 v[30:31], v[14:17], off offset:256
	global_store_dwordx4 v[148:149], v[110:113], off offset:256
	v_cvt_pk_bf16_f32 v97, v92, v93
	v_lshl_add_u64 v[14:15], v[148:149], 0, s[2:3]
	s_mov_b32 s2, 0x58000
	v_lshl_add_u64 v[110:111], v[106:107], 0, v[146:147]
	v_lshl_add_u64 v[90:91], s[18:19], 0, v[90:91]
	v_lshlrev_b64 v[74:75], 11, v[74:75]
	v_add_co_u32_e32 v16, vcc, s2, v148
	global_store_dwordx4 v[110:111], v[94:97], off offset:256
	v_cvt_pk_bf16_f32 v81, v76, v77
	v_lshl_add_u64 v[74:75], s[18:19], 0, v[74:75]
	v_lshl_add_u64 v[94:95], v[90:91], 0, v[146:147]
	v_addc_co_u32_e32 v17, vcc, 0, v149, vcc
	v_cvt_pk_bf16_f32 v126, v126, v127
	v_cvt_pk_bf16_f32 v127, v128, v129
	v_cvt_pk_bf16_f32 v128, v122, v123
	v_cvt_pk_bf16_f32 v129, v124, v125
	v_cvt_pk_bf16_f32 v106, v118, v119
	v_cvt_pk_bf16_f32 v107, v120, v121
	v_cvt_pk_bf16_f32 v108, v114, v115
	v_cvt_pk_bf16_f32 v109, v116, v117
	v_cvt_pk_bf16_f32 v90, v102, v103
	v_cvt_pk_bf16_f32 v91, v104, v105
	v_cvt_pk_bf16_f32 v92, v98, v99
	v_cvt_pk_bf16_f32 v93, v100, v101
	global_store_dwordx4 v[94:95], v[78:81], off offset:256
	v_cvt_pk_bf16_f32 v76, v82, v83
	v_cvt_pk_bf16_f32 v77, v84, v85
	v_lshl_add_u64 v[78:79], v[74:75], 0, v[146:147]
	v_cvt_pk_bf16_f32 v74, v86, v87
	v_cvt_pk_bf16_f32 v75, v88, v89
	v_cvt_pk_bf16_f32 v73, v68, v69
	v_cvt_pk_bf16_f32 v65, v60, v61
	v_cvt_pk_bf16_f32 v42, v54, v55
	v_cvt_pk_bf16_f32 v43, v56, v57
	v_cvt_pk_bf16_f32 v44, v50, v51
	v_cvt_pk_bf16_f32 v45, v52, v53
	v_cvt_pk_bf16_f32 v26, v38, v39
	v_cvt_pk_bf16_f32 v27, v40, v41
	v_cvt_pk_bf16_f32 v28, v34, v35
	v_cvt_pk_bf16_f32 v29, v36, v37
	v_cvt_pk_bf16_f32 v10, v22, v23
	v_cvt_pk_bf16_f32 v11, v24, v25
	v_cvt_pk_bf16_f32 v12, v18, v19
	v_cvt_pk_bf16_f32 v13, v20, v21
	v_cvt_pk_bf16_f32 v6, v6, v7
	v_cvt_pk_bf16_f32 v7, v8, v9
	v_cvt_pk_bf16_f32 v8, v2, v3
	v_cvt_pk_bf16_f32 v9, v4, v5
	s_andn2_b64 vcc, exec, s[0:1]
	s_mov_b64 s[0:1], -1
	global_store_dwordx4 v[148:149], v[126:129], off
	global_store_dwordx4 v[110:111], v[106:109], off
	global_store_dwordx4 v[94:95], v[90:93], off
	global_store_dwordx4 v[78:79], v[74:77], off
	global_store_dwordx4 v[78:79], v[70:73], off offset:256
	global_store_dwordx4 v[58:59], v[62:65], off
	global_store_dwordx4 v[48:49], v[42:45], off
	global_store_dwordx4 v[32:33], v[26:29], off
	global_store_dwordx4 v[16:17], v[10:13], off
	global_store_dwordx4 v[14:15], v[6:9], off offset:256
	s_cbranch_vccnz .LBB0_1127
	s_andn2_b64 vcc, exec, s[12:13]
	s_cbranch_vccnz .LBB0_1126
	s_barrier
	s_branch .LBB0_1126
;     __device__ __forceinline__ void operator()(const f32x4 (&acc)[2][2][4][2], const Unit& u, int wr, int wc, int fr, int fq) const {
;     ...
;         } else {
;             const int col0 = u.pn * BM + wc * 32 + 8 * fq;
; #pragma unroll
;             for (int ai = 0; ai < 2; ++ai)
; #pragma unroll
;                 for (int m = 0; m < 4; ++m) {
;                     const size_t row = (size_t)(row0 + ai * HALF + m * 16);
; #pragma unroll
;                     for (int bj = 0; bj < 2; ++bj) {
;                         const int col = col0 + bj * HALF;
;                         f32x4 v0 = acc[ai][bj][m][0], v1 = acc[ai][bj][m][1];
;                         bf16_t* dst = O + row * ldc + col;
;                         if constexpr (MODE == 2) {
; #pragma unroll
;                             for (int e = 0; e < 4; ++e) { v0[e] = sigm(v0[e]); v1[e] = sigm(v1[e]); }
;                         }
;                         if constexpr (MODE == 4) {
;                             const f32x4 b0 = *(const f32x4*)(bias + u.tag * 256 + col), b1 = *(const f32x4*)(bias + u.tag * 256 + col + 4);
; #pragma unroll
;                             for (int e = 0; e < 4; ++e) { v0[e] = gelu_tanh(v0[e] + b0[e]); v1[e] = gelu_tanh(v1[e] + b1[e]); }
;                         }
;                         if constexpr (MODE == 3) {
;                             const u32x4 gv = *(const u32x4*)(G + row * GP + u.tag * 1024 + col);
;                             v0[0] *= bf_lo(gv.x); v0[1] *= bf_hi(gv.x); v0[2] *= bf_lo(gv.y); v0[3] *= bf_hi(gv.y);
;                             v1[0] *= bf_lo(gv.z); v1[1] *= bf_hi(gv.z); v1[2] *= bf_lo(gv.w); v1[3] *= bf_hi(gv.w);
;                             if (u.tag > 0) {
;                                 const u32x4 ov = *(const u32x4*)dst;
;                                 v0[0] += bf_lo(ov.x); v0[1] += bf_hi(ov.x); v0[2] += bf_lo(ov.y); v0[3] += bf_hi(ov.y);
;                                 v1[0] += bf_lo(ov.z); v1[1] += bf_hi(ov.z); v1[2] += bf_lo(ov.w); v1[3] += bf_hi(ov.w);
;                             }
;                         }
;                         *(u32x4*)dst = pack8(v0, v1);
;                     }
; template <class EpiT, class Sched>
; __device__ __forceinline__ void gemm_phase(LAS unsigned char* lds, int tid_in, const GemmDesc g, const Sched& S, const EpiT& E) {
;     ...
;         if (wr == 0) PG8_BAR;
;         E(acc, cur, wr, wc, fr, fq);
.Lepi_last_10:
	v_lshl_add_u32 v144, s24, 8, v140
	v_lshl_or_b32 v146, s80, 8, v142
	v_ashrrev_i32_e32 v145, 31, v144
	v_lshlrev_b64 v[148:149], 11, v[144:145]
	v_ashrrev_i32_e32 v147, 31, v146
	v_lshl_add_u64 v[148:149], s[18:19], 0, v[148:149]
	v_lshlrev_b64 v[146:147], 1, v[146:147]
	v_lshl_add_u64 v[148:149], v[148:149], 0, v[146:147]
	s_mov_b64 s[2:3], 0x40000
	v_cvt_pk_bf16_f32 v70, v70, v71
	v_cvt_pk_bf16_f32 v71, v72, v73
	v_cvt_pk_bf16_f32 v72, v66, v67
	v_lshl_add_u64 v[66:67], v[148:149], 0, s[2:3]
	v_cvt_pk_bf16_f32 v62, v62, v63
	v_cvt_pk_bf16_f32 v63, v64, v65
	v_cvt_pk_bf16_f32 v64, v58, v59
	v_add_co_u32_e32 v58, vcc, s97, v148
	v_cvt_pk_bf16_f32 v46, v46, v47
	v_cvt_pk_bf16_f32 v47, v48, v49
	v_cvt_pk_bf16_f32 v48, v42, v43
	v_cvt_pk_bf16_f32 v49, v44, v45
	s_mov_b64 s[2:3], 0x48000
	v_addc_co_u32_e32 v59, vcc, 0, v149, vcc
	global_store_dwordx4 v[66:67], v[46:49], off offset:256 sc1
	v_cvt_pk_bf16_f32 v110, v110, v111
	v_cvt_pk_bf16_f32 v111, v112, v113
	v_lshl_add_u64 v[46:47], v[148:149], 0, s[2:3]
	s_mov_b32 s2, 0x48000
	v_cvt_pk_bf16_f32 v112, v106, v107
	v_or_b32_e32 v106, 16, v144
	v_add_co_u32_e32 v48, vcc, s2, v148
	v_cvt_pk_bf16_f32 v30, v30, v31
	v_cvt_pk_bf16_f32 v31, v32, v33
	v_cvt_pk_bf16_f32 v32, v26, v27
	v_cvt_pk_bf16_f32 v33, v28, v29
	s_mov_b64 s[2:3], 0x50000
	v_ashrrev_i32_e32 v107, 31, v106
	v_cvt_pk_bf16_f32 v94, v94, v95
	v_cvt_pk_bf16_f32 v95, v96, v97
	v_cvt_pk_bf16_f32 v96, v90, v91
	v_or_b32_e32 v90, 32, v144
	v_addc_co_u32_e32 v49, vcc, 0, v149, vcc
	global_store_dwordx4 v[46:47], v[30:33], off offset:256 sc1
	v_lshlrev_b64 v[106:107], 11, v[106:107]
	v_ashrrev_i32_e32 v91, 31, v90
	v_lshl_add_u64 v[30:31], v[148:149], 0, s[2:3]
	s_mov_b32 s2, 0x50000
	v_cvt_pk_bf16_f32 v78, v78, v79
	v_cvt_pk_bf16_f32 v79, v80, v81
	v_cvt_pk_bf16_f32 v80, v74, v75
	v_or_b32_e32 v74, 48, v144
	v_add_co_u32_e32 v32, vcc, s2, v148
	v_cvt_pk_bf16_f32 v14, v14, v15
	v_cvt_pk_bf16_f32 v15, v16, v17
	v_cvt_pk_bf16_f32 v16, v10, v11
	v_cvt_pk_bf16_f32 v17, v12, v13
	s_mov_b64 s[2:3], 0x58000
	v_cvt_pk_bf16_f32 v113, v108, v109
	v_lshl_add_u64 v[106:107], s[18:19], 0, v[106:107]
	v_lshlrev_b64 v[90:91], 11, v[90:91]
	v_ashrrev_i32_e32 v75, 31, v74
	v_addc_co_u32_e32 v33, vcc, 0, v149, vcc
	global_store_dwordx4 v[30:31], v[14:17], off offset:256 sc1
	global_store_dwordx4 v[148:149], v[110:113], off offset:256 sc1
	v_cvt_pk_bf16_f32 v97, v92, v93
	v_lshl_add_u64 v[14:15], v[148:149], 0, s[2:3]
	s_mov_b32 s2, 0x58000
	v_lshl_add_u64 v[110:111], v[106:107], 0, v[146:147]
	v_lshl_add_u64 v[90:91], s[18:19], 0, v[90:91]
	v_lshlrev_b64 v[74:75], 11, v[74:75]
	v_add_co_u32_e32 v16, vcc, s2, v148
	global_store_dwordx4 v[110:111], v[94:97], off offset:256 sc1
	v_cvt_pk_bf16_f32 v81, v76, v77
	v_lshl_add_u64 v[74:75], s[18:19], 0, v[74:75]
	v_lshl_add_u64 v[94:95], v[90:91], 0, v[146:147]
	v_addc_co_u32_e32 v17, vcc, 0, v149, vcc
	v_cvt_pk_bf16_f32 v126, v126, v127
	v_cvt_pk_bf16_f32 v127, v128, v129
	v_cvt_pk_bf16_f32 v128, v122, v123
	v_cvt_pk_bf16_f32 v129, v124, v125
	v_cvt_pk_bf16_f32 v106, v118, v119
	v_cvt_pk_bf16_f32 v107, v120, v121
	v_cvt_pk_bf16_f32 v108, v114, v115
	v_cvt_pk_bf16_f32 v109, v116, v117
	v_cvt_pk_bf16_f32 v90, v102, v103
	v_cvt_pk_bf16_f32 v91, v104, v105
	v_cvt_pk_bf16_f32 v92, v98, v99
	v_cvt_pk_bf16_f32 v93, v100, v101
	global_store_dwordx4 v[94:95], v[78:81], off offset:256 sc1
	v_cvt_pk_bf16_f32 v76, v82, v83
	v_cvt_pk_bf16_f32 v77, v84, v85
	v_lshl_add_u64 v[78:79], v[74:75], 0, v[146:147]
	v_cvt_pk_bf16_f32 v74, v86, v87
	v_cvt_pk_bf16_f32 v75, v88, v89
	v_cvt_pk_bf16_f32 v73, v68, v69
	v_cvt_pk_bf16_f32 v65, v60, v61
	v_cvt_pk_bf16_f32 v42, v54, v55
	v_cvt_pk_bf16_f32 v43, v56, v57
	v_cvt_pk_bf16_f32 v44, v50, v51
	v_cvt_pk_bf16_f32 v45, v52, v53
	v_cvt_pk_bf16_f32 v26, v38, v39
	v_cvt_pk_bf16_f32 v27, v40, v41
	v_cvt_pk_bf16_f32 v28, v34, v35
	v_cvt_pk_bf16_f32 v29, v36, v37
	v_cvt_pk_bf16_f32 v10, v22, v23
	v_cvt_pk_bf16_f32 v11, v24, v25
	v_cvt_pk_bf16_f32 v12, v18, v19
	v_cvt_pk_bf16_f32 v13, v20, v21
	v_cvt_pk_bf16_f32 v6, v6, v7
	v_cvt_pk_bf16_f32 v7, v8, v9
	v_cvt_pk_bf16_f32 v8, v2, v3
	v_cvt_pk_bf16_f32 v9, v4, v5
	s_andn2_b64 vcc, exec, s[0:1]
	s_mov_b64 s[0:1], -1
	global_store_dwordx4 v[148:149], v[126:129], off sc1
	global_store_dwordx4 v[110:111], v[106:109], off sc1
	global_store_dwordx4 v[94:95], v[90:93], off sc1
	global_store_dwordx4 v[78:79], v[74:77], off sc1
	global_store_dwordx4 v[78:79], v[70:73], off offset:256 sc1
	global_store_dwordx4 v[58:59], v[62:65], off sc1
	global_store_dwordx4 v[48:49], v[42:45], off sc1
	global_store_dwordx4 v[32:33], v[26:29], off sc1
	global_store_dwordx4 v[16:17], v[10:13], off sc1
	global_store_dwordx4 v[14:15], v[6:9], off offset:256 sc1
	s_branch .LBB0_1127

; __device__ __forceinline__ float sigm(float x) { return rcpf_(1.f + ex2(-1.44269504f * x)); }
; __device__ __forceinline__ u32x4 pack8(f32x4 a, f32x4 b) { u32x4 w; w.x = cvt_pk_bf16(a[0], a[1]); w.y = cvt_pk_bf16(a[2], a[3]); w.z = cvt_pk_bf16(b[0], b[1]); w.w = cvt_pk_bf16(b[2], b[3]); return w; }
;     __device__ __forceinline__ void operator()(const f32x4 (&acc)[2][2][4][2], const Unit& u, int wr, int wc, int fr, int fq) const {
;     ...
;         if constexpr (MODE == 1) {
;             const int col0 = u.pn * 128 + wc * 32 + 8 * fq;
; #pragma unroll
;             for (int ai = 0; ai < 2; ++ai)
; #pragma unroll
;                 for (int m = 0; m < 4; ++m) {
;                     bf16_t* rowp = O + (size_t)(row0 + ai * HALF + m * 16) * ldc + col0;
;                     f32x4 v0, v1;
; #pragma unroll
;                     for (int e = 0; e < 4; ++e) { const float a0 = acc[ai][0][m][0][e], a1 = acc[ai][0][m][1][e]; v0[e] = a0 * sigm(a0) * acc[ai][1][m][0][e]; v1[e] = a1 * sigm(a1) * acc[ai][1][m][1][e]; }
;                     *(u32x4*)rowp = pack8(v0, v1);
;                     __builtin_amdgcn_sched_barrier(0);
;                 }
.LBB0_1267:
	s_andn2_b64 vcc, exec, s[0:1]
	s_cbranch_vccnz .Lepi_last_12
	v_mul_f32_e32 v147, 0xbfb8aa3b, v126
	v_exp_f32_e32 v147, v147
	v_lshl_or_b32 v148, s58, 7, v144
	v_lshl_add_u32 v146, s88, 8, v142
	v_ashrrev_i32_e32 v149, 31, v148
	v_add_f32_e32 v147, 1.0, v147
	v_rcp_f32_e32 v152, v147
	v_mul_f32_e32 v147, 0xbfb8aa3b, v118
	v_exp_f32_e32 v147, v147
	v_mov_b64_e32 v[140:141], s[24:25]
	v_mad_i64_i32 v[150:151], s[2:3], v146, s52, v[140:141]
	v_add_f32_e32 v147, 1.0, v147
	v_rcp_f32_e32 v154, v147
	v_mul_f32_e32 v147, 0xbfb8aa3b, v127
	v_exp_f32_e32 v147, v147
	s_nop 0
	v_add_f32_e32 v147, 1.0, v147
	v_rcp_f32_e32 v153, v147
	s_nop 0
	v_pk_mul_f32 v[126:127], v[126:127], v[152:153]
	s_nop 0
	v_pk_mul_f32 v[122:123], v[126:127], v[122:123]
	v_mul_f32_e32 v126, 0xbfb8aa3b, v119
	v_exp_f32_e32 v126, v126
	s_nop 0
	v_add_f32_e32 v126, 1.0, v126
	v_rcp_f32_e32 v155, v126
	s_nop 0
	v_pk_mul_f32 v[118:119], v[118:119], v[154:155]
	s_nop 0
	v_pk_mul_f32 v[118:119], v[118:119], v[114:115]
	v_mul_f32_e32 v115, 0xbfb8aa3b, v120
	v_exp_f32_e32 v115, v115
	v_mul_f32_e32 v114, 0xbfb8aa3b, v128
	v_exp_f32_e32 v114, v114
	v_cvt_pk_bf16_f32 v118, v118, v119
	v_add_f32_e32 v115, 1.0, v115
	v_rcp_f32_e32 v126, v115
	v_mul_f32_e32 v115, 0xbfb8aa3b, v129
	v_exp_f32_e32 v115, v115
	v_add_f32_e32 v114, 1.0, v114
	v_rcp_f32_e32 v114, v114
	v_add_f32_e32 v115, 1.0, v115
	v_rcp_f32_e32 v115, v115
	s_nop 0
	v_pk_mul_f32 v[114:115], v[128:129], v[114:115]
	s_nop 0
	v_pk_mul_f32 v[124:125], v[114:115], v[124:125]
	v_mul_f32_e32 v114, 0xbfb8aa3b, v121
	v_exp_f32_e32 v114, v114
	s_nop 0
	v_add_f32_e32 v114, 1.0, v114
	v_rcp_f32_e32 v127, v114
	s_nop 0
	v_pk_mul_f32 v[114:115], v[120:121], v[126:127]
	s_nop 0
	v_pk_mul_f32 v[120:121], v[114:115], v[116:117]
	v_lshlrev_b64 v[114:115], 1, v[148:149]
	v_lshl_add_u64 v[126:127], v[150:151], 0, v[114:115]
	v_cvt_pk_bf16_f32 v116, v122, v123
	v_cvt_pk_bf16_f32 v117, v124, v125
	v_cvt_pk_bf16_f32 v119, v120, v121
	global_store_dwordx4 v[126:127], v[116:119], off
	s_nop 1
	v_mul_f32_e32 v119, 0xbfb8aa3b, v102
	v_exp_f32_e32 v119, v119
	v_mul_f32_e32 v118, 0xbfb8aa3b, v110
	v_exp_f32_e32 v118, v118
	v_or_b32_e32 v116, 16, v146
	v_add_f32_e32 v119, 1.0, v119
	v_rcp_f32_e32 v120, v119
	v_mul_f32_e32 v119, 0xbfb8aa3b, v111
	v_exp_f32_e32 v119, v119
	v_add_f32_e32 v118, 1.0, v118
	v_rcp_f32_e32 v118, v118
	v_mad_i64_i32 v[116:117], s[2:3], v116, s52, v[140:141]
	v_add_f32_e32 v119, 1.0, v119
	v_rcp_f32_e32 v119, v119
	s_nop 0
	v_pk_mul_f32 v[110:111], v[110:111], v[118:119]
	s_nop 0
	v_pk_mul_f32 v[106:107], v[110:111], v[106:107]
	v_mul_f32_e32 v110, 0xbfb8aa3b, v103
	v_exp_f32_e32 v110, v110
	s_nop 0
	v_add_f32_e32 v110, 1.0, v110
	v_rcp_f32_e32 v121, v110
	s_nop 0
	v_pk_mul_f32 v[102:103], v[102:103], v[120:121]
	s_nop 0
	v_pk_mul_f32 v[102:103], v[102:103], v[98:99]
	v_mul_f32_e32 v99, 0xbfb8aa3b, v104
	v_exp_f32_e32 v99, v99
	v_mul_f32_e32 v98, 0xbfb8aa3b, v112
	v_exp_f32_e32 v98, v98
	v_add_f32_e32 v99, 1.0, v99
	v_rcp_f32_e32 v110, v99
	v_mul_f32_e32 v99, 0xbfb8aa3b, v113
	v_exp_f32_e32 v99, v99
	v_add_f32_e32 v98, 1.0, v98
	v_rcp_f32_e32 v98, v98
	v_add_f32_e32 v99, 1.0, v99
	v_rcp_f32_e32 v99, v99
	s_nop 0
	v_pk_mul_f32 v[98:99], v[112:113], v[98:99]
	s_nop 0
	v_pk_mul_f32 v[108:109], v[98:99], v[108:109]
	v_mul_f32_e32 v98, 0xbfb8aa3b, v105
	v_exp_f32_e32 v98, v98
	s_nop 0
	v_add_f32_e32 v98, 1.0, v98
	v_rcp_f32_e32 v111, v98
	s_nop 0
	v_pk_mul_f32 v[98:99], v[104:105], v[110:111]
	s_nop 0
	v_pk_mul_f32 v[104:105], v[98:99], v[100:101]
	v_lshl_add_u64 v[110:111], v[116:117], 0, v[114:115]
	v_cvt_pk_bf16_f32 v98, v106, v107
	v_cvt_pk_bf16_f32 v99, v108, v109
	v_cvt_pk_bf16_f32 v100, v102, v103
	v_cvt_pk_bf16_f32 v101, v104, v105
	global_store_dwordx4 v[110:111], v[98:101], off
	s_nop 1
	v_mul_f32_e32 v101, 0xbfb8aa3b, v86
	v_exp_f32_e32 v101, v101
	v_mul_f32_e32 v100, 0xbfb8aa3b, v94
	v_exp_f32_e32 v100, v100
	v_or_b32_e32 v98, 32, v146
	v_add_f32_e32 v101, 1.0, v101
	v_rcp_f32_e32 v102, v101
	v_mul_f32_e32 v101, 0xbfb8aa3b, v95
	v_exp_f32_e32 v101, v101
	v_add_f32_e32 v100, 1.0, v100
	v_rcp_f32_e32 v100, v100
	v_mad_i64_i32 v[98:99], s[2:3], v98, s52, v[140:141]
	v_add_f32_e32 v101, 1.0, v101
	v_rcp_f32_e32 v101, v101
	s_nop 0
	v_pk_mul_f32 v[94:95], v[94:95], v[100:101]
	s_nop 0
	v_pk_mul_f32 v[90:91], v[94:95], v[90:91]
	v_mul_f32_e32 v94, 0xbfb8aa3b, v87
	v_exp_f32_e32 v94, v94
	s_nop 0
	v_add_f32_e32 v94, 1.0, v94
	v_rcp_f32_e32 v103, v94
	s_nop 0
	v_pk_mul_f32 v[86:87], v[86:87], v[102:103]
	s_nop 0
	v_pk_mul_f32 v[86:87], v[86:87], v[82:83]
	v_mul_f32_e32 v83, 0xbfb8aa3b, v88
	v_exp_f32_e32 v83, v83
	v_mul_f32_e32 v82, 0xbfb8aa3b, v96
	v_exp_f32_e32 v82, v82
	v_add_f32_e32 v83, 1.0, v83
	v_rcp_f32_e32 v94, v83
	v_mul_f32_e32 v83, 0xbfb8aa3b, v97
	v_exp_f32_e32 v83, v83
	v_add_f32_e32 v82, 1.0, v82
	v_rcp_f32_e32 v82, v82
	v_add_f32_e32 v83, 1.0, v83
	v_rcp_f32_e32 v83, v83
	s_nop 0
	v_pk_mul_f32 v[82:83], v[96:97], v[82:83]
	s_nop 0
	v_pk_mul_f32 v[92:93], v[82:83], v[92:93]
	v_mul_f32_e32 v82, 0xbfb8aa3b, v89
	v_exp_f32_e32 v82, v82
	s_nop 0
	v_add_f32_e32 v82, 1.0, v82
	v_rcp_f32_e32 v95, v82
	s_nop 0
	v_pk_mul_f32 v[82:83], v[88:89], v[94:95]
	s_nop 0
	v_pk_mul_f32 v[88:89], v[82:83], v[84:85]
	v_lshl_add_u64 v[94:95], v[98:99], 0, v[114:115]
	v_cvt_pk_bf16_f32 v82, v90, v91
	v_cvt_pk_bf16_f32 v83, v92, v93
	v_cvt_pk_bf16_f32 v84, v86, v87
	v_cvt_pk_bf16_f32 v85, v88, v89
	global_store_dwordx4 v[94:95], v[82:85], off
	s_nop 1
	v_mul_f32_e32 v85, 0xbfb8aa3b, v70
	v_exp_f32_e32 v85, v85
	v_mul_f32_e32 v84, 0xbfb8aa3b, v78
	v_exp_f32_e32 v84, v84
	v_or_b32_e32 v82, 48, v146
	v_add_f32_e32 v85, 1.0, v85
; __device__ __forceinline__ float sigm(float x) { return rcpf_(1.f + ex2(-1.44269504f * x)); }
; __device__ __forceinline__ u32x4 pack8(f32x4 a, f32x4 b) { u32x4 w; w.x = cvt_pk_bf16(a[0], a[1]); w.y = cvt_pk_bf16(a[2], a[3]); w.z = cvt_pk_bf16(b[0], b[1]); w.w = cvt_pk_bf16(b[2], b[3]); return w; }
;     __device__ __forceinline__ void operator()(const f32x4 (&acc)[2][2][4][2], const Unit& u, int wr, int wc, int fr, int fq) const {
;     ...
;         if constexpr (MODE == 1) {
;             const int col0 = u.pn * 128 + wc * 32 + 8 * fq;
; #pragma unroll
;             for (int ai = 0; ai < 2; ++ai)
; #pragma unroll
;                 for (int m = 0; m < 4; ++m) {
;                     bf16_t* rowp = O + (size_t)(row0 + ai * HALF + m * 16) * ldc + col0;
;                     f32x4 v0, v1;
; #pragma unroll
;                     for (int e = 0; e < 4; ++e) { const float a0 = acc[ai][0][m][0][e], a1 = acc[ai][0][m][1][e]; v0[e] = a0 * sigm(a0) * acc[ai][1][m][0][e]; v1[e] = a1 * sigm(a1) * acc[ai][1][m][1][e]; }
;                     *(u32x4*)rowp = pack8(v0, v1);
;                     __builtin_amdgcn_sched_barrier(0);
;                 }
	v_rcp_f32_e32 v86, v85
	v_mul_f32_e32 v85, 0xbfb8aa3b, v79
	v_exp_f32_e32 v85, v85
	v_add_f32_e32 v84, 1.0, v84
	v_rcp_f32_e32 v84, v84
	v_mad_i64_i32 v[82:83], s[2:3], v82, s52, v[140:141]
	v_add_f32_e32 v85, 1.0, v85
	v_rcp_f32_e32 v85, v85
	s_nop 0
	v_pk_mul_f32 v[78:79], v[78:79], v[84:85]
	s_nop 0
	v_pk_mul_f32 v[74:75], v[78:79], v[74:75]
	v_mul_f32_e32 v78, 0xbfb8aa3b, v71
	v_exp_f32_e32 v78, v78
	s_nop 0
	v_add_f32_e32 v78, 1.0, v78
	v_rcp_f32_e32 v87, v78
	s_nop 0
	v_pk_mul_f32 v[70:71], v[70:71], v[86:87]
	s_nop 0
	v_pk_mul_f32 v[70:71], v[70:71], v[66:67]
	v_mul_f32_e32 v67, 0xbfb8aa3b, v72
	v_exp_f32_e32 v67, v67
	v_mul_f32_e32 v66, 0xbfb8aa3b, v80
	v_exp_f32_e32 v66, v66
	v_add_f32_e32 v67, 1.0, v67
	v_rcp_f32_e32 v78, v67
	v_mul_f32_e32 v67, 0xbfb8aa3b, v81
	v_exp_f32_e32 v67, v67
	v_add_f32_e32 v66, 1.0, v66
	v_rcp_f32_e32 v66, v66
	v_add_f32_e32 v67, 1.0, v67
	v_rcp_f32_e32 v67, v67
	s_nop 0
	v_pk_mul_f32 v[66:67], v[80:81], v[66:67]
	s_nop 0
	v_pk_mul_f32 v[76:77], v[66:67], v[76:77]
	v_mul_f32_e32 v66, 0xbfb8aa3b, v73
	v_exp_f32_e32 v66, v66
	s_nop 0
	v_add_f32_e32 v66, 1.0, v66
	v_rcp_f32_e32 v79, v66
	s_nop 0
	v_pk_mul_f32 v[66:67], v[72:73], v[78:79]
	s_nop 0
	v_pk_mul_f32 v[72:73], v[66:67], v[68:69]
	v_lshl_add_u64 v[78:79], v[82:83], 0, v[114:115]
	v_cvt_pk_bf16_f32 v66, v74, v75
	v_cvt_pk_bf16_f32 v67, v76, v77
	v_cvt_pk_bf16_f32 v68, v70, v71
	v_cvt_pk_bf16_f32 v69, v72, v73
	global_store_dwordx4 v[78:79], v[66:69], off
	s_nop 1
	v_mul_f32_e32 v69, 0xbfb8aa3b, v54
	v_exp_f32_e32 v69, v69
	v_mul_f32_e32 v68, 0xbfb8aa3b, v62
	v_exp_f32_e32 v68, v68
	v_add_u32_e32 v66, 0x80, v146
	v_add_f32_e32 v69, 1.0, v69
	v_rcp_f32_e32 v70, v69
	v_mul_f32_e32 v69, 0xbfb8aa3b, v63
	v_exp_f32_e32 v69, v69
	v_add_f32_e32 v68, 1.0, v68
	v_rcp_f32_e32 v68, v68
	v_mad_i64_i32 v[66:67], s[2:3], v66, s52, v[140:141]
	v_add_f32_e32 v69, 1.0, v69
	v_rcp_f32_e32 v69, v69
	s_nop 0
	v_pk_mul_f32 v[62:63], v[62:63], v[68:69]
	s_nop 0
	v_pk_mul_f32 v[58:59], v[62:63], v[58:59]
	v_mul_f32_e32 v62, 0xbfb8aa3b, v55
	v_exp_f32_e32 v62, v62
	s_nop 0
	v_add_f32_e32 v62, 1.0, v62
	v_rcp_f32_e32 v71, v62
	s_nop 0
	v_pk_mul_f32 v[54:55], v[54:55], v[70:71]
	s_nop 0
	v_pk_mul_f32 v[54:55], v[54:55], v[50:51]
	v_mul_f32_e32 v51, 0xbfb8aa3b, v56
	v_exp_f32_e32 v51, v51
	v_mul_f32_e32 v50, 0xbfb8aa3b, v64
	v_exp_f32_e32 v50, v50
	v_add_f32_e32 v51, 1.0, v51
	v_rcp_f32_e32 v62, v51
	v_mul_f32_e32 v51, 0xbfb8aa3b, v65
	v_exp_f32_e32 v51, v51
	v_add_f32_e32 v50, 1.0, v50
	v_rcp_f32_e32 v50, v50
	v_add_f32_e32 v51, 1.0, v51
	v_rcp_f32_e32 v51, v51
	s_nop 0
	v_pk_mul_f32 v[50:51], v[64:65], v[50:51]
	s_nop 0
	v_pk_mul_f32 v[60:61], v[50:51], v[60:61]
	v_mul_f32_e32 v50, 0xbfb8aa3b, v57
	v_exp_f32_e32 v50, v50
	s_nop 0
	v_add_f32_e32 v50, 1.0, v50
	v_rcp_f32_e32 v63, v50
	s_nop 0
	v_pk_mul_f32 v[50:51], v[56:57], v[62:63]
	s_nop 0
	v_pk_mul_f32 v[56:57], v[50:51], v[52:53]
	v_lshl_add_u64 v[62:63], v[66:67], 0, v[114:115]
	v_cvt_pk_bf16_f32 v50, v58, v59
	v_cvt_pk_bf16_f32 v51, v60, v61
	v_cvt_pk_bf16_f32 v52, v54, v55
	v_cvt_pk_bf16_f32 v53, v56, v57
	global_store_dwordx4 v[62:63], v[50:53], off
	s_nop 1
	v_mul_f32_e32 v53, 0xbfb8aa3b, v38
	v_exp_f32_e32 v53, v53
	v_mul_f32_e32 v52, 0xbfb8aa3b, v46
	v_exp_f32_e32 v52, v52
	v_add_u32_e32 v50, 0x90, v146
	v_add_f32_e32 v53, 1.0, v53
	v_rcp_f32_e32 v54, v53
	v_mul_f32_e32 v53, 0xbfb8aa3b, v47
	v_exp_f32_e32 v53, v53
	v_add_f32_e32 v52, 1.0, v52
	v_rcp_f32_e32 v52, v52
	v_mad_i64_i32 v[50:51], s[2:3], v50, s52, v[140:141]
	v_add_f32_e32 v53, 1.0, v53
	v_rcp_f32_e32 v53, v53
	s_nop 0
	v_pk_mul_f32 v[46:47], v[46:47], v[52:53]
	s_nop 0
	v_pk_mul_f32 v[42:43], v[46:47], v[42:43]
	v_mul_f32_e32 v46, 0xbfb8aa3b, v39
	v_exp_f32_e32 v46, v46
	s_nop 0
	v_add_f32_e32 v46, 1.0, v46
	v_rcp_f32_e32 v55, v46
	s_nop 0
	v_pk_mul_f32 v[38:39], v[38:39], v[54:55]
	s_nop 0
	v_pk_mul_f32 v[38:39], v[38:39], v[34:35]
	v_mul_f32_e32 v35, 0xbfb8aa3b, v40
	v_exp_f32_e32 v35, v35
	v_mul_f32_e32 v34, 0xbfb8aa3b, v48
	v_exp_f32_e32 v34, v34
	v_add_f32_e32 v35, 1.0, v35
	v_rcp_f32_e32 v46, v35
	v_mul_f32_e32 v35, 0xbfb8aa3b, v49
	v_exp_f32_e32 v35, v35
	v_add_f32_e32 v34, 1.0, v34
	v_rcp_f32_e32 v34, v34
	v_add_f32_e32 v35, 1.0, v35
	v_rcp_f32_e32 v35, v35
	s_nop 0
	v_pk_mul_f32 v[34:35], v[48:49], v[34:35]
	s_nop 0
	v_pk_mul_f32 v[44:45], v[34:35], v[44:45]
	v_mul_f32_e32 v34, 0xbfb8aa3b, v41
	v_exp_f32_e32 v34, v34
	s_nop 0
	v_add_f32_e32 v34, 1.0, v34
	v_rcp_f32_e32 v47, v34
	s_nop 0
	v_pk_mul_f32 v[34:35], v[40:41], v[46:47]
	s_nop 0
	v_pk_mul_f32 v[40:41], v[34:35], v[36:37]
	v_lshl_add_u64 v[46:47], v[50:51], 0, v[114:115]
	v_cvt_pk_bf16_f32 v34, v42, v43
	v_cvt_pk_bf16_f32 v35, v44, v45
	v_cvt_pk_bf16_f32 v36, v38, v39
	v_cvt_pk_bf16_f32 v37, v40, v41
	global_store_dwordx4 v[46:47], v[34:37], off
	s_nop 1
	v_mul_f32_e32 v37, 0xbfb8aa3b, v22
	v_exp_f32_e32 v37, v37
	v_mul_f32_e32 v36, 0xbfb8aa3b, v30
	v_exp_f32_e32 v36, v36
	v_add_u32_e32 v34, 0xa0, v146
	v_add_f32_e32 v37, 1.0, v37
	v_rcp_f32_e32 v38, v37
	v_mul_f32_e32 v37, 0xbfb8aa3b, v31
	v_exp_f32_e32 v37, v37
	v_add_f32_e32 v36, 1.0, v36
	v_rcp_f32_e32 v36, v36
	v_mad_i64_i32 v[34:35], s[2:3], v34, s52, v[140:141]
	v_add_f32_e32 v37, 1.0, v37
	v_rcp_f32_e32 v37, v37
	s_nop 0
	v_pk_mul_f32 v[30:31], v[30:31], v[36:37]
	s_nop 0
	v_pk_mul_f32 v[26:27], v[30:31], v[26:27]
	v_mul_f32_e32 v30, 0xbfb8aa3b, v23
	v_exp_f32_e32 v30, v30
	s_nop 0
	v_add_f32_e32 v30, 1.0, v30
	v_rcp_f32_e32 v39, v30
	s_nop 0
	v_pk_mul_f32 v[22:23], v[22:23], v[38:39]
	s_nop 0
	v_pk_mul_f32 v[22:23], v[22:23], v[18:19]
	v_mul_f32_e32 v19, 0xbfb8aa3b, v24
	v_exp_f32_e32 v19, v19
	v_mul_f32_e32 v18, 0xbfb8aa3b, v32
; __device__ __forceinline__ float sigm(float x) { return rcpf_(1.f + ex2(-1.44269504f * x)); }
; __device__ __forceinline__ u32x4 pack8(f32x4 a, f32x4 b) { u32x4 w; w.x = cvt_pk_bf16(a[0], a[1]); w.y = cvt_pk_bf16(a[2], a[3]); w.z = cvt_pk_bf16(b[0], b[1]); w.w = cvt_pk_bf16(b[2], b[3]); return w; }
; #define PG8_BAR __builtin_amdgcn_s_barrier()
;     __device__ __forceinline__ void operator()(const f32x4 (&acc)[2][2][4][2], const Unit& u, int wr, int wc, int fr, int fq) const {
;     ...
;         if constexpr (MODE == 1) {
;             const int col0 = u.pn * 128 + wc * 32 + 8 * fq;
; #pragma unroll
;             for (int ai = 0; ai < 2; ++ai)
; #pragma unroll
;                 for (int m = 0; m < 4; ++m) {
;                     bf16_t* rowp = O + (size_t)(row0 + ai * HALF + m * 16) * ldc + col0;
;                     f32x4 v0, v1;
; #pragma unroll
;                     for (int e = 0; e < 4; ++e) { const float a0 = acc[ai][0][m][0][e], a1 = acc[ai][0][m][1][e]; v0[e] = a0 * sigm(a0) * acc[ai][1][m][0][e]; v1[e] = a1 * sigm(a1) * acc[ai][1][m][1][e]; }
;                     *(u32x4*)rowp = pack8(v0, v1);
;                     __builtin_amdgcn_sched_barrier(0);
;                 }
; template <class EpiT, class Sched>
; __device__ __forceinline__ void gemm_phase(LAS unsigned char* lds, int tid_in, const GemmDesc g, const Sched& S, const EpiT& E) {
;     ...
;         if (wr == 0) PG8_BAR;
;         E(acc, cur, wr, wc, fr, fq);
;         if (!has_next) break;
; #pragma unroll
;         for (int a = 0; a < 2; ++a)
; #pragma unroll
;             for (int b = 0; b < 2; ++b)
; #pragma unroll
;                 for (int m = 0; m < 4; ++m)
; #pragma unroll
;                     for (int n = 0; n < 2; ++n) acc[a][b][m][n] = (f32x4){0.f, 0.f, 0.f, 0.f};
;         cur = nxt; cA = nA; cB = nB; ++ui;
;         if (wr == 1) PG8_BAR;
	v_exp_f32_e32 v18, v18
	v_add_f32_e32 v19, 1.0, v19
	v_rcp_f32_e32 v30, v19
	v_mul_f32_e32 v19, 0xbfb8aa3b, v33
	v_exp_f32_e32 v19, v19
	v_add_f32_e32 v18, 1.0, v18
	v_rcp_f32_e32 v18, v18
	v_add_f32_e32 v19, 1.0, v19
	v_rcp_f32_e32 v19, v19
	s_nop 0
	v_pk_mul_f32 v[18:19], v[32:33], v[18:19]
	s_nop 0
	v_pk_mul_f32 v[28:29], v[18:19], v[28:29]
	v_mul_f32_e32 v18, 0xbfb8aa3b, v25
	v_exp_f32_e32 v18, v18
	s_nop 0
	v_add_f32_e32 v18, 1.0, v18
	v_rcp_f32_e32 v31, v18
	s_nop 0
	v_pk_mul_f32 v[18:19], v[24:25], v[30:31]
	s_nop 0
	v_pk_mul_f32 v[24:25], v[18:19], v[20:21]
	v_lshl_add_u64 v[30:31], v[34:35], 0, v[114:115]
	v_cvt_pk_bf16_f32 v18, v26, v27
	v_cvt_pk_bf16_f32 v19, v28, v29
	v_cvt_pk_bf16_f32 v20, v22, v23
	v_cvt_pk_bf16_f32 v21, v24, v25
	global_store_dwordx4 v[30:31], v[18:21], off
	s_nop 1
	v_mul_f32_e32 v21, 0xbfb8aa3b, v6
	v_exp_f32_e32 v21, v21
	v_mul_f32_e32 v20, 0xbfb8aa3b, v14
	v_exp_f32_e32 v20, v20
	v_add_u32_e32 v18, 0xb0, v146
	v_add_f32_e32 v21, 1.0, v21
	v_rcp_f32_e32 v22, v21
	v_mul_f32_e32 v21, 0xbfb8aa3b, v15
	v_exp_f32_e32 v21, v21
	v_add_f32_e32 v20, 1.0, v20
	v_rcp_f32_e32 v20, v20
	v_mad_i64_i32 v[18:19], s[2:3], v18, s52, v[140:141]
	v_add_f32_e32 v21, 1.0, v21
	v_rcp_f32_e32 v21, v21
	s_nop 0
	v_pk_mul_f32 v[14:15], v[14:15], v[20:21]
	s_nop 0
	v_pk_mul_f32 v[10:11], v[14:15], v[10:11]
	v_mul_f32_e32 v14, 0xbfb8aa3b, v7
	v_exp_f32_e32 v14, v14
	s_nop 0
	v_add_f32_e32 v14, 1.0, v14
	v_rcp_f32_e32 v23, v14
	s_nop 0
	v_pk_mul_f32 v[6:7], v[6:7], v[22:23]
	s_nop 0
	v_pk_mul_f32 v[6:7], v[6:7], v[2:3]
	v_mul_f32_e32 v3, 0xbfb8aa3b, v8
	v_exp_f32_e32 v3, v3
	v_mul_f32_e32 v2, 0xbfb8aa3b, v16
	v_exp_f32_e32 v2, v2
	v_add_f32_e32 v3, 1.0, v3
	v_rcp_f32_e32 v14, v3
	v_mul_f32_e32 v3, 0xbfb8aa3b, v17
	v_exp_f32_e32 v3, v3
	v_add_f32_e32 v2, 1.0, v2
	v_rcp_f32_e32 v2, v2
	v_add_f32_e32 v3, 1.0, v3
	v_rcp_f32_e32 v3, v3
	s_nop 0
	v_pk_mul_f32 v[2:3], v[16:17], v[2:3]
	s_nop 0
	v_pk_mul_f32 v[12:13], v[2:3], v[12:13]
	v_mul_f32_e32 v2, 0xbfb8aa3b, v9
	v_exp_f32_e32 v2, v2
	s_nop 0
	v_add_f32_e32 v2, 1.0, v2
	v_rcp_f32_e32 v15, v2
	s_nop 0
	v_pk_mul_f32 v[2:3], v[8:9], v[14:15]
	s_nop 0
	v_pk_mul_f32 v[8:9], v[2:3], v[4:5]
	v_lshl_add_u64 v[14:15], v[18:19], 0, v[114:115]
	v_cvt_pk_bf16_f32 v2, v10, v11
	v_cvt_pk_bf16_f32 v3, v12, v13
	v_cvt_pk_bf16_f32 v4, v6, v7
	v_cvt_pk_bf16_f32 v5, v8, v9
	global_store_dwordx4 v[14:15], v[2:5], off
	s_andn2_b64 vcc, exec, s[0:1]
	s_mov_b64 s[0:1], -1
	s_cbranch_vccnz .LBB0_1260
	s_andn2_b64 vcc, exec, s[22:23]
	s_cbranch_vccnz .LBB0_1259
	s_barrier
	s_branch .LBB0_1259
.Lepi_last_12:
	v_mul_f32_e32 v147, 0xbfb8aa3b, v126
	v_exp_f32_e32 v147, v147
	v_lshl_or_b32 v148, s58, 7, v144
	v_lshl_add_u32 v146, s88, 8, v142
	v_ashrrev_i32_e32 v149, 31, v148
	v_add_f32_e32 v147, 1.0, v147
	v_rcp_f32_e32 v152, v147
	v_mul_f32_e32 v147, 0xbfb8aa3b, v118
	v_exp_f32_e32 v147, v147
	v_mov_b64_e32 v[140:141], s[24:25]
	v_mad_i64_i32 v[150:151], s[2:3], v146, s52, v[140:141]
	v_add_f32_e32 v147, 1.0, v147
	v_rcp_f32_e32 v154, v147
	v_mul_f32_e32 v147, 0xbfb8aa3b, v127
	v_exp_f32_e32 v147, v147
	s_nop 0
	v_add_f32_e32 v147, 1.0, v147
	v_rcp_f32_e32 v153, v147
	s_nop 0
	v_pk_mul_f32 v[126:127], v[126:127], v[152:153]
	s_nop 0
	v_pk_mul_f32 v[122:123], v[126:127], v[122:123]
	v_mul_f32_e32 v126, 0xbfb8aa3b, v119
	v_exp_f32_e32 v126, v126
	s_nop 0
	v_add_f32_e32 v126, 1.0, v126
	v_rcp_f32_e32 v155, v126
	s_nop 0
	v_pk_mul_f32 v[118:119], v[118:119], v[154:155]
	s_nop 0
	v_pk_mul_f32 v[118:119], v[118:119], v[114:115]
	v_mul_f32_e32 v115, 0xbfb8aa3b, v120
	v_exp_f32_e32 v115, v115
	v_mul_f32_e32 v114, 0xbfb8aa3b, v128
	v_exp_f32_e32 v114, v114
	v_cvt_pk_bf16_f32 v118, v118, v119
	v_add_f32_e32 v115, 1.0, v115
	v_rcp_f32_e32 v126, v115
	v_mul_f32_e32 v115, 0xbfb8aa3b, v129
	v_exp_f32_e32 v115, v115
	v_add_f32_e32 v114, 1.0, v114
	v_rcp_f32_e32 v114, v114
	v_add_f32_e32 v115, 1.0, v115
	v_rcp_f32_e32 v115, v115
	s_nop 0
	v_pk_mul_f32 v[114:115], v[128:129], v[114:115]
	s_nop 0
	v_pk_mul_f32 v[124:125], v[114:115], v[124:125]
	v_mul_f32_e32 v114, 0xbfb8aa3b, v121
	v_exp_f32_e32 v114, v114
	s_nop 0
	v_add_f32_e32 v114, 1.0, v114
	v_rcp_f32_e32 v127, v114
	s_nop 0
	v_pk_mul_f32 v[114:115], v[120:121], v[126:127]
	s_nop 0
	v_pk_mul_f32 v[120:121], v[114:115], v[116:117]
	v_lshlrev_b64 v[114:115], 1, v[148:149]
	v_lshl_add_u64 v[126:127], v[150:151], 0, v[114:115]
	v_cvt_pk_bf16_f32 v116, v122, v123
	v_cvt_pk_bf16_f32 v117, v124, v125
	v_cvt_pk_bf16_f32 v119, v120, v121
	global_store_dwordx4 v[126:127], v[116:119], off sc1
	s_nop 1
	v_mul_f32_e32 v119, 0xbfb8aa3b, v102
	v_exp_f32_e32 v119, v119
	v_mul_f32_e32 v118, 0xbfb8aa3b, v110
	v_exp_f32_e32 v118, v118
	v_or_b32_e32 v116, 16, v146
	v_add_f32_e32 v119, 1.0, v119
	v_rcp_f32_e32 v120, v119
	v_mul_f32_e32 v119, 0xbfb8aa3b, v111
	v_exp_f32_e32 v119, v119
	v_add_f32_e32 v118, 1.0, v118
	v_rcp_f32_e32 v118, v118
	v_mad_i64_i32 v[116:117], s[2:3], v116, s52, v[140:141]
	v_add_f32_e32 v119, 1.0, v119
	v_rcp_f32_e32 v119, v119
	s_nop 0
	v_pk_mul_f32 v[110:111], v[110:111], v[118:119]
	s_nop 0
	v_pk_mul_f32 v[106:107], v[110:111], v[106:107]
	v_mul_f32_e32 v110, 0xbfb8aa3b, v103
	v_exp_f32_e32 v110, v110
	s_nop 0
	v_add_f32_e32 v110, 1.0, v110
	v_rcp_f32_e32 v121, v110
	s_nop 0
	v_pk_mul_f32 v[102:103], v[102:103], v[120:121]
	s_nop 0
	v_pk_mul_f32 v[102:103], v[102:103], v[98:99]
	v_mul_f32_e32 v99, 0xbfb8aa3b, v104
	v_exp_f32_e32 v99, v99
	v_mul_f32_e32 v98, 0xbfb8aa3b, v112
	v_exp_f32_e32 v98, v98
	v_add_f32_e32 v99, 1.0, v99
	v_rcp_f32_e32 v110, v99
	v_mul_f32_e32 v99, 0xbfb8aa3b, v113
	v_exp_f32_e32 v99, v99
	v_add_f32_e32 v98, 1.0, v98
	v_rcp_f32_e32 v98, v98
; __device__ __forceinline__ float sigm(float x) { return rcpf_(1.f + ex2(-1.44269504f * x)); }
; __device__ __forceinline__ u32x4 pack8(f32x4 a, f32x4 b) { u32x4 w; w.x = cvt_pk_bf16(a[0], a[1]); w.y = cvt_pk_bf16(a[2], a[3]); w.z = cvt_pk_bf16(b[0], b[1]); w.w = cvt_pk_bf16(b[2], b[3]); return w; }
;     __device__ __forceinline__ void operator()(const f32x4 (&acc)[2][2][4][2], const Unit& u, int wr, int wc, int fr, int fq) const {
;     ...
;         if constexpr (MODE == 1) {
;             const int col0 = u.pn * 128 + wc * 32 + 8 * fq;
; #pragma unroll
;             for (int ai = 0; ai < 2; ++ai)
; #pragma unroll
;                 for (int m = 0; m < 4; ++m) {
;                     bf16_t* rowp = O + (size_t)(row0 + ai * HALF + m * 16) * ldc + col0;
;                     f32x4 v0, v1;
; #pragma unroll
;                     for (int e = 0; e < 4; ++e) { const float a0 = acc[ai][0][m][0][e], a1 = acc[ai][0][m][1][e]; v0[e] = a0 * sigm(a0) * acc[ai][1][m][0][e]; v1[e] = a1 * sigm(a1) * acc[ai][1][m][1][e]; }
;                     *(u32x4*)rowp = pack8(v0, v1);
;                     __builtin_amdgcn_sched_barrier(0);
;                 }
	v_add_f32_e32 v99, 1.0, v99
	v_rcp_f32_e32 v99, v99
	s_nop 0
	v_pk_mul_f32 v[98:99], v[112:113], v[98:99]
	s_nop 0
	v_pk_mul_f32 v[108:109], v[98:99], v[108:109]
	v_mul_f32_e32 v98, 0xbfb8aa3b, v105
	v_exp_f32_e32 v98, v98
	s_nop 0
	v_add_f32_e32 v98, 1.0, v98
	v_rcp_f32_e32 v111, v98
	s_nop 0
	v_pk_mul_f32 v[98:99], v[104:105], v[110:111]
	s_nop 0
	v_pk_mul_f32 v[104:105], v[98:99], v[100:101]
	v_lshl_add_u64 v[110:111], v[116:117], 0, v[114:115]
	v_cvt_pk_bf16_f32 v98, v106, v107
	v_cvt_pk_bf16_f32 v99, v108, v109
	v_cvt_pk_bf16_f32 v100, v102, v103
	v_cvt_pk_bf16_f32 v101, v104, v105
	global_store_dwordx4 v[110:111], v[98:101], off sc1
	s_nop 1
	v_mul_f32_e32 v101, 0xbfb8aa3b, v86
	v_exp_f32_e32 v101, v101
	v_mul_f32_e32 v100, 0xbfb8aa3b, v94
	v_exp_f32_e32 v100, v100
	v_or_b32_e32 v98, 32, v146
	v_add_f32_e32 v101, 1.0, v101
	v_rcp_f32_e32 v102, v101
	v_mul_f32_e32 v101, 0xbfb8aa3b, v95
	v_exp_f32_e32 v101, v101
	v_add_f32_e32 v100, 1.0, v100
	v_rcp_f32_e32 v100, v100
	v_mad_i64_i32 v[98:99], s[2:3], v98, s52, v[140:141]
	v_add_f32_e32 v101, 1.0, v101
	v_rcp_f32_e32 v101, v101
	s_nop 0
	v_pk_mul_f32 v[94:95], v[94:95], v[100:101]
	s_nop 0
	v_pk_mul_f32 v[90:91], v[94:95], v[90:91]
	v_mul_f32_e32 v94, 0xbfb8aa3b, v87
	v_exp_f32_e32 v94, v94
	s_nop 0
	v_add_f32_e32 v94, 1.0, v94
	v_rcp_f32_e32 v103, v94
	s_nop 0
	v_pk_mul_f32 v[86:87], v[86:87], v[102:103]
	s_nop 0
	v_pk_mul_f32 v[86:87], v[86:87], v[82:83]
	v_mul_f32_e32 v83, 0xbfb8aa3b, v88
	v_exp_f32_e32 v83, v83
	v_mul_f32_e32 v82, 0xbfb8aa3b, v96
	v_exp_f32_e32 v82, v82
	v_add_f32_e32 v83, 1.0, v83
	v_rcp_f32_e32 v94, v83
	v_mul_f32_e32 v83, 0xbfb8aa3b, v97
	v_exp_f32_e32 v83, v83
	v_add_f32_e32 v82, 1.0, v82
	v_rcp_f32_e32 v82, v82
	v_add_f32_e32 v83, 1.0, v83
	v_rcp_f32_e32 v83, v83
	s_nop 0
	v_pk_mul_f32 v[82:83], v[96:97], v[82:83]
	s_nop 0
	v_pk_mul_f32 v[92:93], v[82:83], v[92:93]
	v_mul_f32_e32 v82, 0xbfb8aa3b, v89
	v_exp_f32_e32 v82, v82
	s_nop 0
	v_add_f32_e32 v82, 1.0, v82
	v_rcp_f32_e32 v95, v82
	s_nop 0
	v_pk_mul_f32 v[82:83], v[88:89], v[94:95]
	s_nop 0
	v_pk_mul_f32 v[88:89], v[82:83], v[84:85]
	v_lshl_add_u64 v[94:95], v[98:99], 0, v[114:115]
	v_cvt_pk_bf16_f32 v82, v90, v91
	v_cvt_pk_bf16_f32 v83, v92, v93
	v_cvt_pk_bf16_f32 v84, v86, v87
	v_cvt_pk_bf16_f32 v85, v88, v89
	global_store_dwordx4 v[94:95], v[82:85], off sc1
	s_nop 1
	v_mul_f32_e32 v85, 0xbfb8aa3b, v70
	v_exp_f32_e32 v85, v85
	v_mul_f32_e32 v84, 0xbfb8aa3b, v78
	v_exp_f32_e32 v84, v84
	v_or_b32_e32 v82, 48, v146
	v_add_f32_e32 v85, 1.0, v85
	v_rcp_f32_e32 v86, v85
	v_mul_f32_e32 v85, 0xbfb8aa3b, v79
	v_exp_f32_e32 v85, v85
	v_add_f32_e32 v84, 1.0, v84
	v_rcp_f32_e32 v84, v84
	v_mad_i64_i32 v[82:83], s[2:3], v82, s52, v[140:141]
	v_add_f32_e32 v85, 1.0, v85
	v_rcp_f32_e32 v85, v85
	s_nop 0
	v_pk_mul_f32 v[78:79], v[78:79], v[84:85]
	s_nop 0
	v_pk_mul_f32 v[74:75], v[78:79], v[74:75]
	v_mul_f32_e32 v78, 0xbfb8aa3b, v71
	v_exp_f32_e32 v78, v78
	s_nop 0
	v_add_f32_e32 v78, 1.0, v78
	v_rcp_f32_e32 v87, v78
	s_nop 0
	v_pk_mul_f32 v[70:71], v[70:71], v[86:87]
	s_nop 0
	v_pk_mul_f32 v[70:71], v[70:71], v[66:67]
	v_mul_f32_e32 v67, 0xbfb8aa3b, v72
	v_exp_f32_e32 v67, v67
	v_mul_f32_e32 v66, 0xbfb8aa3b, v80
	v_exp_f32_e32 v66, v66
	v_add_f32_e32 v67, 1.0, v67
	v_rcp_f32_e32 v78, v67
	v_mul_f32_e32 v67, 0xbfb8aa3b, v81
	v_exp_f32_e32 v67, v67
	v_add_f32_e32 v66, 1.0, v66
	v_rcp_f32_e32 v66, v66
	v_add_f32_e32 v67, 1.0, v67
	v_rcp_f32_e32 v67, v67
	s_nop 0
	v_pk_mul_f32 v[66:67], v[80:81], v[66:67]
	s_nop 0
	v_pk_mul_f32 v[76:77], v[66:67], v[76:77]
	v_mul_f32_e32 v66, 0xbfb8aa3b, v73
	v_exp_f32_e32 v66, v66
	s_nop 0
	v_add_f32_e32 v66, 1.0, v66
	v_rcp_f32_e32 v79, v66
	s_nop 0
	v_pk_mul_f32 v[66:67], v[72:73], v[78:79]
	s_nop 0
	v_pk_mul_f32 v[72:73], v[66:67], v[68:69]
	v_lshl_add_u64 v[78:79], v[82:83], 0, v[114:115]
	v_cvt_pk_bf16_f32 v66, v74, v75
	v_cvt_pk_bf16_f32 v67, v76, v77
	v_cvt_pk_bf16_f32 v68, v70, v71
	v_cvt_pk_bf16_f32 v69, v72, v73
	global_store_dwordx4 v[78:79], v[66:69], off sc1
	s_nop 1
	v_mul_f32_e32 v69, 0xbfb8aa3b, v54
	v_exp_f32_e32 v69, v69
	v_mul_f32_e32 v68, 0xbfb8aa3b, v62
	v_exp_f32_e32 v68, v68
	v_add_u32_e32 v66, 0x80, v146
	v_add_f32_e32 v69, 1.0, v69
	v_rcp_f32_e32 v70, v69
	v_mul_f32_e32 v69, 0xbfb8aa3b, v63
	v_exp_f32_e32 v69, v69
	v_add_f32_e32 v68, 1.0, v68
	v_rcp_f32_e32 v68, v68
	v_mad_i64_i32 v[66:67], s[2:3], v66, s52, v[140:141]
	v_add_f32_e32 v69, 1.0, v69
	v_rcp_f32_e32 v69, v69
	s_nop 0
	v_pk_mul_f32 v[62:63], v[62:63], v[68:69]
	s_nop 0
	v_pk_mul_f32 v[58:59], v[62:63], v[58:59]
	v_mul_f32_e32 v62, 0xbfb8aa3b, v55
	v_exp_f32_e32 v62, v62
	s_nop 0
	v_add_f32_e32 v62, 1.0, v62
	v_rcp_f32_e32 v71, v62
	s_nop 0
	v_pk_mul_f32 v[54:55], v[54:55], v[70:71]
	s_nop 0
	v_pk_mul_f32 v[54:55], v[54:55], v[50:51]
	v_mul_f32_e32 v51, 0xbfb8aa3b, v56
	v_exp_f32_e32 v51, v51
	v_mul_f32_e32 v50, 0xbfb8aa3b, v64
	v_exp_f32_e32 v50, v50
	v_add_f32_e32 v51, 1.0, v51
	v_rcp_f32_e32 v62, v51
	v_mul_f32_e32 v51, 0xbfb8aa3b, v65
	v_exp_f32_e32 v51, v51
	v_add_f32_e32 v50, 1.0, v50
	v_rcp_f32_e32 v50, v50
	v_add_f32_e32 v51, 1.0, v51
	v_rcp_f32_e32 v51, v51
	s_nop 0
	v_pk_mul_f32 v[50:51], v[64:65], v[50:51]
	s_nop 0
	v_pk_mul_f32 v[60:61], v[50:51], v[60:61]
	v_mul_f32_e32 v50, 0xbfb8aa3b, v57
	v_exp_f32_e32 v50, v50
	s_nop 0
	v_add_f32_e32 v50, 1.0, v50
	v_rcp_f32_e32 v63, v50
	s_nop 0
; __device__ __forceinline__ float sigm(float x) { return rcpf_(1.f + ex2(-1.44269504f * x)); }
; __device__ __forceinline__ u32x4 pack8(f32x4 a, f32x4 b) { u32x4 w; w.x = cvt_pk_bf16(a[0], a[1]); w.y = cvt_pk_bf16(a[2], a[3]); w.z = cvt_pk_bf16(b[0], b[1]); w.w = cvt_pk_bf16(b[2], b[3]); return w; }
; #define PG8_BAR __builtin_amdgcn_s_barrier()
;     __device__ __forceinline__ void operator()(const f32x4 (&acc)[2][2][4][2], const Unit& u, int wr, int wc, int fr, int fq) const {
;     ...
;         if constexpr (MODE == 1) {
;             const int col0 = u.pn * 128 + wc * 32 + 8 * fq;
; #pragma unroll
;             for (int ai = 0; ai < 2; ++ai)
; #pragma unroll
;                 for (int m = 0; m < 4; ++m) {
;                     bf16_t* rowp = O + (size_t)(row0 + ai * HALF + m * 16) * ldc + col0;
;                     f32x4 v0, v1;
; #pragma unroll
;                     for (int e = 0; e < 4; ++e) { const float a0 = acc[ai][0][m][0][e], a1 = acc[ai][0][m][1][e]; v0[e] = a0 * sigm(a0) * acc[ai][1][m][0][e]; v1[e] = a1 * sigm(a1) * acc[ai][1][m][1][e]; }
;                     *(u32x4*)rowp = pack8(v0, v1);
;                     __builtin_amdgcn_sched_barrier(0);
;                 }
; template <class EpiT, class Sched>
; __device__ __forceinline__ void gemm_phase(LAS unsigned char* lds, int tid_in, const GemmDesc g, const Sched& S, const EpiT& E) {
;     ...
;         if (wr == 0) PG8_BAR;
;         E(acc, cur, wr, wc, fr, fq);
;         if (!has_next) break;
	v_pk_mul_f32 v[50:51], v[56:57], v[62:63]
	s_nop 0
	v_pk_mul_f32 v[56:57], v[50:51], v[52:53]
	v_lshl_add_u64 v[62:63], v[66:67], 0, v[114:115]
	v_cvt_pk_bf16_f32 v50, v58, v59
	v_cvt_pk_bf16_f32 v51, v60, v61
	v_cvt_pk_bf16_f32 v52, v54, v55
	v_cvt_pk_bf16_f32 v53, v56, v57
	global_store_dwordx4 v[62:63], v[50:53], off sc1
	s_nop 1
	v_mul_f32_e32 v53, 0xbfb8aa3b, v38
	v_exp_f32_e32 v53, v53
	v_mul_f32_e32 v52, 0xbfb8aa3b, v46
	v_exp_f32_e32 v52, v52
	v_add_u32_e32 v50, 0x90, v146
	v_add_f32_e32 v53, 1.0, v53
	v_rcp_f32_e32 v54, v53
	v_mul_f32_e32 v53, 0xbfb8aa3b, v47
	v_exp_f32_e32 v53, v53
	v_add_f32_e32 v52, 1.0, v52
	v_rcp_f32_e32 v52, v52
	v_mad_i64_i32 v[50:51], s[2:3], v50, s52, v[140:141]
	v_add_f32_e32 v53, 1.0, v53
	v_rcp_f32_e32 v53, v53
	s_nop 0
	v_pk_mul_f32 v[46:47], v[46:47], v[52:53]
	s_nop 0
	v_pk_mul_f32 v[42:43], v[46:47], v[42:43]
	v_mul_f32_e32 v46, 0xbfb8aa3b, v39
	v_exp_f32_e32 v46, v46
	s_nop 0
	v_add_f32_e32 v46, 1.0, v46
	v_rcp_f32_e32 v55, v46
	s_nop 0
	v_pk_mul_f32 v[38:39], v[38:39], v[54:55]
	s_nop 0
	v_pk_mul_f32 v[38:39], v[38:39], v[34:35]
	v_mul_f32_e32 v35, 0xbfb8aa3b, v40
	v_exp_f32_e32 v35, v35
	v_mul_f32_e32 v34, 0xbfb8aa3b, v48
	v_exp_f32_e32 v34, v34
	v_add_f32_e32 v35, 1.0, v35
	v_rcp_f32_e32 v46, v35
	v_mul_f32_e32 v35, 0xbfb8aa3b, v49
	v_exp_f32_e32 v35, v35
	v_add_f32_e32 v34, 1.0, v34
	v_rcp_f32_e32 v34, v34
	v_add_f32_e32 v35, 1.0, v35
	v_rcp_f32_e32 v35, v35
	s_nop 0
	v_pk_mul_f32 v[34:35], v[48:49], v[34:35]
	s_nop 0
	v_pk_mul_f32 v[44:45], v[34:35], v[44:45]
	v_mul_f32_e32 v34, 0xbfb8aa3b, v41
	v_exp_f32_e32 v34, v34
	s_nop 0
	v_add_f32_e32 v34, 1.0, v34
	v_rcp_f32_e32 v47, v34
	s_nop 0
	v_pk_mul_f32 v[34:35], v[40:41], v[46:47]
	s_nop 0
	v_pk_mul_f32 v[40:41], v[34:35], v[36:37]
	v_lshl_add_u64 v[46:47], v[50:51], 0, v[114:115]
	v_cvt_pk_bf16_f32 v34, v42, v43
	v_cvt_pk_bf16_f32 v35, v44, v45
	v_cvt_pk_bf16_f32 v36, v38, v39
	v_cvt_pk_bf16_f32 v37, v40, v41
	global_store_dwordx4 v[46:47], v[34:37], off sc1
	s_nop 1
	v_mul_f32_e32 v37, 0xbfb8aa3b, v22
	v_exp_f32_e32 v37, v37
	v_mul_f32_e32 v36, 0xbfb8aa3b, v30
	v_exp_f32_e32 v36, v36
	v_add_u32_e32 v34, 0xa0, v146
	v_add_f32_e32 v37, 1.0, v37
	v_rcp_f32_e32 v38, v37
	v_mul_f32_e32 v37, 0xbfb8aa3b, v31
	v_exp_f32_e32 v37, v37
	v_add_f32_e32 v36, 1.0, v36
	v_rcp_f32_e32 v36, v36
	v_mad_i64_i32 v[34:35], s[2:3], v34, s52, v[140:141]
	v_add_f32_e32 v37, 1.0, v37
	v_rcp_f32_e32 v37, v37
	s_nop 0
	v_pk_mul_f32 v[30:31], v[30:31], v[36:37]
	s_nop 0
	v_pk_mul_f32 v[26:27], v[30:31], v[26:27]
	v_mul_f32_e32 v30, 0xbfb8aa3b, v23
	v_exp_f32_e32 v30, v30
	s_nop 0
	v_add_f32_e32 v30, 1.0, v30
	v_rcp_f32_e32 v39, v30
	s_nop 0
	v_pk_mul_f32 v[22:23], v[22:23], v[38:39]
	s_nop 0
	v_pk_mul_f32 v[22:23], v[22:23], v[18:19]
	v_mul_f32_e32 v19, 0xbfb8aa3b, v24
	v_exp_f32_e32 v19, v19
	v_mul_f32_e32 v18, 0xbfb8aa3b, v32
	v_exp_f32_e32 v18, v18
	v_add_f32_e32 v19, 1.0, v19
	v_rcp_f32_e32 v30, v19
	v_mul_f32_e32 v19, 0xbfb8aa3b, v33
	v_exp_f32_e32 v19, v19
	v_add_f32_e32 v18, 1.0, v18
	v_rcp_f32_e32 v18, v18
	v_add_f32_e32 v19, 1.0, v19
	v_rcp_f32_e32 v19, v19
	s_nop 0
	v_pk_mul_f32 v[18:19], v[32:33], v[18:19]
	s_nop 0
	v_pk_mul_f32 v[28:29], v[18:19], v[28:29]
	v_mul_f32_e32 v18, 0xbfb8aa3b, v25
	v_exp_f32_e32 v18, v18
	s_nop 0
	v_add_f32_e32 v18, 1.0, v18
	v_rcp_f32_e32 v31, v18
	s_nop 0
	v_pk_mul_f32 v[18:19], v[24:25], v[30:31]
	s_nop 0
	v_pk_mul_f32 v[24:25], v[18:19], v[20:21]
	v_lshl_add_u64 v[30:31], v[34:35], 0, v[114:115]
	v_cvt_pk_bf16_f32 v18, v26, v27
	v_cvt_pk_bf16_f32 v19, v28, v29
	v_cvt_pk_bf16_f32 v20, v22, v23
	v_cvt_pk_bf16_f32 v21, v24, v25
	global_store_dwordx4 v[30:31], v[18:21], off sc1
	s_nop 1
	v_mul_f32_e32 v21, 0xbfb8aa3b, v6
	v_exp_f32_e32 v21, v21
	v_mul_f32_e32 v20, 0xbfb8aa3b, v14
	v_exp_f32_e32 v20, v20
	v_add_u32_e32 v18, 0xb0, v146
	v_add_f32_e32 v21, 1.0, v21
	v_rcp_f32_e32 v22, v21
	v_mul_f32_e32 v21, 0xbfb8aa3b, v15
	v_exp_f32_e32 v21, v21
	v_add_f32_e32 v20, 1.0, v20
	v_rcp_f32_e32 v20, v20
	v_mad_i64_i32 v[18:19], s[2:3], v18, s52, v[140:141]
	v_add_f32_e32 v21, 1.0, v21
	v_rcp_f32_e32 v21, v21
	s_nop 0
	v_pk_mul_f32 v[14:15], v[14:15], v[20:21]
	s_nop 0
	v_pk_mul_f32 v[10:11], v[14:15], v[10:11]
	v_mul_f32_e32 v14, 0xbfb8aa3b, v7
	v_exp_f32_e32 v14, v14
	s_nop 0
	v_add_f32_e32 v14, 1.0, v14
	v_rcp_f32_e32 v23, v14
	s_nop 0
	v_pk_mul_f32 v[6:7], v[6:7], v[22:23]
	s_nop 0
	v_pk_mul_f32 v[6:7], v[6:7], v[2:3]
	v_mul_f32_e32 v3, 0xbfb8aa3b, v8
	v_exp_f32_e32 v3, v3
	v_mul_f32_e32 v2, 0xbfb8aa3b, v16
	v_exp_f32_e32 v2, v2
	v_add_f32_e32 v3, 1.0, v3
	v_rcp_f32_e32 v14, v3
	v_mul_f32_e32 v3, 0xbfb8aa3b, v17
	v_exp_f32_e32 v3, v3
	v_add_f32_e32 v2, 1.0, v2
	v_rcp_f32_e32 v2, v2
	v_add_f32_e32 v3, 1.0, v3
	v_rcp_f32_e32 v3, v3
	s_nop 0
	v_pk_mul_f32 v[2:3], v[16:17], v[2:3]
	s_nop 0
	v_pk_mul_f32 v[12:13], v[2:3], v[12:13]
	v_mul_f32_e32 v2, 0xbfb8aa3b, v9
	v_exp_f32_e32 v2, v2
	s_nop 0
	v_add_f32_e32 v2, 1.0, v2
	v_rcp_f32_e32 v15, v2
	s_nop 0
	v_pk_mul_f32 v[2:3], v[8:9], v[14:15]
	s_nop 0
	v_pk_mul_f32 v[8:9], v[2:3], v[4:5]
	v_lshl_add_u64 v[14:15], v[18:19], 0, v[114:115]
	v_cvt_pk_bf16_f32 v2, v10, v11
	v_cvt_pk_bf16_f32 v3, v12, v13
	v_cvt_pk_bf16_f32 v4, v6, v7
	v_cvt_pk_bf16_f32 v5, v8, v9
	global_store_dwordx4 v[14:15], v[2:5], off sc1
	s_andn2_b64 vcc, exec, s[0:1]
	s_mov_b64 s[0:1], -1
	s_branch .LBB0_1260

;     __device__ __forceinline__ void operator()(const f32x4 (&acc)[2][2][4][2], const Unit& u, int wr, int wc, int fr, int fq) const {
;     ...
;         } else {
;             const int col0 = u.pn * BM + wc * 32 + 8 * fq;
; #pragma unroll
;             for (int ai = 0; ai < 2; ++ai)
; #pragma unroll
;                 for (int m = 0; m < 4; ++m) {
;                     const size_t row = (size_t)(row0 + ai * HALF + m * 16);
; #pragma unroll
;                     for (int bj = 0; bj < 2; ++bj) {
;                         const int col = col0 + bj * HALF;
;                         f32x4 v0 = acc[ai][bj][m][0], v1 = acc[ai][bj][m][1];
;                         bf16_t* dst = O + row * ldc + col;
;                         if constexpr (MODE == 2) {
; #pragma unroll
;                             for (int e = 0; e < 4; ++e) { v0[e] = sigm(v0[e]); v1[e] = sigm(v1[e]); }
;                         }
;                         if constexpr (MODE == 4) {
;                             const f32x4 b0 = *(const f32x4*)(bias + u.tag * 256 + col), b1 = *(const f32x4*)(bias + u.tag * 256 + col + 4);
; #pragma unroll
;                             for (int e = 0; e < 4; ++e) { v0[e] = gelu_tanh(v0[e] + b0[e]); v1[e] = gelu_tanh(v1[e] + b1[e]); }
;                         }
;                         if constexpr (MODE == 3) {
;                             const u32x4 gv = *(const u32x4*)(G + row * GP + u.tag * 1024 + col);
;                             v0[0] *= bf_lo(gv.x); v0[1] *= bf_hi(gv.x); v0[2] *= bf_lo(gv.y); v0[3] *= bf_hi(gv.y);
;                             v1[0] *= bf_lo(gv.z); v1[1] *= bf_hi(gv.z); v1[2] *= bf_lo(gv.w); v1[3] *= bf_hi(gv.w);
;                             if (u.tag > 0) {
;                                 const u32x4 ov = *(const u32x4*)dst;
;                                 v0[0] += bf_lo(ov.x); v0[1] += bf_hi(ov.x); v0[2] += bf_lo(ov.y); v0[3] += bf_hi(ov.y);
;                                 v1[0] += bf_lo(ov.z); v1[1] += bf_hi(ov.z); v1[2] += bf_lo(ov.w); v1[3] += bf_hi(ov.w);
;                             }
;                         }
;                         *(u32x4*)dst = pack8(v0, v1);
;                     }
; template <class EpiT, class Sched>
; __device__ __forceinline__ void gemm_phase(LAS unsigned char* lds, int tid_in, const GemmDesc g, const Sched& S, const EpiT& E) {
;     ...
;         if (wr == 0) PG8_BAR;
;         E(acc, cur, wr, wc, fr, fq);
.LBB0_1343:
	s_andn2_b64 vcc, exec, s[0:1]
	s_cbranch_vccnz .Lepi_last_13
	v_lshl_add_u32 v144, s81, 8, v140
	v_lshl_or_b32 v146, s93, 8, v142
	v_ashrrev_i32_e32 v145, 31, v144
	v_lshlrev_b64 v[148:149], 11, v[144:145]
	v_ashrrev_i32_e32 v147, 31, v146
	v_lshl_add_u64 v[148:149], s[18:19], 0, v[148:149]
	v_lshlrev_b64 v[146:147], 1, v[146:147]
	v_lshl_add_u64 v[148:149], v[148:149], 0, v[146:147]
	s_mov_b64 s[2:3], 0x40000
	v_cvt_pk_bf16_f32 v70, v70, v71
	v_cvt_pk_bf16_f32 v71, v72, v73
	v_cvt_pk_bf16_f32 v72, v66, v67
	v_lshl_add_u64 v[66:67], v[148:149], 0, s[2:3]
	v_cvt_pk_bf16_f32 v62, v62, v63
	v_cvt_pk_bf16_f32 v63, v64, v65
	v_cvt_pk_bf16_f32 v64, v58, v59
	v_add_co_u32_e32 v58, vcc, s97, v148
	v_cvt_pk_bf16_f32 v46, v46, v47
	v_cvt_pk_bf16_f32 v47, v48, v49
	v_cvt_pk_bf16_f32 v48, v42, v43
	v_cvt_pk_bf16_f32 v49, v44, v45
	s_mov_b64 s[2:3], 0x48000
	v_addc_co_u32_e32 v59, vcc, 0, v149, vcc
	global_store_dwordx4 v[66:67], v[46:49], off offset:256
	v_cvt_pk_bf16_f32 v110, v110, v111
	v_cvt_pk_bf16_f32 v111, v112, v113
	v_lshl_add_u64 v[46:47], v[148:149], 0, s[2:3]
	s_mov_b32 s2, 0x48000
	v_cvt_pk_bf16_f32 v112, v106, v107
	v_or_b32_e32 v106, 16, v144
	v_add_co_u32_e32 v48, vcc, s2, v148
	v_cvt_pk_bf16_f32 v30, v30, v31
	v_cvt_pk_bf16_f32 v31, v32, v33
	v_cvt_pk_bf16_f32 v32, v26, v27
	v_cvt_pk_bf16_f32 v33, v28, v29
	s_mov_b64 s[2:3], 0x50000
	v_ashrrev_i32_e32 v107, 31, v106
	v_cvt_pk_bf16_f32 v94, v94, v95
	v_cvt_pk_bf16_f32 v95, v96, v97
	v_cvt_pk_bf16_f32 v96, v90, v91
	v_or_b32_e32 v90, 32, v144
	v_addc_co_u32_e32 v49, vcc, 0, v149, vcc
	global_store_dwordx4 v[46:47], v[30:33], off offset:256
	v_lshlrev_b64 v[106:107], 11, v[106:107]
	v_ashrrev_i32_e32 v91, 31, v90
	v_lshl_add_u64 v[30:31], v[148:149], 0, s[2:3]
	s_mov_b32 s2, 0x50000
	v_cvt_pk_bf16_f32 v78, v78, v79
	v_cvt_pk_bf16_f32 v79, v80, v81
	v_cvt_pk_bf16_f32 v80, v74, v75
	v_or_b32_e32 v74, 48, v144
	v_add_co_u32_e32 v32, vcc, s2, v148
	v_cvt_pk_bf16_f32 v14, v14, v15
	v_cvt_pk_bf16_f32 v15, v16, v17
	v_cvt_pk_bf16_f32 v16, v10, v11
	v_cvt_pk_bf16_f32 v17, v12, v13
	s_mov_b64 s[2:3], 0x58000
	v_cvt_pk_bf16_f32 v113, v108, v109
	v_lshl_add_u64 v[106:107], s[18:19], 0, v[106:107]
	v_lshlrev_b64 v[90:91], 11, v[90:91]
	v_ashrrev_i32_e32 v75, 31, v74
	v_addc_co_u32_e32 v33, vcc, 0, v149, vcc
	global_store_dwordx4 v[30:31], v[14:17], off offset:256
	global_store_dwordx4 v[148:149], v[110:113], off offset:256
	v_cvt_pk_bf16_f32 v97, v92, v93
	v_lshl_add_u64 v[14:15], v[148:149], 0, s[2:3]
	s_mov_b32 s2, 0x58000
	v_lshl_add_u64 v[110:111], v[106:107], 0, v[146:147]
	v_lshl_add_u64 v[90:91], s[18:19], 0, v[90:91]
	v_lshlrev_b64 v[74:75], 11, v[74:75]
	v_add_co_u32_e32 v16, vcc, s2, v148
	global_store_dwordx4 v[110:111], v[94:97], off offset:256
	v_cvt_pk_bf16_f32 v81, v76, v77
	v_lshl_add_u64 v[74:75], s[18:19], 0, v[74:75]
	v_lshl_add_u64 v[94:95], v[90:91], 0, v[146:147]
	v_addc_co_u32_e32 v17, vcc, 0, v149, vcc
	v_cvt_pk_bf16_f32 v126, v126, v127
	v_cvt_pk_bf16_f32 v127, v128, v129
	v_cvt_pk_bf16_f32 v128, v122, v123
	v_cvt_pk_bf16_f32 v129, v124, v125
	v_cvt_pk_bf16_f32 v106, v118, v119
	v_cvt_pk_bf16_f32 v107, v120, v121
	v_cvt_pk_bf16_f32 v108, v114, v115
	v_cvt_pk_bf16_f32 v109, v116, v117
	v_cvt_pk_bf16_f32 v90, v102, v103
	v_cvt_pk_bf16_f32 v91, v104, v105
	v_cvt_pk_bf16_f32 v92, v98, v99
	v_cvt_pk_bf16_f32 v93, v100, v101
	global_store_dwordx4 v[94:95], v[78:81], off offset:256
	v_cvt_pk_bf16_f32 v76, v82, v83
	v_cvt_pk_bf16_f32 v77, v84, v85
	v_lshl_add_u64 v[78:79], v[74:75], 0, v[146:147]
	v_cvt_pk_bf16_f32 v74, v86, v87
	v_cvt_pk_bf16_f32 v75, v88, v89
	v_cvt_pk_bf16_f32 v73, v68, v69
	v_cvt_pk_bf16_f32 v65, v60, v61
	v_cvt_pk_bf16_f32 v42, v54, v55
	v_cvt_pk_bf16_f32 v43, v56, v57
	v_cvt_pk_bf16_f32 v44, v50, v51
	v_cvt_pk_bf16_f32 v45, v52, v53
	v_cvt_pk_bf16_f32 v26, v38, v39
	v_cvt_pk_bf16_f32 v27, v40, v41
	v_cvt_pk_bf16_f32 v28, v34, v35
	v_cvt_pk_bf16_f32 v29, v36, v37
	v_cvt_pk_bf16_f32 v10, v22, v23
	v_cvt_pk_bf16_f32 v11, v24, v25
	v_cvt_pk_bf16_f32 v12, v18, v19
	v_cvt_pk_bf16_f32 v13, v20, v21
	v_cvt_pk_bf16_f32 v6, v6, v7
	v_cvt_pk_bf16_f32 v7, v8, v9
	v_cvt_pk_bf16_f32 v8, v2, v3
	v_cvt_pk_bf16_f32 v9, v4, v5
	s_andn2_b64 vcc, exec, s[0:1]
	s_mov_b64 s[0:1], -1
	global_store_dwordx4 v[148:149], v[126:129], off
	global_store_dwordx4 v[110:111], v[106:109], off
	global_store_dwordx4 v[94:95], v[90:93], off
	global_store_dwordx4 v[78:79], v[74:77], off
	global_store_dwordx4 v[78:79], v[70:73], off offset:256
	global_store_dwordx4 v[58:59], v[62:65], off
	global_store_dwordx4 v[48:49], v[42:45], off
	global_store_dwordx4 v[32:33], v[26:29], off
	global_store_dwordx4 v[16:17], v[10:13], off
	global_store_dwordx4 v[14:15], v[6:9], off offset:256
	s_cbranch_vccnz .LBB0_1332
	s_andn2_b64 vcc, exec, s[12:13]
	s_cbranch_vccnz .LBB0_1331
	s_barrier
	s_branch .LBB0_1331
;     __device__ __forceinline__ void operator()(const f32x4 (&acc)[2][2][4][2], const Unit& u, int wr, int wc, int fr, int fq) const {
;     ...
;         } else {
;             const int col0 = u.pn * BM + wc * 32 + 8 * fq;
; #pragma unroll
;             for (int ai = 0; ai < 2; ++ai)
; #pragma unroll
;                 for (int m = 0; m < 4; ++m) {
;                     const size_t row = (size_t)(row0 + ai * HALF + m * 16);
; #pragma unroll
;                     for (int bj = 0; bj < 2; ++bj) {
;                         const int col = col0 + bj * HALF;
;                         f32x4 v0 = acc[ai][bj][m][0], v1 = acc[ai][bj][m][1];
;                         bf16_t* dst = O + row * ldc + col;
;                         if constexpr (MODE == 2) {
; #pragma unroll
;                             for (int e = 0; e < 4; ++e) { v0[e] = sigm(v0[e]); v1[e] = sigm(v1[e]); }
;                         }
;                         if constexpr (MODE == 4) {
;                             const f32x4 b0 = *(const f32x4*)(bias + u.tag * 256 + col), b1 = *(const f32x4*)(bias + u.tag * 256 + col + 4);
; #pragma unroll
;                             for (int e = 0; e < 4; ++e) { v0[e] = gelu_tanh(v0[e] + b0[e]); v1[e] = gelu_tanh(v1[e] + b1[e]); }
;                         }
;                         if constexpr (MODE == 3) {
;                             const u32x4 gv = *(const u32x4*)(G + row * GP + u.tag * 1024 + col);
;                             v0[0] *= bf_lo(gv.x); v0[1] *= bf_hi(gv.x); v0[2] *= bf_lo(gv.y); v0[3] *= bf_hi(gv.y);
;                             v1[0] *= bf_lo(gv.z); v1[1] *= bf_hi(gv.z); v1[2] *= bf_lo(gv.w); v1[3] *= bf_hi(gv.w);
;                             if (u.tag > 0) {
;                                 const u32x4 ov = *(const u32x4*)dst;
;                                 v0[0] += bf_lo(ov.x); v0[1] += bf_hi(ov.x); v0[2] += bf_lo(ov.y); v0[3] += bf_hi(ov.y);
;                                 v1[0] += bf_lo(ov.z); v1[1] += bf_hi(ov.z); v1[2] += bf_lo(ov.w); v1[3] += bf_hi(ov.w);
;                             }
;                         }
;                         *(u32x4*)dst = pack8(v0, v1);
;                     }
; template <class EpiT, class Sched>
; __device__ __forceinline__ void gemm_phase(LAS unsigned char* lds, int tid_in, const GemmDesc g, const Sched& S, const EpiT& E) {
;     ...
;         if (wr == 0) PG8_BAR;
;         E(acc, cur, wr, wc, fr, fq);
.Lepi_last_13:
	v_lshl_add_u32 v144, s81, 8, v140
	v_lshl_or_b32 v146, s93, 8, v142
	v_ashrrev_i32_e32 v145, 31, v144
	v_lshlrev_b64 v[148:149], 11, v[144:145]
	v_ashrrev_i32_e32 v147, 31, v146
	v_lshl_add_u64 v[148:149], s[18:19], 0, v[148:149]
	v_lshlrev_b64 v[146:147], 1, v[146:147]
	v_lshl_add_u64 v[148:149], v[148:149], 0, v[146:147]
	s_mov_b64 s[2:3], 0x40000
	v_cvt_pk_bf16_f32 v70, v70, v71
	v_cvt_pk_bf16_f32 v71, v72, v73
	v_cvt_pk_bf16_f32 v72, v66, v67
	v_lshl_add_u64 v[66:67], v[148:149], 0, s[2:3]
	v_cvt_pk_bf16_f32 v62, v62, v63
	v_cvt_pk_bf16_f32 v63, v64, v65
	v_cvt_pk_bf16_f32 v64, v58, v59
	v_add_co_u32_e32 v58, vcc, s97, v148
	v_cvt_pk_bf16_f32 v46, v46, v47
	v_cvt_pk_bf16_f32 v47, v48, v49
	v_cvt_pk_bf16_f32 v48, v42, v43
	v_cvt_pk_bf16_f32 v49, v44, v45
	s_mov_b64 s[2:3], 0x48000
	v_addc_co_u32_e32 v59, vcc, 0, v149, vcc
	global_store_dwordx4 v[66:67], v[46:49], off offset:256 sc1
	v_cvt_pk_bf16_f32 v110, v110, v111
	v_cvt_pk_bf16_f32 v111, v112, v113
	v_lshl_add_u64 v[46:47], v[148:149], 0, s[2:3]
	s_mov_b32 s2, 0x48000
	v_cvt_pk_bf16_f32 v112, v106, v107
	v_or_b32_e32 v106, 16, v144
	v_add_co_u32_e32 v48, vcc, s2, v148
	v_cvt_pk_bf16_f32 v30, v30, v31
	v_cvt_pk_bf16_f32 v31, v32, v33
	v_cvt_pk_bf16_f32 v32, v26, v27
	v_cvt_pk_bf16_f32 v33, v28, v29
	s_mov_b64 s[2:3], 0x50000
	v_ashrrev_i32_e32 v107, 31, v106
	v_cvt_pk_bf16_f32 v94, v94, v95
	v_cvt_pk_bf16_f32 v95, v96, v97
	v_cvt_pk_bf16_f32 v96, v90, v91
	v_or_b32_e32 v90, 32, v144
	v_addc_co_u32_e32 v49, vcc, 0, v149, vcc
	global_store_dwordx4 v[46:47], v[30:33], off offset:256 sc1
	v_lshlrev_b64 v[106:107], 11, v[106:107]
	v_ashrrev_i32_e32 v91, 31, v90
	v_lshl_add_u64 v[30:31], v[148:149], 0, s[2:3]
	s_mov_b32 s2, 0x50000
	v_cvt_pk_bf16_f32 v78, v78, v79
	v_cvt_pk_bf16_f32 v79, v80, v81
	v_cvt_pk_bf16_f32 v80, v74, v75
	v_or_b32_e32 v74, 48, v144
	v_add_co_u32_e32 v32, vcc, s2, v148
	v_cvt_pk_bf16_f32 v14, v14, v15
	v_cvt_pk_bf16_f32 v15, v16, v17
	v_cvt_pk_bf16_f32 v16, v10, v11
	v_cvt_pk_bf16_f32 v17, v12, v13
	s_mov_b64 s[2:3], 0x58000
	v_cvt_pk_bf16_f32 v113, v108, v109
	v_lshl_add_u64 v[106:107], s[18:19], 0, v[106:107]
	v_lshlrev_b64 v[90:91], 11, v[90:91]
	v_ashrrev_i32_e32 v75, 31, v74
	v_addc_co_u32_e32 v33, vcc, 0, v149, vcc
	global_store_dwordx4 v[30:31], v[14:17], off offset:256 sc1
	global_store_dwordx4 v[148:149], v[110:113], off offset:256 sc1
	v_cvt_pk_bf16_f32 v97, v92, v93
	v_lshl_add_u64 v[14:15], v[148:149], 0, s[2:3]
	s_mov_b32 s2, 0x58000
	v_lshl_add_u64 v[110:111], v[106:107], 0, v[146:147]
	v_lshl_add_u64 v[90:91], s[18:19], 0, v[90:91]
	v_lshlrev_b64 v[74:75], 11, v[74:75]
	v_add_co_u32_e32 v16, vcc, s2, v148
	global_store_dwordx4 v[110:111], v[94:97], off offset:256 sc1
	v_cvt_pk_bf16_f32 v81, v76, v77
	v_lshl_add_u64 v[74:75], s[18:19], 0, v[74:75]
	v_lshl_add_u64 v[94:95], v[90:91], 0, v[146:147]
	v_addc_co_u32_e32 v17, vcc, 0, v149, vcc
	v_cvt_pk_bf16_f32 v126, v126, v127
	v_cvt_pk_bf16_f32 v127, v128, v129
	v_cvt_pk_bf16_f32 v128, v122, v123
	v_cvt_pk_bf16_f32 v129, v124, v125
	v_cvt_pk_bf16_f32 v106, v118, v119
	v_cvt_pk_bf16_f32 v107, v120, v121
	v_cvt_pk_bf16_f32 v108, v114, v115
	v_cvt_pk_bf16_f32 v109, v116, v117
	v_cvt_pk_bf16_f32 v90, v102, v103
	v_cvt_pk_bf16_f32 v91, v104, v105
	v_cvt_pk_bf16_f32 v92, v98, v99
	v_cvt_pk_bf16_f32 v93, v100, v101
	global_store_dwordx4 v[94:95], v[78:81], off offset:256 sc1
	v_cvt_pk_bf16_f32 v76, v82, v83
	v_cvt_pk_bf16_f32 v77, v84, v85
	v_lshl_add_u64 v[78:79], v[74:75], 0, v[146:147]
	v_cvt_pk_bf16_f32 v74, v86, v87
	v_cvt_pk_bf16_f32 v75, v88, v89
	v_cvt_pk_bf16_f32 v73, v68, v69
	v_cvt_pk_bf16_f32 v65, v60, v61
	v_cvt_pk_bf16_f32 v42, v54, v55
	v_cvt_pk_bf16_f32 v43, v56, v57
	v_cvt_pk_bf16_f32 v44, v50, v51
	v_cvt_pk_bf16_f32 v45, v52, v53
	v_cvt_pk_bf16_f32 v26, v38, v39
	v_cvt_pk_bf16_f32 v27, v40, v41
	v_cvt_pk_bf16_f32 v28, v34, v35
	v_cvt_pk_bf16_f32 v29, v36, v37
	v_cvt_pk_bf16_f32 v10, v22, v23
	v_cvt_pk_bf16_f32 v11, v24, v25
	v_cvt_pk_bf16_f32 v12, v18, v19
	v_cvt_pk_bf16_f32 v13, v20, v21
	v_cvt_pk_bf16_f32 v6, v6, v7
	v_cvt_pk_bf16_f32 v7, v8, v9
	v_cvt_pk_bf16_f32 v8, v2, v3
	v_cvt_pk_bf16_f32 v9, v4, v5
	s_andn2_b64 vcc, exec, s[0:1]
	s_mov_b64 s[0:1], -1
	global_store_dwordx4 v[148:149], v[126:129], off sc1
	global_store_dwordx4 v[110:111], v[106:109], off sc1
	global_store_dwordx4 v[94:95], v[90:93], off sc1
	global_store_dwordx4 v[78:79], v[74:77], off sc1
	global_store_dwordx4 v[78:79], v[70:73], off offset:256 sc1
	global_store_dwordx4 v[58:59], v[62:65], off sc1
	global_store_dwordx4 v[48:49], v[42:45], off sc1
	global_store_dwordx4 v[32:33], v[26:29], off sc1
	global_store_dwordx4 v[16:17], v[10:13], off sc1
	global_store_dwordx4 v[14:15], v[6:9], off offset:256 sc1
	s_branch .LBB0_1332
